# VM2 NOMAX attention main loops: all 4 Q fragments held in otherwise-unused VGPRs (v218-233) across the loop, no Q LDS reads or lgkmcnt(0) drains in QK phase; counted lgkmcnt for V fragments
# speedup vs baseline: 1.0125x; 1.0016x over previous
; #define WAIT_BAR(N) asm volatile("s_waitcnt vmcnt(" #N ") lgkmcnt(0)\n\ts_barrier":::"memory")
;   #define DMA_K(t,slot) glds16(ksrc+(long)(t)*KVBLK*KVP,(unsigned)__builtin_amdgcn_readfirstlane(kdst+(slot)))
;   #define DMA_V(t,slot) do{ glds16(vsrc+(long)(t)*KVBLK*KVP,(unsigned)__builtin_amdgcn_readfirstlane(vdst+VM*(slot))); if constexpr(VM==2) glds16(vsrc+64+(long)(t)*KVBLK*KVP,(unsigned)__builtin_amdgcn_readfirstlane(vdst+VM*(slot)+8192)); }while(0)
; template<int THRL,int VM,bool NOMAX> __device__ __forceinline__ void attn_unit(const bf16*Qb,const bf16*__restrict__ Kh,const bf16*__restrict__ Vh,bf16*Ob,const int NT,const int sp,float*wscr,char*shm){
;     ...
;   const bf16*ksrc=Kh+(long)lane*KVP+wid*8;
;   const bf16*vsrc=Vh+(long)(16*(wid&3)+(lane>>2))*KVP+(wid>>2)*32+(lane&3)*8;
;   const unsigned kdst=lds0+LDS_K+wid*1024, vdst=lds0+LDS_V+wid*1024;
;     ...
;   const int vb0=(int)(lds0+LDS_V)+((lane>>4)&1)*32+(lane&3)*8+(4*hi+((lane&15)>>2))*64;
;   const char*Kbase=shm+LDS_K; bf16x8 kf[8];
;   const lds_cptr shm3=(lds_cptr)shm; const lds_cptr kp0=shm3+LDS_K+hi*1024+r32*16; const lds_cptr vp0=shm3+LDS_V+((lane>>4)&1)*32+(lane&3)*8+(4*hi+((lane&15)>>2))*64;
;   if(wid>=4)__builtin_amdgcn_s_setprio(1);
;   DMA_K(0,0);DMA_V(0,0);DMA_K(1,SLOTB);
;   bf16x8 qr[4];
;   #pragma unroll
;   for(int d0=0;d0<4;++d0)qr[d0]=*reinterpret_cast<const bf16x8*>(&Qw[(long)r32*QOP+d0*16+hi*8]);
;   const lds_cptr qpk=shm3+LDS_OST_+wid*4096+lane*16;
;   if constexpr(VM==2){
;     #pragma unroll
;     for(int d0=0;d0<4;++d0)*(__attribute__((address_space(3))) bf16x8*)(const_cast<__attribute__((address_space(3))) char*>(qpk)+d0*1024)=qr[d0]; }
;   float mhat=0.f,l_reg=0.f;f32x16 o[2*VM];
;   #pragma unroll
;   for(int d_=0;d_<2*VM;++d_)o[d_]=f32x16{};
;  f32x16 negm=f32x16{}; if constexpr(VM==1){asm volatile("":"+v"(negm));}
;   bool resc=false;
;     ...
;   f32x16 pA0,pA1,pB0,pB1;
;   int sl_prev=0,sl_cur=0,sl_next=SLOTB;
;     ...
;   DMA_K(2,2*SLOTB);
;   WAIT_BAR(3);
;   qkt(pA0,pA1,Kbase,qr,negm,r32,hi);asm volatile("s_nop 15\n\ts_nop 7":"+v"(pA0),"+v"(pA1));
.LBB0_862:
	s_xor_b64 s[6:7], s[16:17], -1
	s_lshl_b32 s16, s8, 7
	s_add_u32 s35, s83, s16
	s_addc_u32 s88, s84, 0
	s_add_u32 s16, s0, s16
	s_addc_u32 s17, s1, 0
	s_lshl_b32 s86, s85, 5
	v_and_b32_e32 v187, 63, v32
	s_ashr_i32 s87, s86, 31
	s_lshl_b64 s[86:87], s[86:87], 11
	v_mul_u32_u24_e32 v0, 0x500, v187
	s_add_u32 s86, s35, s86
	v_lshlrev_b32_e32 v168, 1, v0
	s_addc_u32 s87, s88, s87
	v_lshl_add_u64 v[0:1], s[16:17], 0, v[168:169]
	s_lshl_b32 s16, s85, 3
	s_ashr_i32 s17, s16, 31
	v_lshl_add_u64 v[54:55], s[16:17], 1, v[0:1]
	s_mov_b64 s[16:17], 0x200
	v_lshl_add_u64 v[174:175], v[54:55], 0, s[16:17]
	s_lshl_b32 s16, s85, 4
	v_bfe_u32 v0, v32, 2, 4
	v_and_or_b32 v0, s16, 48, v0
	v_mul_u32_u24_e32 v0, 0x500, v0
	s_ashr_i32 s16, s34, 3
	v_lshlrev_b32_e32 v168, 1, v0
	s_andn2_b32 s16, s16, 31
	v_lshlrev_b32_e32 v2, 3, v32
	v_lshl_add_u64 v[0:1], s[0:1], 0, v[168:169]
	s_ashr_i32 s17, s16, 31
	v_and_b32_e32 v190, 24, v2
	v_lshl_add_u64 v[0:1], s[16:17], 1, v[0:1]
	v_lshlrev_b32_e32 v168, 1, v190
	v_lshl_add_u64 v[56:57], v[0:1], 0, v[168:169]
	s_mov_b64 s[16:17], 0x600
	v_lshl_add_u64 v[170:171], v[56:57], 0, s[16:17]
	s_lshl_b32 s17, s85, 10
	s_cmp_lg_u32 0, -1
	s_cselect_b32 s16, 0, 0
	s_add_i32 s35, s17, s16
	s_mov_b32 s88, m0
	s_mov_b32 m0, s35
	s_nop 0
	global_load_lds_dwordx4 v[174:175], off
	s_mov_b32 m0, s88
	s_add_i32 s16, s35, 0x6000
	s_mov_b32 s88, m0
	s_mov_b32 m0, s16
	s_nop 0
	global_load_lds_dwordx4 v[170:171], off
	s_mov_b32 m0, s88
	v_and_b32_e32 v186, 31, v32
	v_lshl_add_u64 v[172:173], v[56:57], 0, s[12:13]
	s_add_i32 s88, s35, 0x8000
	s_mov_b32 s89, m0
	s_mov_b32 m0, s88
	s_nop 0
	global_load_lds_dwordx4 v[172:173], off
	s_mov_b32 m0, s89
	v_lshl_add_u64 v[0:1], v[54:55], 0, s[14:15]
	v_bfe_u32 v185, v32, 5, 1
	s_add_i32 s88, s35, 0x2000
	s_mov_b32 s89, m0
	s_mov_b32 m0, s88
	s_nop 0
	global_load_lds_dwordx4 v[0:1], off
	s_mov_b32 m0, s89
	v_lshlrev_b32_e32 v0, 11, v186
	v_lshl_or_b32 v4, v185, 4, v0
	global_load_dwordx4 v[0:3], v4, s[86:87] offset:1024
	global_load_dwordx4 v[34:37], v4, s[86:87] offset:1056
	global_load_dwordx4 v[38:41], v4, s[86:87] offset:1088
	global_load_dwordx4 v[42:45], v4, s[86:87] offset:1120
	s_lshl_b32 s85, s85, 12
	s_add_i32 s85, s85, 0
	v_lshlrev_b32_e32 v6, 4, v187
	s_add_i32 s85, s85, 0x12800
	v_add_u32_e32 v188, s85, v6
	v_lshlrev_b32_e32 v4, 10, v185
	v_lshlrev_b32_e32 v5, 4, v186
	v_add3_u32 v189, 0, v4, v5
	v_lshl_add_u64 v[4:5], v[54:55], 0, s[36:37]
	s_add_i32 s86, s35, 0x4000
	v_lshlrev_b32_e32 v33, 1, v32
	v_lshlrev_b32_e32 v32, 4, v32
	v_and_b32_e32 v191, 32, v33
	v_and_b32_e32 v32, 0xc0, v32
	v_lshl_or_b32 v192, v185, 8, v32
	v_add_u32_e32 v32, 0, v191
	v_add3_u32 v168, v32, v190, v192
	v_lshl_add_u64 v[32:33], v[54:55], 0, s[40:41]
	s_add_i32 s88, s35, 0xa000
	s_add_i32 s90, s35, 0xc000
	v_mov_b32_e32 v193, 0
	s_mov_b32 s89, 0
	s_movk_i32 s87, 0x2000
	v_lshl_add_u64 v[176:177], v[56:57], 0, s[48:49]
	v_lshl_add_u64 v[178:179], v[56:57], 0, s[50:51]
	v_lshl_add_u64 v[180:181], v[54:55], 0, s[52:53]
	v_mov_b32_e32 v54, v193
	v_mov_b32_e32 v55, v193
	v_mov_b32_e32 v58, v193
	v_mov_b32_e32 v59, v193
	v_mov_b32_e32 v60, v193
	v_mov_b32_e32 v61, v193
	v_mov_b32_e32 v62, v193
	v_mov_b32_e32 v63, v193
	s_waitcnt vmcnt(3)
	ds_write_b128 v188, v[0:3]
	s_waitcnt vmcnt(2)
	ds_write_b128 v188, v[34:37] offset:1024
	s_waitcnt vmcnt(1)
	ds_write_b128 v188, v[38:41] offset:2048
	s_waitcnt vmcnt(0)
	ds_write_b128 v188, v[42:45] offset:3072
	s_mov_b32 s85, m0
	s_mov_b32 m0, s86
	s_nop 0
	global_load_lds_dwordx4 v[4:5], off
	s_mov_b32 m0, s85
	s_waitcnt vmcnt(3) lgkmcnt(0)
	s_barrier
	ds_read_b128 v[4:7], v189
	ds_read_b128 v[8:11], v189 offset:512
	s_waitcnt lgkmcnt(1)
	v_mfma_f32_32x32x16_bf16 v[16:31], v[4:7], v[0:3], 0
	ds_read_b128 v[46:49], v189 offset:2048
	ds_read_b128 v[50:53], v189 offset:2560
	s_mov_b32 s85, -1
	s_movk_i32 s86, 0x4000
	s_waitcnt lgkmcnt(2)
	v_mfma_f32_32x32x16_bf16 v[0:15], v[8:11], v[0:3], 0
	s_waitcnt lgkmcnt(1)
	v_mfma_f32_32x32x16_bf16 v[16:31], v[46:49], v[34:37], v[16:31]
	s_waitcnt lgkmcnt(0)
	v_mfma_f32_32x32x16_bf16 v[0:15], v[50:53], v[34:37], v[0:15]
	ds_read_b128 v[34:37], v189 offset:4096
	ds_read_b128 v[46:49], v189 offset:4608
	s_waitcnt lgkmcnt(1)
	v_mfma_f32_32x32x16_bf16 v[16:31], v[34:37], v[38:41], v[16:31]
	ds_read_b128 v[34:37], v189 offset:6656
	ds_read_b128 v[50:53], v189 offset:6144
	s_waitcnt lgkmcnt(2)
	v_mfma_f32_32x32x16_bf16 v[0:15], v[46:49], v[38:41], v[0:15]
	v_lshl_add_u64 v[38:39], v[56:57], 0, s[42:43]
	v_lshl_add_u64 v[40:41], v[56:57], 0, s[44:45]
	v_mov_b32_e32 v48, 0
	v_mov_b32_e32 v49, v193
	v_mov_b32_e32 v56, v193
	v_mov_b32_e32 v57, v193
	v_mov_b32_e32 v46, v193
	s_waitcnt lgkmcnt(0)
	v_mfma_f32_32x32x16_bf16 v[16:31], v[50:53], v[42:45], v[16:31]
	v_mov_b32_e32 v50, v193
	v_mov_b32_e32 v51, v193
	v_mov_b32_e32 v52, v193
	v_mov_b32_e32 v53, v193
	v_mov_b32_e32 v47, v193
	v_mfma_f32_32x32x16_bf16 v[0:15], v[34:37], v[42:45], v[0:15]
	s_nop 15
	s_nop 7
	s_waitcnt vmcnt(0) lgkmcnt(0)
	s_barrier
; #define WAIT_BAR(N) asm volatile("s_waitcnt vmcnt(" #N ") lgkmcnt(0)\n\ts_barrier":::"memory")
;   #define DMA_K(t,slot) glds16(ksrc+(long)(t)*KVBLK*KVP,(unsigned)__builtin_amdgcn_readfirstlane(kdst+(slot)))
;   #define DMA_V(t,slot) do{ glds16(vsrc+(long)(t)*KVBLK*KVP,(unsigned)__builtin_amdgcn_readfirstlane(vdst+VM*(slot))); if constexpr(VM==2) glds16(vsrc+64+(long)(t)*KVBLK*KVP,(unsigned)__builtin_amdgcn_readfirstlane(vdst+VM*(slot)+8192)); }while(0)
;   #define ROT() do{sl_prev=sl_cur;sl_cur=sl_next;sl_next=(sl_next==(NSLOT-1)*SLOTB)?0:sl_next+SLOTB;}while(0)
; template<int THRL,int VM,bool NOMAX> __device__ __forceinline__ void attn_unit(const bf16*Qb,const bf16*__restrict__ Kh,const bf16*__restrict__ Vh,bf16*Ob,const int NT,const int sp,float*wscr,char*shm){
;     ...
;   START(pA0,pA1);
;   _Pragma("unroll") for(int r=0;r<16;++r)pA1[r]=__builtin_amdgcn_exp2f(pA1[r]);
;   WAIT_BAR(0);
;   DMA_K(3,0);DMA_V(1,SLOTB);
;   ROT();
;   kload8(kf,kp0+sl_cur);
;   if constexpr(VM==2){WAIT_BAR(3);}else{WAIT_BAR(2);}
;   s16x4 vlo[8],vhi[8]; u32x4 pw0,pw1,pw2,pw3;
	s_mov_b32 s91, m0
	s_mov_b32 m0, s35
	s_nop 0
	global_load_lds_dwordx4 v[32:33], off
	s_mov_b32 m0, s91
	v_mov_b32_e32 v32, 0
	s_mov_b32 s91, m0
	s_mov_b32 m0, s88
	s_nop 0
	global_load_lds_dwordx4 v[38:39], off
	s_mov_b32 m0, s91
	s_mov_b32 s88, m0
	s_mov_b32 m0, s90
	s_nop 0
	global_load_lds_dwordx4 v[40:41], off
	s_mov_b32 m0, s88
	ds_read_b128 v[100:103], v189 offset:8192
	ds_read_b128 v[96:99], v189 offset:8704
	ds_read_b128 v[164:167], v189 offset:10240
	ds_read_b128 v[160:163], v189 offset:10752
	ds_read_b128 v[140:143], v189 offset:12288
	ds_read_b128 v[136:139], v189 offset:12800
	ds_read_b128 v[132:135], v189 offset:14336
	ds_read_b128 v[128:131], v189 offset:14848
	v_exp_f32_e32 v80, v16
	v_exp_f32_e32 v81, v17
	v_exp_f32_e32 v82, v18
	v_exp_f32_e32 v83, v19
	v_exp_f32_e32 v84, v20
	v_exp_f32_e32 v85, v21
	v_exp_f32_e32 v86, v22
	v_exp_f32_e32 v87, v23
	v_exp_f32_e32 v88, v24
	v_exp_f32_e32 v89, v25
	v_exp_f32_e32 v90, v26
	v_exp_f32_e32 v91, v27
	v_exp_f32_e32 v92, v28
	v_exp_f32_e32 v93, v29
	v_exp_f32_e32 v94, v30
	v_exp_f32_e32 v95, v31
	v_exp_f32_e32 v64, v0
	v_exp_f32_e32 v65, v1
	v_exp_f32_e32 v66, v2
	v_exp_f32_e32 v67, v3
	v_exp_f32_e32 v68, v4
	v_exp_f32_e32 v69, v5
	v_exp_f32_e32 v70, v6
	v_exp_f32_e32 v71, v7
	v_exp_f32_e32 v72, v8
	v_exp_f32_e32 v73, v9
	v_exp_f32_e32 v74, v10
	v_exp_f32_e32 v75, v11
	v_exp_f32_e32 v76, v12
	v_exp_f32_e32 v77, v13
	v_exp_f32_e32 v78, v14
	v_exp_f32_e32 v79, v15
	ds_read_b128 v[218:221], v188
	ds_read_b128 v[222:225], v188 offset:1024
	ds_read_b128 v[226:229], v188 offset:2048
	ds_read_b128 v[230:233], v188 offset:3072
	s_waitcnt vmcnt(3) lgkmcnt(0)
	s_barrier
	v_mov_b32_e32 v33, v193
	v_mov_b32_e32 v34, v193
	v_mov_b32_e32 v35, v193
	v_mov_b32_e32 v36, v193
	v_mov_b32_e32 v37, v193
	v_mov_b32_e32 v38, v193
	v_mov_b32_e32 v39, v193
	v_mov_b32_e32 v40, v193
	v_mov_b32_e32 v41, v193
	v_mov_b32_e32 v42, v193
	v_mov_b32_e32 v43, v193
	v_mov_b32_e32 v44, v193
	v_mov_b32_e32 v45, v193
	v_mov_b32_e32 v16, 0
	v_mov_b32_e32 v17, v193
	v_mov_b32_e32 v18, v193
	v_mov_b32_e32 v19, v193
	v_mov_b32_e32 v20, v193
	v_mov_b32_e32 v21, v193
	v_mov_b32_e32 v22, v193
	v_mov_b32_e32 v23, v193
	v_mov_b32_e32 v24, v193
	v_mov_b32_e32 v25, v193
	v_mov_b32_e32 v26, v193
	v_mov_b32_e32 v27, v193
	v_mov_b32_e32 v28, v193
	v_mov_b32_e32 v29, v193
	v_mov_b32_e32 v30, v193
	v_mov_b32_e32 v31, v193
	v_mov_b32_e32 v0, 0
	v_mov_b32_e32 v1, v193
	v_mov_b32_e32 v2, v193
	v_mov_b32_e32 v3, v193
	v_mov_b32_e32 v4, v193
	v_mov_b32_e32 v5, v193
	v_mov_b32_e32 v6, v193
	v_mov_b32_e32 v7, v193
	v_mov_b32_e32 v8, v193
	v_mov_b32_e32 v9, v193
	v_mov_b32_e32 v10, v193
	v_mov_b32_e32 v11, v193
	v_mov_b32_e32 v12, v193
	v_mov_b32_e32 v13, v193
	v_mov_b32_e32 v14, v193
	v_mov_b32_e32 v15, v193
.LBB0_863:
	v_lshl_add_u32 v206, s89, 1, v168
	ds_read_b64_tr_b16 v[194:195], v206 offset:24576
	ds_read_b64_tr_b16 v[196:197], v206 offset:25088
	v_add_f32_e32 v108, v80, v81
	v_add_f32_e32 v108, v82, v108
	v_add_f32_e32 v108, v83, v108
	v_add_f32_e32 v108, v84, v108
	v_add_f32_e32 v108, v85, v108
	v_cvt_pk_bf16_f32 v156, v80, v81
	v_cvt_pk_bf16_f32 v157, v82, v83
	v_mfma_f32_32x32x16_bf16 v[112:127], v[100:103], v[218:221], 0
	ds_read_b64_tr_b16 v[80:81], v206 offset:28672
	ds_read_b64_tr_b16 v[82:83], v206 offset:29184
	v_add_f32_e32 v104, v86, v108
	v_add_f32_e32 v104, v87, v104
	v_add_f32_e32 v104, v88, v104
	v_add_f32_e32 v144, v89, v104
	v_mfma_f32_32x32x16_bf16 v[96:111], v[96:99], v[218:221], 0
	v_cvt_pk_bf16_f32 v158, v84, v85
	v_cvt_pk_bf16_f32 v159, v86, v87
	ds_read_b64_tr_b16 v[84:85], v206 offset:25600
	ds_read_b64_tr_b16 v[86:87], v206 offset:26112
	v_add_f32_e32 v144, v90, v144
	v_add_f32_e32 v144, v91, v144
	v_add_f32_e32 v144, v92, v144
	v_add_f32_e32 v144, v93, v144
	v_cvt_pk_bf16_f32 v152, v88, v89
	v_cvt_pk_bf16_f32 v153, v90, v91
	v_mfma_f32_32x32x16_bf16 v[112:127], v[164:167], v[222:225], v[112:127]
	ds_read_b64_tr_b16 v[88:89], v206 offset:29696
	ds_read_b64_tr_b16 v[90:91], v206 offset:30208
	v_add_f32_e32 v144, v94, v144
	v_add_f32_e32 v144, v95, v144
	v_add_f32_e32 v144, v64, v144
	v_add_f32_e32 v144, v65, v144
	v_mfma_f32_32x32x16_bf16 v[96:111], v[160:163], v[222:225], v[96:111]
	v_cvt_pk_bf16_f32 v154, v92, v93
	v_cvt_pk_bf16_f32 v155, v94, v95
	ds_read_b64_tr_b16 v[92:93], v206 offset:26624
	ds_read_b64_tr_b16 v[94:95], v206 offset:27136
	v_add_f32_e32 v144, v66, v144
	v_add_f32_e32 v144, v67, v144
	v_add_f32_e32 v144, v68, v144
	v_add_f32_e32 v144, v69, v144
	v_cvt_pk_bf16_f32 v148, v64, v65
	v_cvt_pk_bf16_f32 v149, v66, v67
	v_mfma_f32_32x32x16_bf16 v[112:127], v[140:143], v[226:229], v[112:127]
	ds_read_b64_tr_b16 v[198:199], v206 offset:30720
	ds_read_b64_tr_b16 v[200:201], v206 offset:31232
	v_add_f32_e32 v140, v70, v144
	v_add_f32_e32 v140, v71, v140
	v_add_f32_e32 v140, v72, v140
	v_add_f32_e32 v140, v73, v140
	v_mfma_f32_32x32x16_bf16 v[96:111], v[136:139], v[226:229], v[96:111]
	v_cvt_pk_bf16_f32 v150, v68, v69
	v_cvt_pk_bf16_f32 v151, v70, v71
	ds_read_b64_tr_b16 v[202:203], v206 offset:27648
	ds_read_b64_tr_b16 v[204:205], v206 offset:28160
	v_add_f32_e32 v68, v74, v140
	v_add_f32_e32 v68, v75, v68
	v_add_f32_e32 v68, v76, v68
	v_add_f32_e32 v68, v77, v68
	v_cvt_pk_bf16_f32 v144, v72, v73
	v_cvt_pk_bf16_f32 v145, v74, v75
	v_mfma_f32_32x32x16_bf16 v[112:127], v[132:135], v[230:233], v[112:127]
	ds_read_b64_tr_b16 v[72:73], v206 offset:31744
	ds_read_b64_tr_b16 v[74:75], v206 offset:32256
	v_add_f32_e32 v68, v78, v68
	v_add_f32_e32 v68, v79, v68
	v_add_f32_e32 v68, 0, v68
	v_cvt_pk_bf16_f32 v146, v76, v77
	v_mfma_f32_32x32x16_bf16 v[96:111], v[128:131], v[230:233], v[96:111]
	v_cvt_pk_bf16_f32 v147, v78, v79
	s_add_i32 s88, s87, s35
	v_lshl_add_u64 v[64:65], v[180:181], 0, s[54:55]
	s_mov_b32 s89, m0
	s_mov_b32 m0, s88
	s_nop 0
	global_load_lds_dwordx4 v[64:65], off
	s_mov_b32 m0, s89
	s_lshl_b32 s88, s86, 1
	v_lshl_add_u64 v[64:65], v[178:179], 0, s[54:55]
	s_add_i32 s88, s88, s16
	s_mov_b32 s89, m0
	s_mov_b32 m0, s88
	s_nop 0
	global_load_lds_dwordx4 v[64:65], off
	s_mov_b32 m0, s89
	v_lshl_add_u64 v[64:65], v[176:177], 0, s[54:55]
	s_addk_i32 s88, 0x2000
	s_mov_b32 s89, m0
	s_mov_b32 m0, s88
	s_nop 0
	global_load_lds_dwordx4 v[64:65], off
	s_mov_b32 m0, s89
	v_add_f32_e32 v193, v193, v68
	s_waitcnt lgkmcnt(12)
	v_mfma_f32_32x32x16_bf16 v[48:63], v[156:159], v[194:197], v[48:63]
	ds_read_b64_tr_b16 v[76:77], v206 offset:32768
	ds_read_b64_tr_b16 v[78:79], v206 offset:33280
	v_exp_f32_e32 v112, v112
	v_exp_f32_e32 v113, v113
	v_mfma_f32_32x32x16_bf16 v[32:47], v[156:159], v[80:83], v[32:47]
	ds_read_b64_tr_b16 v[194:195], v206 offset:36864
	ds_read_b64_tr_b16 v[196:197], v206 offset:37376
	v_exp_f32_e32 v114, v114
	v_exp_f32_e32 v115, v115
	v_add_u32_e32 v128, s86, v189
	ds_read_b128 v[68:71], v128
	ds_read_b128 v[64:67], v128 offset:512
	s_waitcnt lgkmcnt(14)
	v_mfma_f32_32x32x16_bf16 v[48:63], v[152:155], v[84:87], v[48:63]
	ds_read_b64_tr_b16 v[80:81], v206 offset:33792
	ds_read_b64_tr_b16 v[82:83], v206 offset:34304
	v_exp_f32_e32 v116, v116
	v_exp_f32_e32 v117, v117
	ds_read_b128 v[164:167], v128 offset:2048
	ds_read_b128 v[140:143], v128 offset:2560
	v_mfma_f32_32x32x16_bf16 v[32:47], v[152:155], v[88:91], v[32:47]
	ds_read_b64_tr_b16 v[84:85], v206 offset:37888
	ds_read_b64_tr_b16 v[86:87], v206 offset:38400
	v_exp_f32_e32 v118, v118
	v_exp_f32_e32 v119, v119
	ds_read_b128 v[160:163], v128 offset:4096
	ds_read_b128 v[132:135], v128 offset:4608
	s_waitcnt lgkmcnt(14)
	v_mfma_f32_32x32x16_bf16 v[48:63], v[148:151], v[92:95], v[48:63]
	ds_read_b64_tr_b16 v[88:89], v206 offset:34816
	ds_read_b64_tr_b16 v[90:91], v206 offset:35328
	v_exp_f32_e32 v120, v120
	v_exp_f32_e32 v121, v121
	ds_read_b128 v[136:139], v128 offset:6144
	ds_read_b128 v[128:131], v128 offset:6656
	v_mfma_f32_32x32x16_bf16 v[32:47], v[148:151], v[198:201], v[32:47]
	ds_read_b64_tr_b16 v[92:93], v206 offset:38912
	ds_read_b64_tr_b16 v[94:95], v206 offset:39424
	v_exp_f32_e32 v122, v122
	v_exp_f32_e32 v123, v123
	s_waitcnt lgkmcnt(14)
	v_mfma_f32_32x32x16_bf16 v[48:63], v[144:147], v[202:205], v[48:63]
	ds_read_b64_tr_b16 v[198:199], v206 offset:35840
	ds_read_b64_tr_b16 v[200:201], v206 offset:36352
	v_exp_f32_e32 v124, v124
	v_exp_f32_e32 v125, v125
	v_mfma_f32_32x32x16_bf16 v[32:47], v[144:147], v[72:75], v[32:47]
	ds_read_b64_tr_b16 v[202:203], v206 offset:39936
	ds_read_b64_tr_b16 v[204:205], v206 offset:40448
	v_exp_f32_e32 v126, v126
	v_exp_f32_e32 v127, v127
	s_waitcnt lgkmcnt(14)
	v_mfma_f32_32x32x16_bf16 v[16:31], v[156:159], v[76:79], v[16:31]
	v_exp_f32_e32 v96, v96
	v_exp_f32_e32 v97, v97
	v_mfma_f32_32x32x16_bf16 v[0:15], v[156:159], v[194:197], v[0:15]
	v_exp_f32_e32 v98, v98
	v_exp_f32_e32 v99, v99
	v_mfma_f32_32x32x16_bf16 v[16:31], v[152:155], v[80:83], v[16:31]
	v_exp_f32_e32 v100, v100
	v_exp_f32_e32 v101, v101
	s_waitcnt lgkmcnt(12)
	v_mfma_f32_32x32x16_bf16 v[0:15], v[152:155], v[84:87], v[0:15]
	v_exp_f32_e32 v102, v102
	v_exp_f32_e32 v103, v103
	s_waitcnt lgkmcnt(8)
	v_mfma_f32_32x32x16_bf16 v[16:31], v[148:151], v[88:91], v[16:31]
	v_exp_f32_e32 v104, v104
	v_exp_f32_e32 v105, v105
	s_waitcnt lgkmcnt(4)
	v_mfma_f32_32x32x16_bf16 v[0:15], v[148:151], v[92:95], v[0:15]
	v_exp_f32_e32 v106, v106
	v_exp_f32_e32 v107, v107
	s_waitcnt lgkmcnt(2)
	v_mfma_f32_32x32x16_bf16 v[16:31], v[144:147], v[198:201], v[16:31]
	v_exp_f32_e32 v108, v108
	v_exp_f32_e32 v109, v109
	s_waitcnt lgkmcnt(0)
	v_mfma_f32_32x32x16_bf16 v[0:15], v[144:147], v[202:205], v[0:15]
	v_exp_f32_e32 v110, v110
	v_exp_f32_e32 v111, v111
	s_waitcnt vmcnt(3) lgkmcnt(0)
	s_barrier
	s_add_i32 s88, s86, 0x2000
	s_cmpk_lg_i32 s86, 0x4000
	s_cselect_b32 s88, s88, 0
	v_lshl_add_u32 v206, s87, 1, v168
	ds_read_b64_tr_b16 v[194:195], v206 offset:24576
	ds_read_b64_tr_b16 v[196:197], v206 offset:25088
	v_add_f32_e32 v76, v112, v113
	v_add_f32_e32 v76, v114, v76
	v_add_f32_e32 v76, v115, v76
	v_add_f32_e32 v76, v116, v76
	v_mfma_f32_32x32x16_bf16 v[80:95], v[68:71], v[218:221], 0
	v_add_f32_e32 v76, v117, v76
	v_cvt_pk_bf16_f32 v156, v112, v113
	v_cvt_pk_bf16_f32 v157, v114, v115
	ds_read_b64_tr_b16 v[112:113], v206 offset:28672
	ds_read_b64_tr_b16 v[114:115], v206 offset:29184
	v_add_f32_e32 v72, v118, v76
	v_add_f32_e32 v72, v119, v72
	v_add_f32_e32 v72, v120, v72
	v_add_f32_e32 v144, v121, v72
	v_mfma_f32_32x32x16_bf16 v[64:79], v[64:67], v[218:221], 0
	v_cvt_pk_bf16_f32 v158, v116, v117
	v_cvt_pk_bf16_f32 v159, v118, v119
	ds_read_b64_tr_b16 v[116:117], v206 offset:25600
	ds_read_b64_tr_b16 v[118:119], v206 offset:26112
	v_add_f32_e32 v144, v122, v144
	v_add_f32_e32 v144, v123, v144
	v_add_f32_e32 v144, v124, v144
	v_add_f32_e32 v144, v125, v144
	v_mfma_f32_32x32x16_bf16 v[80:95], v[164:167], v[222:225], v[80:95]
	v_cvt_pk_bf16_f32 v152, v120, v121
	v_cvt_pk_bf16_f32 v153, v122, v123
	ds_read_b64_tr_b16 v[120:121], v206 offset:29696
	ds_read_b64_tr_b16 v[122:123], v206 offset:30208
	v_add_f32_e32 v144, v126, v144
	v_add_f32_e32 v144, v127, v144
	v_add_f32_e32 v144, v96, v144
	v_add_f32_e32 v144, v97, v144
	v_mfma_f32_32x32x16_bf16 v[64:79], v[140:143], v[222:225], v[64:79]
	v_cvt_pk_bf16_f32 v154, v124, v125
	v_cvt_pk_bf16_f32 v155, v126, v127
	ds_read_b64_tr_b16 v[124:125], v206 offset:26624
	ds_read_b64_tr_b16 v[126:127], v206 offset:27136
	v_add_f32_e32 v144, v98, v144
	v_add_f32_e32 v144, v99, v144
	v_add_f32_e32 v144, v100, v144
	v_add_f32_e32 v144, v101, v144
	v_mfma_f32_32x32x16_bf16 v[80:95], v[160:163], v[226:229], v[80:95]
	v_cvt_pk_bf16_f32 v148, v96, v97
	v_cvt_pk_bf16_f32 v149, v98, v99
	ds_read_b64_tr_b16 v[198:199], v206 offset:30720
	ds_read_b64_tr_b16 v[200:201], v206 offset:31232
	v_add_f32_e32 v140, v102, v144
	v_add_f32_e32 v140, v103, v140
	v_add_f32_e32 v140, v104, v140
	v_add_f32_e32 v140, v105, v140
	v_mfma_f32_32x32x16_bf16 v[64:79], v[132:135], v[226:229], v[64:79]
	v_cvt_pk_bf16_f32 v150, v100, v101
	v_cvt_pk_bf16_f32 v151, v102, v103
	ds_read_b64_tr_b16 v[202:203], v206 offset:27648
	ds_read_b64_tr_b16 v[204:205], v206 offset:28160
	v_add_f32_e32 v100, v106, v140
	v_add_f32_e32 v100, v107, v100
	v_add_f32_e32 v100, v108, v100
	v_add_f32_e32 v100, v109, v100
	v_mfma_f32_32x32x16_bf16 v[80:95], v[136:139], v[230:233], v[80:95]
	v_cvt_pk_bf16_f32 v144, v104, v105
	v_cvt_pk_bf16_f32 v145, v106, v107
	ds_read_b64_tr_b16 v[104:105], v206 offset:31744
	ds_read_b64_tr_b16 v[106:107], v206 offset:32256
	v_add_f32_e32 v100, v110, v100
	v_add_f32_e32 v100, v111, v100
	v_add_f32_e32 v100, 0, v100
	v_cvt_pk_bf16_f32 v146, v108, v109
	v_mfma_f32_32x32x16_bf16 v[64:79], v[128:131], v[230:233], v[64:79]
	v_cvt_pk_bf16_f32 v147, v110, v111
	s_add_i32 s87, s86, s35
	s_mov_b32 s89, m0
	s_mov_b32 m0, s87
	s_nop 0
	global_load_lds_dwordx4 v[180:181], off
	s_mov_b32 m0, s89
	s_lshl_b32 s87, s88, 1
	s_add_i32 s87, s87, s16
	s_mov_b32 s89, m0
	s_mov_b32 m0, s87
	s_nop 0
	global_load_lds_dwordx4 v[178:179], off
	s_mov_b32 m0, s89
	s_addk_i32 s87, 0x2000
	s_mov_b32 s89, m0
	s_mov_b32 m0, s87
	s_nop 0
	global_load_lds_dwordx4 v[176:177], off
	s_mov_b32 m0, s89
	v_add_f32_e32 v193, v193, v100
	s_waitcnt lgkmcnt(12)
; #define WAIT_BAR(N) asm volatile("s_waitcnt vmcnt(" #N ") lgkmcnt(0)\n\ts_barrier":::"memory")
;   #define RESC() do{ if(!NOMAX&&resc){ asm volatile("s_waitcnt lgkmcnt(0)":::"memory"); \
;       _Pragma("unroll") for(int d_=0;d_<2*VM;++d_) _Pragma("unroll") for(int r=0;r<16;++r)o[d_][r]*=wsf[crow(r,hi)]; } }while(0)
;   #define ROT() do{sl_prev=sl_cur;sl_cur=sl_next;sl_next=(sl_next==(NSLOT-1)*SLOTB)?0:sl_next+SLOTB;}while(0)
;   #define ENDW(tt) do{ if((tt)+3<NT){ if constexpr(VM==2){WAIT_BAR(3);}else{WAIT_BAR(2);} } else if((tt)+2<NT){ if constexpr(VM==2){WAIT_BAR(2);}else{WAIT_BAR(1);} } else {WAIT_BAR(0);} }while(0)
; template<int THRL,int VM,bool NOMAX> __device__ __forceinline__ void attn_unit(const bf16*Qb,const bf16*__restrict__ Kh,const bf16*__restrict__ Vh,bf16*Ob,const int NT,const int sp,float*wscr,char*shm){
;     ...
;   int t=1;
;   for(;t+5<NT;t+=2){
;     STEP(pB0,pB1,pA0,pA1,t,true,true,true);     if constexpr(VM==2){WAIT_BAR(3);}else{WAIT_BAR(2);} RESC(); ROT();
;     STEP(pA0,pA1,pB0,pB1,t+1,true,true,true);   if constexpr(VM==2){WAIT_BAR(3);}else{WAIT_BAR(2);} RESC(); ROT();
;   }
;     ...
;   for(;t+1<NT;t+=2){
;     STEP(pB0,pB1,pA0,pA1,t,(t+3<NT),(t+1<NT),(t+1<NT));       ENDW(t);   RESC(); ROT();
;     STEP(pA0,pA1,pB0,pB1,t+1,(t+4<NT),(t+2<NT),(t+2<NT));     ENDW(t+1); RESC(); ROT();
	v_mfma_f32_32x32x16_bf16 v[48:63], v[156:159], v[194:197], v[48:63]
	ds_read_b64_tr_b16 v[108:109], v206 offset:32768
	ds_read_b64_tr_b16 v[110:111], v206 offset:33280
	v_exp_f32_e32 v80, v80
	v_exp_f32_e32 v81, v81
	v_mfma_f32_32x32x16_bf16 v[32:47], v[156:159], v[112:115], v[32:47]
	ds_read_b64_tr_b16 v[194:195], v206 offset:36864
	ds_read_b64_tr_b16 v[196:197], v206 offset:37376
	v_exp_f32_e32 v82, v82
	v_exp_f32_e32 v83, v83
	v_add_u32_e32 v128, s88, v189
	ds_read_b128 v[100:103], v128
	ds_read_b128 v[96:99], v128 offset:512
	s_waitcnt lgkmcnt(14)
	v_mfma_f32_32x32x16_bf16 v[48:63], v[152:155], v[116:119], v[48:63]
	ds_read_b64_tr_b16 v[112:113], v206 offset:33792
	ds_read_b64_tr_b16 v[114:115], v206 offset:34304
	v_exp_f32_e32 v84, v84
	v_exp_f32_e32 v85, v85
	ds_read_b128 v[164:167], v128 offset:2048
	ds_read_b128 v[160:163], v128 offset:2560
	v_mfma_f32_32x32x16_bf16 v[32:47], v[152:155], v[120:123], v[32:47]
	ds_read_b64_tr_b16 v[116:117], v206 offset:37888
	ds_read_b64_tr_b16 v[118:119], v206 offset:38400
	v_exp_f32_e32 v86, v86
	v_exp_f32_e32 v87, v87
	ds_read_b128 v[140:143], v128 offset:4096
	ds_read_b128 v[136:139], v128 offset:4608
	s_waitcnt lgkmcnt(14)
	v_mfma_f32_32x32x16_bf16 v[48:63], v[148:151], v[124:127], v[48:63]
	ds_read_b64_tr_b16 v[120:121], v206 offset:34816
	ds_read_b64_tr_b16 v[122:123], v206 offset:35328
	v_exp_f32_e32 v88, v88
	v_exp_f32_e32 v89, v89
	ds_read_b128 v[132:135], v128 offset:6144
	ds_read_b128 v[128:131], v128 offset:6656
	v_mfma_f32_32x32x16_bf16 v[32:47], v[148:151], v[198:201], v[32:47]
	ds_read_b64_tr_b16 v[124:125], v206 offset:38912
	ds_read_b64_tr_b16 v[126:127], v206 offset:39424
	v_exp_f32_e32 v90, v90
	v_exp_f32_e32 v91, v91
	s_waitcnt lgkmcnt(14)
	v_mfma_f32_32x32x16_bf16 v[48:63], v[144:147], v[202:205], v[48:63]
	ds_read_b64_tr_b16 v[198:199], v206 offset:35840
	ds_read_b64_tr_b16 v[200:201], v206 offset:36352
	v_exp_f32_e32 v92, v92
	v_exp_f32_e32 v93, v93
	v_mfma_f32_32x32x16_bf16 v[32:47], v[144:147], v[104:107], v[32:47]
	ds_read_b64_tr_b16 v[202:203], v206 offset:39936
	ds_read_b64_tr_b16 v[204:205], v206 offset:40448
	v_exp_f32_e32 v94, v94
	v_exp_f32_e32 v95, v95
	s_waitcnt lgkmcnt(14)
	v_mfma_f32_32x32x16_bf16 v[16:31], v[156:159], v[108:111], v[16:31]
	v_exp_f32_e32 v64, v64
	v_exp_f32_e32 v65, v65
	v_mfma_f32_32x32x16_bf16 v[0:15], v[156:159], v[194:197], v[0:15]
	v_exp_f32_e32 v66, v66
	v_exp_f32_e32 v67, v67
	v_mfma_f32_32x32x16_bf16 v[16:31], v[152:155], v[112:115], v[16:31]
	v_exp_f32_e32 v68, v68
	v_exp_f32_e32 v69, v69
	s_waitcnt lgkmcnt(12)
	v_mfma_f32_32x32x16_bf16 v[0:15], v[152:155], v[116:119], v[0:15]
	v_exp_f32_e32 v70, v70
	v_exp_f32_e32 v71, v71
	s_waitcnt lgkmcnt(8)
	v_mfma_f32_32x32x16_bf16 v[16:31], v[148:151], v[120:123], v[16:31]
	v_exp_f32_e32 v72, v72
	v_exp_f32_e32 v73, v73
	s_waitcnt lgkmcnt(4)
	v_mfma_f32_32x32x16_bf16 v[0:15], v[148:151], v[124:127], v[0:15]
	v_exp_f32_e32 v74, v74
	v_exp_f32_e32 v75, v75
	s_waitcnt lgkmcnt(2)
	v_mfma_f32_32x32x16_bf16 v[16:31], v[144:147], v[198:201], v[16:31]
	v_exp_f32_e32 v76, v76
	v_exp_f32_e32 v77, v77
	s_waitcnt lgkmcnt(0)
	v_mfma_f32_32x32x16_bf16 v[0:15], v[144:147], v[202:205], v[0:15]
	v_exp_f32_e32 v78, v78
	v_exp_f32_e32 v79, v79
	s_add_i32 s90, s88, 0x2000
	s_waitcnt vmcnt(3) lgkmcnt(0)
	s_barrier
	s_cmpk_lg_i32 s88, 0x4000
	s_mov_b32 s89, s86
	s_cselect_b32 s86, s90, 0
	s_add_i32 s85, s85, 2
	v_lshl_add_u64 v[176:177], v[176:177], 0, s[56:57]
	v_lshl_add_u64 v[178:179], v[178:179], 0, s[56:57]
	v_lshl_add_u64 v[180:181], v[180:181], 0, s[56:57]
	s_mov_b32 s87, s88
	s_cmpk_lt_u32 s85, 0x79
	s_cbranch_scc1 .LBB0_863
	s_and_b32 s34, s34, 0x3fffffc0
	s_lshl_b32 s34, s34, 2
	s_add_i32 s34, s34, 0
	s_add_i32 s34, s34, 0x12000
	s_cmp_lg_u32 0, -1
	s_cselect_b32 s85, 0, 0
	s_add_i32 s86, s85, 0x6000
	v_add_u32_e32 v104, s86, v191
	v_add3_u32 v176, v104, v190, v192
	v_add_u32_e32 v177, 0x6000, v168
	ds_read_b64_tr_b16 v[178:179], v168 offset:57344
	ds_read_b64_tr_b16 v[180:181], v168 offset:57856
	v_add_f32_e32 v108, v80, v81
	ds_read_b128 v[104:107], v188
	v_add_f32_e32 v108, v82, v108
	v_add_f32_e32 v108, v83, v108
	v_add_f32_e32 v108, v84, v108
	v_add_f32_e32 v108, v85, v108
	v_cvt_pk_bf16_f32 v156, v80, v81
	v_cvt_pk_bf16_f32 v157, v82, v83
	s_waitcnt lgkmcnt(0)
	v_mfma_f32_32x32x16_bf16 v[112:127], v[100:103], v[104:107], 0
	ds_read_b64_tr_b16 v[80:81], v168 offset:61440
	ds_read_b64_tr_b16 v[82:83], v168 offset:61952
	ds_read_b128 v[100:103], v188
	v_add_f32_e32 v104, v86, v108
	v_add_f32_e32 v104, v87, v104
	v_add_f32_e32 v104, v88, v104
	v_add_f32_e32 v144, v89, v104
	v_cvt_pk_bf16_f32 v158, v84, v85
	v_cvt_pk_bf16_f32 v159, v86, v87
	s_waitcnt lgkmcnt(0)
	v_mfma_f32_32x32x16_bf16 v[96:111], v[96:99], v[100:103], 0
	ds_read_b64_tr_b16 v[84:85], v168 offset:58368
	ds_read_b64_tr_b16 v[86:87], v168 offset:58880
	ds_read_b128 v[194:197], v188 offset:1024
	v_add_f32_e32 v144, v90, v144
	v_add_f32_e32 v144, v91, v144
	v_add_f32_e32 v144, v92, v144
	v_add_f32_e32 v144, v93, v144
	v_cvt_pk_bf16_f32 v152, v88, v89
	v_cvt_pk_bf16_f32 v153, v90, v91
	s_waitcnt lgkmcnt(0)
	v_mfma_f32_32x32x16_bf16 v[112:127], v[164:167], v[194:197], v[112:127]
	ds_read_b64_tr_b16 v[88:89], v168 offset:62464
	ds_read_b64_tr_b16 v[90:91], v168 offset:62976
	ds_read_b128 v[164:167], v188 offset:1024
	v_add_f32_e32 v144, v94, v144
	v_add_f32_e32 v144, v95, v144
	v_add_f32_e32 v144, v64, v144
	v_add_f32_e32 v144, v65, v144
	v_cvt_pk_bf16_f32 v154, v92, v93
	v_cvt_pk_bf16_f32 v155, v94, v95
	s_waitcnt lgkmcnt(0)
	v_mfma_f32_32x32x16_bf16 v[96:111], v[160:163], v[164:167], v[96:111]
	ds_read_b64_tr_b16 v[194:195], v168 offset:59392
	ds_read_b64_tr_b16 v[196:197], v168 offset:59904
	ds_read_b128 v[92:95], v188 offset:2048
	v_add_f32_e32 v144, v66, v144
	v_add_f32_e32 v144, v67, v144
	v_add_f32_e32 v144, v68, v144
	v_add_f32_e32 v144, v69, v144
	v_cvt_pk_bf16_f32 v148, v64, v65
	v_cvt_pk_bf16_f32 v149, v66, v67
	s_waitcnt lgkmcnt(0)
	v_mfma_f32_32x32x16_bf16 v[112:127], v[140:143], v[92:95], v[112:127]
	ds_read_b64_tr_b16 v[140:141], v168 offset:63488
	ds_read_b64_tr_b16 v[142:143], v168 offset:64000
	ds_read_b128 v[64:67], v188 offset:2048
	v_add_f32_e32 v92, v70, v144
	v_add_f32_e32 v92, v71, v92
	v_add_f32_e32 v92, v72, v92
	v_add_f32_e32 v92, v73, v92
	v_cvt_pk_bf16_f32 v150, v68, v69
	v_cvt_pk_bf16_f32 v151, v70, v71
	s_waitcnt lgkmcnt(0)
	v_mfma_f32_32x32x16_bf16 v[96:111], v[136:139], v[64:67], v[96:111]
	ds_read_b64_tr_b16 v[136:137], v168 offset:60416
	ds_read_b64_tr_b16 v[138:139], v168 offset:60928
	ds_read_b128 v[64:67], v188 offset:3072
	v_add_f32_e32 v68, v74, v92
	v_add_f32_e32 v68, v75, v68
	v_add_f32_e32 v68, v76, v68
	v_add_f32_e32 v68, v77, v68
	v_cvt_pk_bf16_f32 v144, v72, v73
	v_cvt_pk_bf16_f32 v145, v74, v75
	s_waitcnt lgkmcnt(0)
	v_mfma_f32_32x32x16_bf16 v[112:127], v[132:135], v[64:67], v[112:127]
	ds_read_b64_tr_b16 v[72:73], v168 offset:64512
	ds_read_b64_tr_b16 v[74:75], v168 offset:65024
	ds_read_b128 v[64:67], v188 offset:3072
	v_add_f32_e32 v68, v78, v68
	v_add_f32_e32 v68, v79, v68
	v_add_f32_e32 v68, 0, v68
	v_cvt_pk_bf16_f32 v146, v76, v77
	v_cvt_pk_bf16_f32 v147, v78, v79
	s_waitcnt lgkmcnt(0)
	v_mfma_f32_32x32x16_bf16 v[96:111], v[128:131], v[64:67], v[96:111]
	v_lshl_add_u64 v[64:65], v[174:175], 0, s[58:59]
	s_mov_b32 s86, m0
	s_mov_b32 m0, s35
	s_nop 0
	global_load_lds_dwordx4 v[64:65], off
	s_mov_b32 m0, s86
	s_add_i32 s85, s85, s17
	v_lshl_add_u64 v[64:65], v[170:171], 0, s[60:61]
	s_add_i32 s17, s85, 0xa000
	s_mov_b32 s35, m0
	s_mov_b32 m0, s17
	s_nop 0
	global_load_lds_dwordx4 v[64:65], off
	s_mov_b32 m0, s35
	v_lshl_add_u64 v[64:65], v[172:173], 0, s[60:61]
	s_add_i32 s35, s17, 0x2000
	s_mov_b32 s86, m0
	s_mov_b32 m0, s35
	s_nop 0
	global_load_lds_dwordx4 v[64:65], off
	s_mov_b32 m0, s86
	v_add_f32_e32 v198, v193, v68
	v_mfma_f32_32x32x16_bf16 v[48:63], v[156:159], v[178:181], v[48:63]
	ds_read_b64_tr_b16 v[76:77], v177 offset:40960
	ds_read_b64_tr_b16 v[78:79], v177 offset:41472
	v_exp_f32_e32 v112, v112
	v_exp_f32_e32 v113, v113
	v_mfma_f32_32x32x16_bf16 v[32:47], v[156:159], v[80:83], v[32:47]
	ds_read_b64_tr_b16 v[128:129], v177 offset:45056
	ds_read_b64_tr_b16 v[130:131], v177 offset:45568
	v_exp_f32_e32 v114, v114
	v_exp_f32_e32 v115, v115
	ds_read_b128 v[68:71], v189 offset:8192
	ds_read_b128 v[64:67], v189 offset:8704
	v_mfma_f32_32x32x16_bf16 v[48:63], v[152:155], v[84:87], v[48:63]
	ds_read_b64_tr_b16 v[132:133], v177 offset:41984
	ds_read_b64_tr_b16 v[134:135], v177 offset:42496
	v_exp_f32_e32 v116, v116
	v_exp_f32_e32 v117, v117
	ds_read_b128 v[164:167], v189 offset:10240
	ds_read_b128 v[92:95], v189 offset:10752
	v_mfma_f32_32x32x16_bf16 v[32:47], v[152:155], v[88:91], v[32:47]
	ds_read_b64_tr_b16 v[178:179], v177 offset:46080
	ds_read_b64_tr_b16 v[180:181], v177 offset:46592
	v_exp_f32_e32 v118, v118
	v_exp_f32_e32 v119, v119
	ds_read_b128 v[160:163], v189 offset:12288
	ds_read_b128 v[84:87], v189 offset:12800
	v_mfma_f32_32x32x16_bf16 v[48:63], v[148:151], v[194:197], v[48:63]
	ds_read_b64_tr_b16 v[190:191], v177 offset:43008
	ds_read_b64_tr_b16 v[192:193], v177 offset:43520
	v_exp_f32_e32 v120, v120
	v_exp_f32_e32 v121, v121
	ds_read_b128 v[88:91], v189 offset:14336
	ds_read_b128 v[80:83], v189 offset:14848
	v_mfma_f32_32x32x16_bf16 v[32:47], v[148:151], v[140:143], v[32:47]
	ds_read_b64_tr_b16 v[194:195], v177 offset:47104
	ds_read_b64_tr_b16 v[196:197], v177 offset:47616
	v_exp_f32_e32 v122, v122
	v_exp_f32_e32 v123, v123
	v_mfma_f32_32x32x16_bf16 v[48:63], v[144:147], v[136:139], v[48:63]
	ds_read_b64_tr_b16 v[140:141], v177 offset:44032
	ds_read_b64_tr_b16 v[142:143], v177 offset:44544
	v_exp_f32_e32 v124, v124
	v_exp_f32_e32 v125, v125
	v_mfma_f32_32x32x16_bf16 v[32:47], v[144:147], v[72:75], v[32:47]
	ds_read_b64_tr_b16 v[136:137], v177 offset:48128
	ds_read_b64_tr_b16 v[138:139], v177 offset:48640
	v_exp_f32_e32 v126, v126
	v_exp_f32_e32 v127, v127
	s_waitcnt lgkmcnt(14)
	v_mfma_f32_32x32x16_bf16 v[16:31], v[156:159], v[76:79], v[16:31]
	v_exp_f32_e32 v96, v96
	v_exp_f32_e32 v97, v97
	v_mfma_f32_32x32x16_bf16 v[0:15], v[156:159], v[128:131], v[0:15]
	v_exp_f32_e32 v98, v98
	v_exp_f32_e32 v99, v99
	v_mfma_f32_32x32x16_bf16 v[16:31], v[152:155], v[132:135], v[16:31]
	v_exp_f32_e32 v100, v100
	v_exp_f32_e32 v101, v101
	s_waitcnt lgkmcnt(12)
	v_mfma_f32_32x32x16_bf16 v[0:15], v[152:155], v[178:181], v[0:15]
	v_exp_f32_e32 v102, v102
	v_exp_f32_e32 v103, v103
	s_waitcnt lgkmcnt(8)
	v_mfma_f32_32x32x16_bf16 v[16:31], v[148:151], v[190:193], v[16:31]
	v_exp_f32_e32 v104, v104
	v_exp_f32_e32 v105, v105
	s_waitcnt lgkmcnt(4)
	v_mfma_f32_32x32x16_bf16 v[0:15], v[148:151], v[194:197], v[0:15]
	v_exp_f32_e32 v106, v106
	v_exp_f32_e32 v107, v107
	s_waitcnt lgkmcnt(2)
	v_mfma_f32_32x32x16_bf16 v[16:31], v[144:147], v[140:143], v[16:31]
	v_exp_f32_e32 v108, v108
	v_exp_f32_e32 v109, v109
	s_waitcnt lgkmcnt(0)
	v_mfma_f32_32x32x16_bf16 v[0:15], v[144:147], v[136:139], v[0:15]
	v_exp_f32_e32 v110, v110
	v_exp_f32_e32 v111, v111
	s_waitcnt vmcnt(3) lgkmcnt(0)
	s_barrier
	ds_read_b64_tr_b16 v[178:179], v168 offset:24576
	ds_read_b64_tr_b16 v[180:181], v168 offset:25088
	v_add_f32_e32 v76, v112, v113
	ds_read_b128 v[72:75], v188
	v_add_f32_e32 v76, v114, v76
	v_add_f32_e32 v76, v115, v76
	v_add_f32_e32 v76, v116, v76
	v_add_f32_e32 v76, v117, v76
	v_cvt_pk_bf16_f32 v156, v112, v113
	v_cvt_pk_bf16_f32 v157, v114, v115
	s_waitcnt lgkmcnt(0)
	v_mfma_f32_32x32x16_bf16 v[128:143], v[68:71], v[72:75], 0
	ds_read_b64_tr_b16 v[112:113], v168 offset:28672
	ds_read_b64_tr_b16 v[114:115], v168 offset:29184
	ds_read_b128 v[68:71], v188
	v_add_f32_e32 v72, v118, v76
	v_add_f32_e32 v72, v119, v72
	v_add_f32_e32 v72, v120, v72
	v_add_f32_e32 v144, v121, v72
	s_waitcnt lgkmcnt(0)
	v_mfma_f32_32x32x16_bf16 v[64:79], v[64:67], v[68:71], 0
	v_cvt_pk_bf16_f32 v158, v116, v117
	v_cvt_pk_bf16_f32 v159, v118, v119
	ds_read_b64_tr_b16 v[116:117], v168 offset:25600
	ds_read_b64_tr_b16 v[118:119], v168 offset:26112
	ds_read_b128 v[190:193], v188 offset:1024
	v_add_f32_e32 v144, v122, v144
	v_add_f32_e32 v144, v123, v144
	v_add_f32_e32 v144, v124, v144
	v_add_f32_e32 v144, v125, v144
	v_cvt_pk_bf16_f32 v152, v120, v121
	v_cvt_pk_bf16_f32 v153, v122, v123
	s_waitcnt lgkmcnt(0)
	v_mfma_f32_32x32x16_bf16 v[128:143], v[164:167], v[190:193], v[128:143]
	ds_read_b64_tr_b16 v[120:121], v168 offset:29696
	ds_read_b64_tr_b16 v[122:123], v168 offset:30208
	ds_read_b128 v[164:167], v188 offset:1024
	v_add_f32_e32 v144, v126, v144
	v_add_f32_e32 v144, v127, v144
	v_add_f32_e32 v144, v96, v144
	v_add_f32_e32 v144, v97, v144
	s_waitcnt lgkmcnt(0)
	v_mfma_f32_32x32x16_bf16 v[64:79], v[92:95], v[164:167], v[64:79]
	v_cvt_pk_bf16_f32 v154, v124, v125
	v_cvt_pk_bf16_f32 v155, v126, v127
	ds_read_b64_tr_b16 v[92:93], v168 offset:26624
	ds_read_b64_tr_b16 v[94:95], v168 offset:27136
	ds_read_b128 v[124:127], v188 offset:2048
	v_add_f32_e32 v144, v98, v144
	v_add_f32_e32 v144, v99, v144
	v_add_f32_e32 v144, v100, v144
	v_add_f32_e32 v144, v101, v144
	v_cvt_pk_bf16_f32 v148, v96, v97
	v_cvt_pk_bf16_f32 v149, v98, v99
	s_waitcnt lgkmcnt(0)
	v_mfma_f32_32x32x16_bf16 v[128:143], v[160:163], v[124:127], v[128:143]
	ds_read_b64_tr_b16 v[96:97], v168 offset:30720
	ds_read_b64_tr_b16 v[98:99], v168 offset:31232
	ds_read_b128 v[124:127], v188 offset:2048
	v_add_f32_e32 v144, v102, v144
	v_add_f32_e32 v144, v103, v144
	v_add_f32_e32 v144, v104, v144
	v_add_f32_e32 v144, v105, v144
	s_waitcnt lgkmcnt(0)
	v_mfma_f32_32x32x16_bf16 v[64:79], v[84:87], v[124:127], v[64:79]
	v_cvt_pk_bf16_f32 v150, v100, v101
	v_cvt_pk_bf16_f32 v151, v102, v103
	ds_read_b64_tr_b16 v[100:101], v168 offset:27648
	ds_read_b64_tr_b16 v[102:103], v168 offset:28160
	ds_read_b128 v[84:87], v188 offset:3072
	v_add_f32_e32 v124, v106, v144
	v_add_f32_e32 v124, v107, v124
	v_add_f32_e32 v124, v108, v124
	v_add_f32_e32 v124, v109, v124
	v_cvt_pk_bf16_f32 v144, v104, v105
	v_cvt_pk_bf16_f32 v145, v106, v107
	s_waitcnt lgkmcnt(0)
	v_mfma_f32_32x32x16_bf16 v[128:143], v[88:91], v[84:87], v[128:143]
	ds_read_b64_tr_b16 v[88:89], v168 offset:31744
	ds_read_b64_tr_b16 v[90:91], v168 offset:32256
	ds_read_b128 v[84:87], v188 offset:3072
	v_add_f32_e32 v104, v110, v124
	v_add_f32_e32 v104, v111, v104
	v_add_f32_e32 v104, 0, v104
	v_cvt_pk_bf16_f32 v146, v108, v109
	s_waitcnt lgkmcnt(0)
	v_mfma_f32_32x32x16_bf16 v[64:79], v[80:83], v[84:87], v[64:79]
	v_cvt_pk_bf16_f32 v147, v110, v111
	v_lshl_add_u64 v[80:81], v[174:175], 0, s[62:63]
	s_add_i32 s86, s85, 0x2000
	s_mov_b32 s87, m0
	s_mov_b32 m0, s86
	s_nop 0
	global_load_lds_dwordx4 v[80:81], off
	s_mov_b32 m0, s87
	v_lshl_add_u64 v[80:81], v[170:171], 0, s[64:65]
	s_add_i32 s86, s85, 0xe000
	s_mov_b32 s87, m0
	s_mov_b32 m0, s86
	s_nop 0
	global_load_lds_dwordx4 v[80:81], off
	s_mov_b32 m0, s87
	v_lshl_add_u64 v[80:81], v[172:173], 0, s[64:65]
	s_add_i32 s85, s85, 0x10000
	s_mov_b32 s86, m0
	s_mov_b32 m0, s85
	s_nop 0
	global_load_lds_dwordx4 v[80:81], off
	s_mov_b32 m0, s86
	v_add_f32_e32 v198, v198, v104
	v_mfma_f32_32x32x16_bf16 v[48:63], v[156:159], v[178:181], v[48:63]
	ds_read_b64_tr_b16 v[104:105], v168 offset:32768
	ds_read_b64_tr_b16 v[106:107], v168 offset:33280
	v_exp_f32_e32 v128, v128
	v_exp_f32_e32 v129, v129
	v_mfma_f32_32x32x16_bf16 v[32:47], v[156:159], v[112:115], v[32:47]
	ds_read_b64_tr_b16 v[108:109], v168 offset:36864
	ds_read_b64_tr_b16 v[110:111], v168 offset:37376
	v_exp_f32_e32 v130, v130
	v_exp_f32_e32 v131, v131
	ds_read_b128 v[84:87], v189 offset:16384
	ds_read_b128 v[80:83], v189 offset:16896
	v_mfma_f32_32x32x16_bf16 v[48:63], v[152:155], v[116:119], v[48:63]
	ds_read_b64_tr_b16 v[178:179], v168 offset:33792
	ds_read_b64_tr_b16 v[180:181], v168 offset:34304
	v_exp_f32_e32 v132, v132
	v_exp_f32_e32 v133, v133
	ds_read_b128 v[164:167], v189 offset:18432
	ds_read_b128 v[124:127], v189 offset:18944
	v_mfma_f32_32x32x16_bf16 v[32:47], v[152:155], v[120:123], v[32:47]
	ds_read_b64_tr_b16 v[190:191], v168 offset:37888
	ds_read_b64_tr_b16 v[192:193], v168 offset:38400
	v_exp_f32_e32 v134, v134
	v_exp_f32_e32 v135, v135
	ds_read_b128 v[160:163], v189 offset:20480
	ds_read_b128 v[116:119], v189 offset:20992
	v_mfma_f32_32x32x16_bf16 v[48:63], v[148:151], v[92:95], v[48:63]
	ds_read_b64_tr_b16 v[194:195], v168 offset:34816
	ds_read_b64_tr_b16 v[196:197], v168 offset:35328
	v_exp_f32_e32 v136, v136
	v_exp_f32_e32 v137, v137
	ds_read_b128 v[120:123], v189 offset:22528
	ds_read_b128 v[112:115], v189 offset:23040
	v_mfma_f32_32x32x16_bf16 v[32:47], v[148:151], v[96:99], v[32:47]
	ds_read_b64_tr_b16 v[92:93], v168 offset:38912
	ds_read_b64_tr_b16 v[94:95], v168 offset:39424
	v_exp_f32_e32 v138, v138
	v_exp_f32_e32 v139, v139
	v_mfma_f32_32x32x16_bf16 v[48:63], v[144:147], v[100:103], v[48:63]
	ds_read_b64_tr_b16 v[96:97], v168 offset:35840
	ds_read_b64_tr_b16 v[98:99], v168 offset:36352
	v_exp_f32_e32 v140, v140
	v_exp_f32_e32 v141, v141
	v_mfma_f32_32x32x16_bf16 v[32:47], v[144:147], v[88:91], v[32:47]
	ds_read_b64_tr_b16 v[100:101], v168 offset:39936
	ds_read_b64_tr_b16 v[102:103], v168 offset:40448
	v_exp_f32_e32 v142, v142
	v_exp_f32_e32 v143, v143
	s_waitcnt lgkmcnt(14)
	v_mfma_f32_32x32x16_bf16 v[16:31], v[156:159], v[104:107], v[16:31]
	v_exp_f32_e32 v64, v64
	v_exp_f32_e32 v65, v65
	v_mfma_f32_32x32x16_bf16 v[0:15], v[156:159], v[108:111], v[0:15]
	v_exp_f32_e32 v66, v66
	v_exp_f32_e32 v67, v67
	v_mfma_f32_32x32x16_bf16 v[16:31], v[152:155], v[178:181], v[16:31]
	v_exp_f32_e32 v68, v68
	v_exp_f32_e32 v69, v69
	s_waitcnt lgkmcnt(12)
	v_mfma_f32_32x32x16_bf16 v[0:15], v[152:155], v[190:193], v[0:15]
	v_exp_f32_e32 v70, v70
	v_exp_f32_e32 v71, v71
	s_waitcnt lgkmcnt(8)
	v_mfma_f32_32x32x16_bf16 v[16:31], v[148:151], v[194:197], v[16:31]
	v_exp_f32_e32 v72, v72
	v_exp_f32_e32 v73, v73
	s_waitcnt lgkmcnt(4)
	v_mfma_f32_32x32x16_bf16 v[0:15], v[148:151], v[92:95], v[0:15]
	v_exp_f32_e32 v74, v74
	v_exp_f32_e32 v75, v75
	s_waitcnt lgkmcnt(2)
	v_mfma_f32_32x32x16_bf16 v[16:31], v[144:147], v[96:99], v[16:31]
	v_exp_f32_e32 v76, v76
	v_exp_f32_e32 v77, v77
	s_waitcnt lgkmcnt(0)
	v_mfma_f32_32x32x16_bf16 v[0:15], v[144:147], v[100:103], v[0:15]
	v_exp_f32_e32 v78, v78
	v_exp_f32_e32 v79, v79
	s_waitcnt vmcnt(3) lgkmcnt(0)
	s_barrier
	ds_read_b64_tr_b16 v[178:179], v168 offset:40960
	ds_read_b64_tr_b16 v[180:181], v168 offset:41472
	v_add_f32_e32 v92, v128, v129
	ds_read_b128 v[88:91], v188
	v_add_f32_e32 v92, v130, v92
	v_add_f32_e32 v92, v131, v92
	v_add_f32_e32 v92, v132, v92
	v_add_f32_e32 v92, v133, v92
	v_cvt_pk_bf16_f32 v156, v128, v129
	v_cvt_pk_bf16_f32 v157, v130, v131
	s_waitcnt lgkmcnt(0)
	v_mfma_f32_32x32x16_bf16 v[96:111], v[84:87], v[88:91], 0
	ds_read_b64_tr_b16 v[128:129], v168 offset:45056
	ds_read_b64_tr_b16 v[130:131], v168 offset:45568
	ds_read_b128 v[84:87], v188
	v_add_f32_e32 v88, v134, v92
	v_add_f32_e32 v88, v135, v88
	v_add_f32_e32 v88, v136, v88
	v_add_f32_e32 v144, v137, v88
	v_cvt_pk_bf16_f32 v158, v132, v133
	v_cvt_pk_bf16_f32 v159, v134, v135
	s_waitcnt lgkmcnt(0)
	v_mfma_f32_32x32x16_bf16 v[80:95], v[80:83], v[84:87], 0
	ds_read_b64_tr_b16 v[132:133], v168 offset:41984
	ds_read_b64_tr_b16 v[134:135], v168 offset:42496
	ds_read_b128 v[190:193], v188 offset:1024
	v_add_f32_e32 v144, v138, v144
	v_add_f32_e32 v144, v139, v144
	v_add_f32_e32 v144, v140, v144
	v_add_f32_e32 v144, v141, v144
	v_cvt_pk_bf16_f32 v152, v136, v137
	v_cvt_pk_bf16_f32 v153, v138, v139
	s_waitcnt lgkmcnt(0)
	v_mfma_f32_32x32x16_bf16 v[96:111], v[164:167], v[190:193], v[96:111]
	ds_read_b64_tr_b16 v[136:137], v168 offset:46080
	ds_read_b64_tr_b16 v[138:139], v168 offset:46592
	ds_read_b128 v[164:167], v188 offset:1024
	v_add_f32_e32 v144, v142, v144
	v_add_f32_e32 v144, v143, v144
	v_add_f32_e32 v144, v64, v144
	v_add_f32_e32 v144, v65, v144
	v_cvt_pk_bf16_f32 v154, v140, v141
	v_cvt_pk_bf16_f32 v155, v142, v143
	s_waitcnt lgkmcnt(0)
	v_mfma_f32_32x32x16_bf16 v[80:95], v[124:127], v[164:167], v[80:95]
	ds_read_b64_tr_b16 v[124:125], v168 offset:43008
	ds_read_b64_tr_b16 v[126:127], v168 offset:43520
	ds_read_b128 v[140:143], v188 offset:2048
	v_add_f32_e32 v144, v66, v144
	v_add_f32_e32 v144, v67, v144
	v_add_f32_e32 v144, v68, v144
	v_add_f32_e32 v144, v69, v144
	v_cvt_pk_bf16_f32 v148, v64, v65
	v_cvt_pk_bf16_f32 v149, v66, v67
	s_waitcnt lgkmcnt(0)
	v_mfma_f32_32x32x16_bf16 v[96:111], v[160:163], v[140:143], v[96:111]
	ds_read_b64_tr_b16 v[190:191], v168 offset:47104
	ds_read_b64_tr_b16 v[192:193], v168 offset:47616
	ds_read_b128 v[64:67], v188 offset:2048
	v_add_f32_e32 v140, v70, v144
	v_add_f32_e32 v140, v71, v140
	v_add_f32_e32 v140, v72, v140
	v_add_f32_e32 v140, v73, v140
	v_cvt_pk_bf16_f32 v150, v68, v69
	v_cvt_pk_bf16_f32 v151, v70, v71
	s_waitcnt lgkmcnt(0)
	v_mfma_f32_32x32x16_bf16 v[80:95], v[116:119], v[64:67], v[80:95]
	ds_read_b64_tr_b16 v[116:117], v168 offset:44032
	ds_read_b64_tr_b16 v[118:119], v168 offset:44544
	ds_read_b128 v[64:67], v188 offset:3072
	v_add_f32_e32 v68, v74, v140
	v_add_f32_e32 v68, v75, v68
	v_add_f32_e32 v68, v76, v68
	v_add_f32_e32 v68, v77, v68
	v_cvt_pk_bf16_f32 v144, v72, v73
	v_cvt_pk_bf16_f32 v145, v74, v75
	s_waitcnt lgkmcnt(0)
	v_mfma_f32_32x32x16_bf16 v[96:111], v[120:123], v[64:67], v[96:111]
	ds_read_b64_tr_b16 v[72:73], v168 offset:48128
	ds_read_b64_tr_b16 v[74:75], v168 offset:48640
	ds_read_b128 v[64:67], v188 offset:3072
	v_add_f32_e32 v68, v78, v68
	v_add_f32_e32 v68, v79, v68
	v_add_f32_e32 v68, 0, v68
	v_cvt_pk_bf16_f32 v146, v76, v77
	v_cvt_pk_bf16_f32 v147, v78, v79
	s_waitcnt lgkmcnt(0)
	v_mfma_f32_32x32x16_bf16 v[80:95], v[112:115], v[64:67], v[80:95]
	v_lshl_add_u64 v[64:65], v[170:171], 0, s[58:59]
	s_mov_b32 s85, m0
	s_mov_b32 m0, s16
	s_nop 0
	global_load_lds_dwordx4 v[64:65], off
	s_mov_b32 m0, s85
	v_lshl_add_u64 v[64:65], v[172:173], 0, s[58:59]
	s_addk_i32 s16, 0x2000
	s_mov_b32 s85, m0
	s_mov_b32 m0, s16
	s_nop 0
	global_load_lds_dwordx4 v[64:65], off
	s_mov_b32 m0, s85
	v_add_f32_e32 v174, v198, v68
	v_mfma_f32_32x32x16_bf16 v[48:63], v[156:159], v[178:181], v[48:63]
	ds_read_b64_tr_b16 v[76:77], v168 offset:49152
	ds_read_b64_tr_b16 v[78:79], v168 offset:49664
	v_exp_f32_e32 v96, v96
	v_exp_f32_e32 v97, v97
	v_mfma_f32_32x32x16_bf16 v[32:47], v[156:159], v[128:131], v[32:47]
	ds_read_b64_tr_b16 v[112:113], v168 offset:53248
	ds_read_b64_tr_b16 v[114:115], v168 offset:53760
	v_exp_f32_e32 v98, v98
	v_exp_f32_e32 v99, v99
	ds_read_b128 v[68:71], v189
	ds_read_b128 v[64:67], v189 offset:512
	v_mfma_f32_32x32x16_bf16 v[48:63], v[152:155], v[132:135], v[48:63]
	ds_read_b64_tr_b16 v[120:121], v168 offset:50176
	ds_read_b64_tr_b16 v[122:123], v168 offset:50688
	v_exp_f32_e32 v100, v100
	v_exp_f32_e32 v101, v101
	ds_read_b128 v[164:167], v189 offset:2048
	ds_read_b128 v[140:143], v189 offset:2560
	v_mfma_f32_32x32x16_bf16 v[32:47], v[152:155], v[136:139], v[32:47]
	ds_read_b64_tr_b16 v[178:179], v168 offset:54272
	ds_read_b64_tr_b16 v[180:181], v168 offset:54784
	v_exp_f32_e32 v102, v102
	v_exp_f32_e32 v103, v103
	ds_read_b128 v[160:163], v189 offset:4096
	ds_read_b128 v[132:135], v189 offset:4608
	v_mfma_f32_32x32x16_bf16 v[48:63], v[148:151], v[124:127], v[48:63]
	ds_read_b64_tr_b16 v[194:195], v168 offset:51200
	ds_read_b64_tr_b16 v[196:197], v168 offset:51712
	v_exp_f32_e32 v104, v104
	v_exp_f32_e32 v105, v105
	ds_read_b128 v[136:139], v189 offset:6144
	ds_read_b128 v[128:131], v189 offset:6656
	v_mfma_f32_32x32x16_bf16 v[32:47], v[148:151], v[190:193], v[32:47]
	ds_read_b64_tr_b16 v[124:125], v168 offset:55296
	ds_read_b64_tr_b16 v[126:127], v168 offset:55808
	v_exp_f32_e32 v106, v106
	v_exp_f32_e32 v107, v107
	v_mfma_f32_32x32x16_bf16 v[48:63], v[144:147], v[116:119], v[48:63]
	ds_read_b64_tr_b16 v[190:191], v168 offset:52224
	ds_read_b64_tr_b16 v[192:193], v168 offset:52736
	v_exp_f32_e32 v108, v108
	v_exp_f32_e32 v109, v109
	v_mfma_f32_32x32x16_bf16 v[32:47], v[144:147], v[72:75], v[32:47]
	ds_read_b64_tr_b16 v[116:117], v168 offset:56320
	ds_read_b64_tr_b16 v[118:119], v168 offset:56832
	v_exp_f32_e32 v110, v110
	v_exp_f32_e32 v111, v111
	s_waitcnt lgkmcnt(14)
	v_mfma_f32_32x32x16_bf16 v[16:31], v[156:159], v[76:79], v[16:31]
	v_exp_f32_e32 v80, v80
	v_exp_f32_e32 v81, v81
	v_mfma_f32_32x32x16_bf16 v[0:15], v[156:159], v[112:115], v[0:15]
	v_exp_f32_e32 v82, v82
	v_exp_f32_e32 v83, v83
	v_mfma_f32_32x32x16_bf16 v[16:31], v[152:155], v[120:123], v[16:31]
	v_exp_f32_e32 v84, v84
	v_exp_f32_e32 v85, v85
	s_waitcnt lgkmcnt(12)
	v_mfma_f32_32x32x16_bf16 v[0:15], v[152:155], v[178:181], v[0:15]
	v_exp_f32_e32 v86, v86
	v_exp_f32_e32 v87, v87
	s_waitcnt lgkmcnt(8)
	v_mfma_f32_32x32x16_bf16 v[16:31], v[148:151], v[194:197], v[16:31]
	v_exp_f32_e32 v88, v88
	v_exp_f32_e32 v89, v89
	s_waitcnt lgkmcnt(4)
	v_mfma_f32_32x32x16_bf16 v[0:15], v[148:151], v[124:127], v[0:15]
	v_exp_f32_e32 v90, v90
	v_exp_f32_e32 v91, v91
	s_waitcnt lgkmcnt(2)
	v_mfma_f32_32x32x16_bf16 v[16:31], v[144:147], v[190:193], v[16:31]
	v_exp_f32_e32 v92, v92
	v_exp_f32_e32 v93, v93
	s_waitcnt lgkmcnt(0)
	v_mfma_f32_32x32x16_bf16 v[0:15], v[144:147], v[116:119], v[0:15]
	v_exp_f32_e32 v94, v94
	v_exp_f32_e32 v95, v95
	s_waitcnt vmcnt(2) lgkmcnt(0)
	s_barrier
	ds_read_b64_tr_b16 v[178:179], v168 offset:57344
	ds_read_b64_tr_b16 v[180:181], v168 offset:57856
	v_add_f32_e32 v76, v96, v97
	ds_read_b128 v[72:75], v188
	v_add_f32_e32 v76, v98, v76
	v_add_f32_e32 v76, v99, v76
	v_add_f32_e32 v76, v100, v76
	v_add_f32_e32 v76, v101, v76
	v_cvt_pk_bf16_f32 v156, v96, v97
	v_cvt_pk_bf16_f32 v157, v98, v99
	s_waitcnt lgkmcnt(0)
	v_mfma_f32_32x32x16_bf16 v[112:127], v[68:71], v[72:75], 0
	ds_read_b64_tr_b16 v[96:97], v168 offset:61440
	ds_read_b64_tr_b16 v[98:99], v168 offset:61952
	ds_read_b128 v[68:71], v188
	v_add_f32_e32 v72, v102, v76
	v_add_f32_e32 v72, v103, v72
	v_add_f32_e32 v72, v104, v72
	v_add_f32_e32 v144, v105, v72
	s_waitcnt lgkmcnt(0)
	v_mfma_f32_32x32x16_bf16 v[64:79], v[64:67], v[68:71], 0
	v_cvt_pk_bf16_f32 v158, v100, v101
	v_cvt_pk_bf16_f32 v159, v102, v103
	ds_read_b64_tr_b16 v[100:101], v168 offset:58368
	ds_read_b64_tr_b16 v[102:103], v168 offset:58880
	ds_read_b128 v[190:193], v188 offset:1024
	v_add_f32_e32 v144, v106, v144
	v_add_f32_e32 v144, v107, v144
	v_add_f32_e32 v144, v108, v144
	v_add_f32_e32 v144, v109, v144
	v_cvt_pk_bf16_f32 v152, v104, v105
	v_cvt_pk_bf16_f32 v153, v106, v107
	s_waitcnt lgkmcnt(0)
	v_mfma_f32_32x32x16_bf16 v[112:127], v[164:167], v[190:193], v[112:127]
	ds_read_b64_tr_b16 v[104:105], v168 offset:62464
	ds_read_b64_tr_b16 v[106:107], v168 offset:62976
	ds_read_b128 v[164:167], v188 offset:1024
	v_add_f32_e32 v144, v110, v144
	v_add_f32_e32 v144, v111, v144
	v_add_f32_e32 v144, v80, v144
	v_add_f32_e32 v144, v81, v144
	s_waitcnt lgkmcnt(0)
	v_mfma_f32_32x32x16_bf16 v[64:79], v[140:143], v[164:167], v[64:79]
	v_cvt_pk_bf16_f32 v154, v108, v109
	v_cvt_pk_bf16_f32 v155, v110, v111
	ds_read_b64_tr_b16 v[108:109], v168 offset:59392
	ds_read_b64_tr_b16 v[110:111], v168 offset:59904
	ds_read_b128 v[140:143], v188 offset:2048
	v_add_f32_e32 v144, v82, v144
	v_add_f32_e32 v144, v83, v144
	v_add_f32_e32 v144, v84, v144
	v_add_f32_e32 v144, v85, v144
	v_cvt_pk_bf16_f32 v148, v80, v81
	v_cvt_pk_bf16_f32 v149, v82, v83
	s_waitcnt lgkmcnt(0)
	v_mfma_f32_32x32x16_bf16 v[112:127], v[160:163], v[140:143], v[112:127]
	ds_read_b64_tr_b16 v[190:191], v168 offset:63488
	ds_read_b64_tr_b16 v[192:193], v168 offset:64000
	ds_read_b128 v[80:83], v188 offset:2048
	v_add_f32_e32 v140, v86, v144
	v_add_f32_e32 v140, v87, v140
	v_add_f32_e32 v140, v88, v140
	v_add_f32_e32 v140, v89, v140
	s_waitcnt lgkmcnt(0)
	v_mfma_f32_32x32x16_bf16 v[64:79], v[132:135], v[80:83], v[64:79]
	v_cvt_pk_bf16_f32 v150, v84, v85
	v_cvt_pk_bf16_f32 v151, v86, v87
	ds_read_b64_tr_b16 v[84:85], v168 offset:60416
	ds_read_b64_tr_b16 v[86:87], v168 offset:60928
	ds_read_b128 v[80:83], v188 offset:3072
	v_add_f32_e32 v132, v90, v140
	v_add_f32_e32 v132, v91, v132
	v_add_f32_e32 v132, v92, v132
	v_add_f32_e32 v132, v93, v132
	v_cvt_pk_bf16_f32 v144, v88, v89
	v_cvt_pk_bf16_f32 v145, v90, v91
	s_waitcnt lgkmcnt(0)
	v_mfma_f32_32x32x16_bf16 v[112:127], v[136:139], v[80:83], v[112:127]
	ds_read_b64_tr_b16 v[88:89], v168 offset:64512
	ds_read_b64_tr_b16 v[90:91], v168 offset:65024
	ds_read_b128 v[80:83], v188 offset:3072
	v_add_f32_e32 v132, v94, v132
	v_add_f32_e32 v132, v95, v132
	v_add_f32_e32 v132, 0, v132
	v_cvt_pk_bf16_f32 v146, v92, v93
	s_waitcnt lgkmcnt(0)
	v_mfma_f32_32x32x16_bf16 v[64:79], v[128:131], v[80:83], v[64:79]
	v_cvt_pk_bf16_f32 v147, v94, v95
	v_lshl_add_u64 v[80:81], v[170:171], 0, s[62:63]
	s_mov_b32 s16, m0
	s_mov_b32 m0, s17
	s_nop 0
	global_load_lds_dwordx4 v[80:81], off
	s_mov_b32 m0, s16
	v_lshl_add_u64 v[80:81], v[172:173], 0, s[62:63]
	s_mov_b32 s16, m0
	s_mov_b32 m0, s35
	s_nop 0
	global_load_lds_dwordx4 v[80:81], off
	s_mov_b32 m0, s16
	v_add_f32_e32 v174, v174, v132
	v_mfma_f32_32x32x16_bf16 v[48:63], v[156:159], v[178:181], v[48:63]
	ds_read_b64_tr_b16 v[92:93], v177 offset:40960
	ds_read_b64_tr_b16 v[94:95], v177 offset:41472
	v_exp_f32_e32 v112, v112
	v_exp_f32_e32 v113, v113
	v_mfma_f32_32x32x16_bf16 v[32:47], v[156:159], v[96:99], v[32:47]
	ds_read_b64_tr_b16 v[170:171], v177 offset:45056
	ds_read_b64_tr_b16 v[172:173], v177 offset:45568
	v_exp_f32_e32 v114, v114
	v_exp_f32_e32 v115, v115
	ds_read_b128 v[80:83], v189 offset:8192
	ds_read_b128 v[96:99], v189 offset:8704
	v_mfma_f32_32x32x16_bf16 v[48:63], v[152:155], v[100:103], v[48:63]
	ds_read_b64_tr_b16 v[178:179], v177 offset:41984
	ds_read_b64_tr_b16 v[180:181], v177 offset:42496
	v_exp_f32_e32 v116, v116
	v_exp_f32_e32 v117, v117
	ds_read_b128 v[164:167], v189 offset:10240
	ds_read_b128 v[140:143], v189 offset:10752
	v_mfma_f32_32x32x16_bf16 v[32:47], v[152:155], v[104:107], v[32:47]
	ds_read_b64_tr_b16 v[100:101], v177 offset:46080
	ds_read_b64_tr_b16 v[102:103], v177 offset:46592
	v_exp_f32_e32 v118, v118
	v_exp_f32_e32 v119, v119
	ds_read_b128 v[160:163], v189 offset:12288
	ds_read_b128 v[132:135], v189 offset:12800
	v_mfma_f32_32x32x16_bf16 v[48:63], v[148:151], v[108:111], v[48:63]
	ds_read_b64_tr_b16 v[104:105], v177 offset:43008
	ds_read_b64_tr_b16 v[106:107], v177 offset:43520
	v_exp_f32_e32 v120, v120
	v_exp_f32_e32 v121, v121
	ds_read_b128 v[136:139], v189 offset:14336
	ds_read_b128 v[128:131], v189 offset:14848
	v_mfma_f32_32x32x16_bf16 v[32:47], v[148:151], v[190:193], v[32:47]
	ds_read_b64_tr_b16 v[108:109], v177 offset:47104
	ds_read_b64_tr_b16 v[110:111], v177 offset:47616
	v_exp_f32_e32 v122, v122
	v_exp_f32_e32 v123, v123
	v_mfma_f32_32x32x16_bf16 v[48:63], v[144:147], v[84:87], v[48:63]
	ds_read_b64_tr_b16 v[190:191], v177 offset:44032
	ds_read_b64_tr_b16 v[192:193], v177 offset:44544
	v_exp_f32_e32 v124, v124
	v_exp_f32_e32 v125, v125
	v_mfma_f32_32x32x16_bf16 v[32:47], v[144:147], v[88:91], v[32:47]
	ds_read_b64_tr_b16 v[84:85], v177 offset:48128
	ds_read_b64_tr_b16 v[86:87], v177 offset:48640
	v_exp_f32_e32 v126, v126
	v_exp_f32_e32 v127, v127
	s_waitcnt lgkmcnt(14)
	v_mfma_f32_32x32x16_bf16 v[16:31], v[156:159], v[92:95], v[16:31]
	v_exp_f32_e32 v64, v64
	v_exp_f32_e32 v65, v65
	v_mfma_f32_32x32x16_bf16 v[0:15], v[156:159], v[170:173], v[0:15]
	v_exp_f32_e32 v66, v66
	v_exp_f32_e32 v67, v67
	v_mfma_f32_32x32x16_bf16 v[16:31], v[152:155], v[178:181], v[16:31]
	v_exp_f32_e32 v68, v68
	v_exp_f32_e32 v69, v69
	s_waitcnt lgkmcnt(12)
	v_mfma_f32_32x32x16_bf16 v[0:15], v[152:155], v[100:103], v[0:15]
	v_exp_f32_e32 v70, v70
	v_exp_f32_e32 v71, v71
	s_waitcnt lgkmcnt(8)
	v_mfma_f32_32x32x16_bf16 v[16:31], v[148:151], v[104:107], v[16:31]
	v_exp_f32_e32 v72, v72
	v_exp_f32_e32 v73, v73
	s_waitcnt lgkmcnt(4)
	v_mfma_f32_32x32x16_bf16 v[0:15], v[148:151], v[108:111], v[0:15]
	v_exp_f32_e32 v74, v74
	v_exp_f32_e32 v75, v75
	s_waitcnt lgkmcnt(2)
	v_mfma_f32_32x32x16_bf16 v[16:31], v[144:147], v[190:193], v[16:31]
	v_exp_f32_e32 v76, v76
	v_exp_f32_e32 v77, v77
	s_waitcnt lgkmcnt(0)
	v_mfma_f32_32x32x16_bf16 v[0:15], v[144:147], v[84:87], v[0:15]
	v_exp_f32_e32 v78, v78
	v_exp_f32_e32 v79, v79
	s_waitcnt vmcnt(0) lgkmcnt(0)
	s_barrier
	ds_read_b64_tr_b16 v[170:171], v168 offset:24576
	ds_read_b64_tr_b16 v[172:173], v168 offset:25088
	v_add_f32_e32 v88, v112, v113
	ds_read_b128 v[84:87], v188
	v_add_f32_e32 v88, v114, v88
	v_add_f32_e32 v88, v115, v88
	v_add_f32_e32 v88, v116, v88
	v_add_f32_e32 v104, v117, v88
	v_cvt_pk_bf16_f32 v156, v112, v113
	v_cvt_pk_bf16_f32 v157, v114, v115
	s_waitcnt lgkmcnt(0)
	v_mfma_f32_32x32x16_bf16 v[80:95], v[80:83], v[84:87], 0
	ds_read_b64_tr_b16 v[112:113], v168 offset:28672
	ds_read_b64_tr_b16 v[114:115], v168 offset:29184
	ds_read_b128 v[100:103], v188
	v_add_f32_e32 v104, v118, v104
	v_add_f32_e32 v104, v119, v104
	v_add_f32_e32 v104, v120, v104
	v_add_f32_e32 v144, v121, v104
	v_cvt_pk_bf16_f32 v158, v116, v117
	v_cvt_pk_bf16_f32 v159, v118, v119
	s_waitcnt lgkmcnt(0)
	v_mfma_f32_32x32x16_bf16 v[96:111], v[96:99], v[100:103], 0
	ds_read_b64_tr_b16 v[116:117], v168 offset:25600
	ds_read_b64_tr_b16 v[118:119], v168 offset:26112
	ds_read_b128 v[178:181], v188 offset:1024
	v_add_f32_e32 v144, v122, v144
	v_add_f32_e32 v144, v123, v144
	v_add_f32_e32 v144, v124, v144
	v_add_f32_e32 v144, v125, v144
	v_cvt_pk_bf16_f32 v152, v120, v121
	v_cvt_pk_bf16_f32 v153, v122, v123
	s_waitcnt lgkmcnt(0)
	v_mfma_f32_32x32x16_bf16 v[80:95], v[164:167], v[178:181], v[80:95]
	ds_read_b64_tr_b16 v[120:121], v168 offset:29696
	ds_read_b64_tr_b16 v[122:123], v168 offset:30208
	ds_read_b128 v[164:167], v188 offset:1024
	v_add_f32_e32 v144, v126, v144
	v_add_f32_e32 v144, v127, v144
	v_add_f32_e32 v144, v64, v144
	v_add_f32_e32 v144, v65, v144
	v_cvt_pk_bf16_f32 v154, v124, v125
	v_cvt_pk_bf16_f32 v155, v126, v127
	s_waitcnt lgkmcnt(0)
	v_mfma_f32_32x32x16_bf16 v[96:111], v[140:143], v[164:167], v[96:111]
	ds_read_b64_tr_b16 v[124:125], v168 offset:26624
	ds_read_b64_tr_b16 v[126:127], v168 offset:27136
	ds_read_b128 v[140:143], v188 offset:2048
	v_add_f32_e32 v144, v66, v144
	v_add_f32_e32 v144, v67, v144
	v_add_f32_e32 v144, v68, v144
	v_add_f32_e32 v144, v69, v144
	v_cvt_pk_bf16_f32 v148, v64, v65
	v_cvt_pk_bf16_f32 v149, v66, v67
	s_waitcnt lgkmcnt(0)
	v_mfma_f32_32x32x16_bf16 v[80:95], v[160:163], v[140:143], v[80:95]
	ds_read_b64_tr_b16 v[64:65], v168 offset:30720
	ds_read_b64_tr_b16 v[66:67], v168 offset:31232
	ds_read_b128 v[140:143], v188 offset:2048
	v_add_f32_e32 v144, v70, v144
	v_add_f32_e32 v144, v71, v144
	v_add_f32_e32 v144, v72, v144
	v_add_f32_e32 v144, v73, v144
	v_cvt_pk_bf16_f32 v150, v68, v69
	v_cvt_pk_bf16_f32 v151, v70, v71
	s_waitcnt lgkmcnt(0)
	v_mfma_f32_32x32x16_bf16 v[96:111], v[132:135], v[140:143], v[96:111]
	ds_read_b64_tr_b16 v[68:69], v168 offset:27648
	ds_read_b64_tr_b16 v[70:71], v168 offset:28160
	ds_read_b128 v[132:135], v188 offset:3072
	v_add_f32_e32 v140, v74, v144
	v_add_f32_e32 v140, v75, v140
	v_add_f32_e32 v140, v76, v140
	v_add_f32_e32 v140, v77, v140
	v_cvt_pk_bf16_f32 v144, v72, v73
	v_cvt_pk_bf16_f32 v145, v74, v75
	s_waitcnt lgkmcnt(0)
	v_mfma_f32_32x32x16_bf16 v[80:95], v[136:139], v[132:135], v[80:95]
	ds_read_b64_tr_b16 v[72:73], v168 offset:31744
	ds_read_b64_tr_b16 v[74:75], v168 offset:32256
	ds_read_b128 v[132:135], v188 offset:3072
	v_add_f32_e32 v136, v78, v140
	v_add_f32_e32 v136, v79, v136
	v_add_f32_e32 v136, 0, v136
	v_cvt_pk_bf16_f32 v146, v76, v77
	v_cvt_pk_bf16_f32 v147, v78, v79
	s_waitcnt lgkmcnt(0)
	v_mfma_f32_32x32x16_bf16 v[96:111], v[128:131], v[132:135], v[96:111]
	v_mfma_f32_32x32x16_bf16 v[48:63], v[156:159], v[170:173], v[48:63]
	ds_read_b64_tr_b16 v[76:77], v168 offset:32768
	ds_read_b64_tr_b16 v[78:79], v168 offset:33280
	v_exp_f32_e32 v80, v80
	v_exp_f32_e32 v81, v81
	v_mfma_f32_32x32x16_bf16 v[32:47], v[156:159], v[112:115], v[32:47]
	ds_read_b64_tr_b16 v[128:129], v168 offset:36864
	ds_read_b64_tr_b16 v[130:131], v168 offset:37376
	v_exp_f32_e32 v82, v82
	v_exp_f32_e32 v83, v83
	v_mfma_f32_32x32x16_bf16 v[48:63], v[152:155], v[116:119], v[48:63]
	ds_read_b64_tr_b16 v[112:113], v168 offset:33792
	ds_read_b64_tr_b16 v[114:115], v168 offset:34304
	v_exp_f32_e32 v84, v84
	v_exp_f32_e32 v85, v85
	v_mfma_f32_32x32x16_bf16 v[32:47], v[152:155], v[120:123], v[32:47]
	ds_read_b64_tr_b16 v[116:117], v168 offset:37888
	ds_read_b64_tr_b16 v[118:119], v168 offset:38400
	v_exp_f32_e32 v86, v86
	v_exp_f32_e32 v87, v87
	v_mfma_f32_32x32x16_bf16 v[48:63], v[148:151], v[124:127], v[48:63]
	ds_read_b64_tr_b16 v[120:121], v168 offset:34816
	ds_read_b64_tr_b16 v[122:123], v168 offset:35328
	v_exp_f32_e32 v88, v88
	v_exp_f32_e32 v89, v89
	v_mfma_f32_32x32x16_bf16 v[32:47], v[148:151], v[64:67], v[32:47]
	ds_read_b64_tr_b16 v[124:125], v168 offset:38912
	ds_read_b64_tr_b16 v[126:127], v168 offset:39424
	v_exp_f32_e32 v90, v90
	v_exp_f32_e32 v91, v91
	v_mfma_f32_32x32x16_bf16 v[48:63], v[144:147], v[68:71], v[48:63]
	ds_read_b64_tr_b16 v[64:65], v168 offset:35840
	ds_read_b64_tr_b16 v[66:67], v168 offset:36352
	v_exp_f32_e32 v92, v92
	v_exp_f32_e32 v93, v93
	v_mfma_f32_32x32x16_bf16 v[32:47], v[144:147], v[72:75], v[32:47]
	ds_read_b64_tr_b16 v[68:69], v168 offset:39936
	ds_read_b64_tr_b16 v[70:71], v168 offset:40448
	v_exp_f32_e32 v94, v94
	v_exp_f32_e32 v95, v95
	s_waitcnt lgkmcnt(14)
; #define SBAR() __builtin_amdgcn_sched_barrier(0)
;   #define RESC() do{ if(!NOMAX&&resc){ asm volatile("s_waitcnt lgkmcnt(0)":::"memory"); \
;       _Pragma("unroll") for(int d_=0;d_<2*VM;++d_) _Pragma("unroll") for(int r=0;r<16;++r)o[d_][r]*=wsf[crow(r,hi)]; } }while(0)
;   #define PKW(P,B) cvtpk_s(P[B],P[B+1])
; template<int THRL,int VM,bool NOMAX> __device__ __forceinline__ void attn_unit(const bf16*Qb,const bf16*__restrict__ Kh,const bf16*__restrict__ Vh,bf16*Ob,const int NT,const int sp,float*wscr,char*shm){
;     ...
;   STEP(pB0,pB1,pA0,pA1,NT-1,false,false,false); RESC();
;   { float sacc=pB0[0]+pB0[1]; _Pragma("unroll") for(int r=2;r<16;++r)sacc+=pB0[r]; _Pragma("unroll") for(int r=0;r<16;++r)sacc+=pB1[r]; l_reg+=sacc;
;     pw0=(u32x4){PKW(pB0,0),PKW(pB0,2),PKW(pB0,4),PKW(pB0,6)};pw1=(u32x4){PKW(pB0,8),PKW(pB0,10),PKW(pB0,12),PKW(pB0,14)};pw2=(u32x4){PKW(pB1,0),PKW(pB1,2),PKW(pB1,4),PKW(pB1,6)};pw3=(u32x4){PKW(pB1,8),PKW(pB1,10),PKW(pB1,12),PKW(pB1,14)};
;     SBAR(); pv(o,vb0+VM*sl_cur,PAF(0),PAF(1),PAF(2),PAF(3)); if constexpr(VM==2) pv(o+2,vb0+VM*sl_cur+8192,PAF(0),PAF(1),PAF(2),PAF(3)); }
;     ...
;   {auto rr=__builtin_amdgcn_permlane32_swap(__float_as_uint(l_reg),__float_as_uint(l_reg),false,false);l_reg=__uint_as_float(rr[0])+__uint_as_float(rr[1]);}
;   if(hi==0)wsf[32+r32]=l_reg;asm volatile("s_waitcnt lgkmcnt(0)":::"memory");
	v_mfma_f32_32x32x16_bf16 v[16:31], v[156:159], v[76:79], v[16:31]
	v_exp_f32_e32 v96, v96
	v_exp_f32_e32 v97, v97
	s_waitcnt lgkmcnt(12)
	v_mfma_f32_32x32x16_bf16 v[0:15], v[156:159], v[128:131], v[0:15]
	v_exp_f32_e32 v98, v98
	v_exp_f32_e32 v99, v99
	s_waitcnt lgkmcnt(10)
	v_mfma_f32_32x32x16_bf16 v[16:31], v[152:155], v[112:115], v[16:31]
	v_exp_f32_e32 v100, v100
	v_exp_f32_e32 v101, v101
	s_waitcnt lgkmcnt(8)
	v_mfma_f32_32x32x16_bf16 v[0:15], v[152:155], v[116:119], v[0:15]
	v_exp_f32_e32 v102, v102
	v_exp_f32_e32 v103, v103
	s_waitcnt lgkmcnt(6)
	v_mfma_f32_32x32x16_bf16 v[16:31], v[148:151], v[120:123], v[16:31]
	v_exp_f32_e32 v104, v104
	v_exp_f32_e32 v105, v105
	s_waitcnt lgkmcnt(4)
	v_mfma_f32_32x32x16_bf16 v[0:15], v[148:151], v[124:127], v[0:15]
	v_exp_f32_e32 v106, v106
	v_exp_f32_e32 v107, v107
	s_waitcnt lgkmcnt(2)
	v_mfma_f32_32x32x16_bf16 v[16:31], v[144:147], v[64:67], v[16:31]
	v_exp_f32_e32 v108, v108
	v_exp_f32_e32 v109, v109
	s_waitcnt lgkmcnt(0)
	v_mfma_f32_32x32x16_bf16 v[0:15], v[144:147], v[68:71], v[0:15]
	v_exp_f32_e32 v110, v110
	v_exp_f32_e32 v111, v111
	v_add_f32_e32 v64, v80, v81
	v_add_f32_e32 v64, v82, v64
	v_add_f32_e32 v64, v83, v64
	v_add_f32_e32 v64, v84, v64
	v_add_f32_e32 v64, v85, v64
	v_add_f32_e32 v64, v86, v64
	v_add_f32_e32 v64, v87, v64
	v_add_f32_e32 v64, v88, v64
	v_add_f32_e32 v64, v89, v64
	v_add_f32_e32 v64, v90, v64
	v_add_f32_e32 v64, v91, v64
	v_add_f32_e32 v64, v92, v64
	v_add_f32_e32 v64, v93, v64
	v_add_f32_e32 v64, v94, v64
	v_add_f32_e32 v64, v95, v64
	v_add_f32_e32 v64, v64, v96
	v_add_f32_e32 v64, v97, v64
	v_add_f32_e32 v64, v98, v64
	v_add_f32_e32 v64, v99, v64
	v_add_f32_e32 v64, v100, v64
	v_add_f32_e32 v64, v101, v64
	v_add_f32_e32 v64, v102, v64
	v_add_f32_e32 v64, v103, v64
	v_add_f32_e32 v64, v104, v64
	v_add_f32_e32 v64, v105, v64
	v_add_f32_e32 v64, v106, v64
	v_add_f32_e32 v64, v107, v64
	v_add_f32_e32 v64, v108, v64
	v_add_f32_e32 v64, v109, v64
	v_add_f32_e32 v64, v110, v64
	v_add_f32_e32 v64, v111, v64
	v_add_f32_e32 v65, v174, v136
	v_add_f32_e32 v64, v65, v64
	v_cvt_pk_bf16_f32 v66, v80, v81
	v_cvt_pk_bf16_f32 v67, v82, v83
	v_cvt_pk_bf16_f32 v68, v84, v85
	v_cvt_pk_bf16_f32 v69, v86, v87
	v_cvt_pk_bf16_f32 v70, v88, v89
	v_cvt_pk_bf16_f32 v71, v90, v91
	v_cvt_pk_bf16_f32 v72, v92, v93
	v_cvt_pk_bf16_f32 v73, v94, v95
	v_cvt_pk_bf16_f32 v74, v96, v97
	v_cvt_pk_bf16_f32 v75, v98, v99
	v_cvt_pk_bf16_f32 v76, v100, v101
	v_cvt_pk_bf16_f32 v77, v102, v103
	v_cvt_pk_bf16_f32 v78, v104, v105
	v_cvt_pk_bf16_f32 v79, v106, v107
	v_cvt_pk_bf16_f32 v80, v108, v109
	v_cvt_pk_bf16_f32 v81, v110, v111
	v_add_u32_e32 v65, 0x4000, v176
	ds_read_b64_tr_b16 v[82:83],v65 offset:0
	ds_read_b64_tr_b16 v[84:85],v65 offset:512
	ds_read_b64_tr_b16 v[86:87],v65 offset:1024
	ds_read_b64_tr_b16 v[88:89],v65 offset:1536
	ds_read_b64_tr_b16 v[90:91],v65 offset:2048
	ds_read_b64_tr_b16 v[92:93],v65 offset:2560
	ds_read_b64_tr_b16 v[94:95],v65 offset:3072
	ds_read_b64_tr_b16 v[96:97],v65 offset:3584
	s_waitcnt lgkmcnt(0)
	s_nop 0
	v_mfma_f32_32x32x16_bf16 v[48:63], v[66:69], v[82:85], v[48:63]
	ds_read_b64_tr_b16 v[82:83],v65 offset:4096
	ds_read_b64_tr_b16 v[84:85],v65 offset:4608
	v_mfma_f32_32x32x16_bf16 v[48:63], v[70:73], v[86:89], v[48:63]
	ds_read_b64_tr_b16 v[86:87],v65 offset:5120
	ds_read_b64_tr_b16 v[88:89],v65 offset:5632
	v_mfma_f32_32x32x16_bf16 v[48:63], v[74:77], v[90:93], v[48:63]
	ds_read_b64_tr_b16 v[90:91],v65 offset:6144
	ds_read_b64_tr_b16 v[92:93],v65 offset:6656
	ds_read_b64_tr_b16 v[98:99],v65 offset:7168
	ds_read_b64_tr_b16 v[100:101],v65 offset:7680
	s_waitcnt lgkmcnt(0)
	v_mfma_f32_32x32x16_bf16 v[48:63], v[78:81], v[94:97], v[48:63]
	v_mfma_f32_32x32x16_bf16 v[32:47], v[66:69], v[82:85], v[32:47]
	v_add_u32_e32 v65, 0x6000, v176
	ds_read_b64_tr_b16 v[82:83],v65 offset:0
	ds_read_b64_tr_b16 v[84:85],v65 offset:512
	v_mfma_f32_32x32x16_bf16 v[32:47], v[70:73], v[86:89], v[32:47]
	ds_read_b64_tr_b16 v[86:87],v65 offset:1024
	ds_read_b64_tr_b16 v[88:89],v65 offset:1536
	v_mfma_f32_32x32x16_bf16 v[32:47], v[74:77], v[90:93], v[32:47]
	ds_read_b64_tr_b16 v[90:91],v65 offset:2048
	ds_read_b64_tr_b16 v[92:93],v65 offset:2560
	ds_read_b64_tr_b16 v[94:95],v65 offset:3072
	ds_read_b64_tr_b16 v[96:97],v65 offset:3584
	s_waitcnt lgkmcnt(0)
	v_mfma_f32_32x32x16_bf16 v[32:47], v[78:81], v[98:101], v[32:47]
	v_mfma_f32_32x32x16_bf16 v[16:31], v[66:69], v[82:85], v[16:31]
	ds_read_b64_tr_b16 v[82:83],v65 offset:4096
	ds_read_b64_tr_b16 v[84:85],v65 offset:4608
	v_mfma_f32_32x32x16_bf16 v[16:31], v[70:73], v[86:89], v[16:31]
	ds_read_b64_tr_b16 v[86:87],v65 offset:5120
	ds_read_b64_tr_b16 v[88:89],v65 offset:5632
	v_mfma_f32_32x32x16_bf16 v[16:31], v[74:77], v[90:93], v[16:31]
	ds_read_b64_tr_b16 v[90:91],v65 offset:6144
	ds_read_b64_tr_b16 v[92:93],v65 offset:6656
	ds_read_b64_tr_b16 v[98:99],v65 offset:7168
	ds_read_b64_tr_b16 v[100:101],v65 offset:7680
	s_waitcnt lgkmcnt(0)
	v_mfma_f32_32x32x16_bf16 v[16:31], v[78:81], v[94:97], v[16:31]
	v_mfma_f32_32x32x16_bf16 v[0:15], v[66:69], v[82:85], v[0:15]
	v_mov_b32_e32 v65, v64
	s_nop 1
	v_permlane32_swap_b32_e32 v64, v65
	v_cmp_gt_u32_e32 vcc, 32, v187
	v_mfma_f32_32x32x16_bf16 v[0:15], v[70:73], v[86:89], v[0:15]
	v_mfma_f32_32x32x16_bf16 v[0:15], v[74:77], v[90:93], v[0:15]
	v_mfma_f32_32x32x16_bf16 v[0:15], v[78:81], v[98:101], v[0:15]
	s_and_saveexec_b64 s[16:17], vcc
	s_cbranch_execz .LBB0_859
	v_add_f32_e32 v64, v64, v65
	v_lshl_add_u32 v65, v186, 2, s34
	ds_write_b32 v65, v64 offset:128
	s_branch .LBB0_859

; #define WAIT_BAR(N) asm volatile("s_waitcnt vmcnt(" #N ") lgkmcnt(0)\n\ts_barrier":::"memory")
;   #define DMA_K(t,slot) glds16(ksrc+(long)(t)*KVBLK*KVP,(unsigned)__builtin_amdgcn_readfirstlane(kdst+(slot)))
;   #define DMA_V(t,slot) do{ glds16(vsrc+(long)(t)*KVBLK*KVP,(unsigned)__builtin_amdgcn_readfirstlane(vdst+VM*(slot))); if constexpr(VM==2) glds16(vsrc+64+(long)(t)*KVBLK*KVP,(unsigned)__builtin_amdgcn_readfirstlane(vdst+VM*(slot)+8192)); }while(0)
; template<int THRL,int VM,bool NOMAX> __device__ __forceinline__ void attn_unit(const bf16*Qb,const bf16*__restrict__ Kh,const bf16*__restrict__ Vh,bf16*Ob,const int NT,const int sp,float*wscr,char*shm){
;     ...
;   const bf16*ksrc=Kh+(long)lane*KVP+wid*8;
;   const bf16*vsrc=Vh+(long)(16*(wid&3)+(lane>>2))*KVP+(wid>>2)*32+(lane&3)*8;
;   const unsigned kdst=lds0+LDS_K+wid*1024, vdst=lds0+LDS_V+wid*1024;
;     ...
;   const int vb0=(int)(lds0+LDS_V)+((lane>>4)&1)*32+(lane&3)*8+(4*hi+((lane&15)>>2))*64;
;   const char*Kbase=shm+LDS_K; bf16x8 kf[8];
;   const lds_cptr shm3=(lds_cptr)shm; const lds_cptr kp0=shm3+LDS_K+hi*1024+r32*16; const lds_cptr vp0=shm3+LDS_V+((lane>>4)&1)*32+(lane&3)*8+(4*hi+((lane&15)>>2))*64;
;   if(wid>=4)__builtin_amdgcn_s_setprio(1);
;   DMA_K(0,0);DMA_V(0,0);DMA_K(1,SLOTB);
;   bf16x8 qr[4];
;   #pragma unroll
;   for(int d0=0;d0<4;++d0)qr[d0]=*reinterpret_cast<const bf16x8*>(&Qw[(long)r32*QOP+d0*16+hi*8]);
;   const lds_cptr qpk=shm3+LDS_OST_+wid*4096+lane*16;
;   if constexpr(VM==2){
;     #pragma unroll
;     for(int d0=0;d0<4;++d0)*(__attribute__((address_space(3))) bf16x8*)(const_cast<__attribute__((address_space(3))) char*>(qpk)+d0*1024)=qr[d0]; }
;   float mhat=0.f,l_reg=0.f;f32x16 o[2*VM];
;   #pragma unroll
;   for(int d_=0;d_<2*VM;++d_)o[d_]=f32x16{};
;  f32x16 negm=f32x16{}; if constexpr(VM==1){asm volatile("":"+v"(negm));}
;   bool resc=false;
;     ...
;   f32x16 pA0,pA1,pB0,pB1;
;   int sl_prev=0,sl_cur=0,sl_next=SLOTB;
;     ...
;   DMA_K(2,2*SLOTB);
;   WAIT_BAR(3);
;   qkt(pA0,pA1,Kbase,qr,negm,r32,hi);asm volatile("s_nop 15\n\ts_nop 7":"+v"(pA0),"+v"(pA1));
.LBB0_873:
	s_xor_b64 s[6:7], s[16:17], -1
	s_lshl_b32 s16, s8, 7
	s_add_u32 s35, s83, s16
	s_addc_u32 s88, s84, 0
	s_add_u32 s16, s0, s16
	s_addc_u32 s17, s1, 0
	s_lshl_b32 s86, s85, 5
	v_and_b32_e32 v187, 63, v32
	s_ashr_i32 s87, s86, 31
	s_lshl_b64 s[86:87], s[86:87], 11
	v_mul_u32_u24_e32 v0, 0x500, v187
	s_add_u32 s86, s35, s86
	v_lshlrev_b32_e32 v168, 1, v0
	s_addc_u32 s87, s88, s87
	v_lshl_add_u64 v[0:1], s[16:17], 0, v[168:169]
	s_lshl_b32 s16, s85, 3
	s_ashr_i32 s17, s16, 31
	v_lshl_add_u64 v[54:55], s[16:17], 1, v[0:1]
	s_mov_b64 s[16:17], 0x200
	v_lshl_add_u64 v[174:175], v[54:55], 0, s[16:17]
	s_lshl_b32 s16, s85, 4
	v_bfe_u32 v0, v32, 2, 4
	v_and_or_b32 v0, s16, 48, v0
	s_ashr_i32 s16, s34, 3
	v_mul_u32_u24_e32 v0, 0x500, v0
	s_andn2_b32 s16, s16, 31
	v_lshlrev_b32_e32 v168, 1, v0
	s_ashr_i32 s17, s16, 31
	v_lshlrev_b32_e32 v2, 3, v32
	s_lshl_b32 s35, s85, 10
	v_lshl_add_u64 v[0:1], s[0:1], 0, v[168:169]
	v_and_b32_e32 v190, 24, v2
	s_cmp_lg_u32 0, -1
	v_lshl_add_u64 v[0:1], s[16:17], 1, v[0:1]
	v_lshlrev_b32_e32 v168, 1, v190
	s_cselect_b32 s16, 0, 0
	v_lshl_add_u64 v[56:57], v[0:1], 0, v[168:169]
	s_add_i32 s17, s35, s16
	s_mov_b32 s88, m0
	s_mov_b32 m0, s17
	s_nop 0
	global_load_lds_dwordx4 v[174:175], off
	s_mov_b32 m0, s88
	v_lshl_add_u64 v[170:171], v[56:57], 0, s[12:13]
	s_add_i32 s16, s17, 0x6000
	s_mov_b32 s88, m0
	s_mov_b32 m0, s16
	s_nop 0
	global_load_lds_dwordx4 v[170:171], off
	s_mov_b32 m0, s88
	v_and_b32_e32 v186, 31, v32
	v_lshl_add_u64 v[172:173], v[56:57], 0, s[14:15]
	s_add_i32 s88, s17, 0x8000
	s_mov_b32 s89, m0
	s_mov_b32 m0, s88
	s_nop 0
	global_load_lds_dwordx4 v[172:173], off
	s_mov_b32 m0, s89
	v_lshl_add_u64 v[0:1], v[54:55], 0, s[36:37]
	v_bfe_u32 v185, v32, 5, 1
	s_add_i32 s88, s17, 0x2000
	s_mov_b32 s89, m0
	s_mov_b32 m0, s88
	s_nop 0
	global_load_lds_dwordx4 v[0:1], off
	s_mov_b32 m0, s89
	v_lshlrev_b32_e32 v0, 11, v186
	v_lshl_or_b32 v4, v185, 4, v0
	global_load_dwordx4 v[0:3], v4, s[86:87] offset:1024
	global_load_dwordx4 v[34:37], v4, s[86:87] offset:1056
	global_load_dwordx4 v[38:41], v4, s[86:87] offset:1088
	global_load_dwordx4 v[42:45], v4, s[86:87] offset:1120
	s_lshl_b32 s85, s85, 12
	s_add_i32 s85, s85, 0
	v_lshlrev_b32_e32 v6, 4, v187
	s_add_i32 s85, s85, 0x12800
	v_add_u32_e32 v168, s85, v6
	v_lshlrev_b32_e32 v4, 10, v185
	v_lshlrev_b32_e32 v5, 4, v186
	v_add3_u32 v189, 0, v4, v5
	v_lshl_add_u64 v[4:5], v[54:55], 0, s[40:41]
	s_add_i32 s86, s17, 0x4000
	v_lshlrev_b32_e32 v33, 1, v32
	v_lshlrev_b32_e32 v32, 4, v32
	v_and_b32_e32 v191, 32, v33
	v_and_b32_e32 v32, 0xc0, v32
	v_lshl_or_b32 v192, v185, 8, v32
	v_add_u32_e32 v32, 0, v191
	v_add3_u32 v188, v32, v190, v192
	v_lshl_add_u64 v[32:33], v[54:55], 0, s[42:43]
	s_add_i32 s88, s17, 0xa000
	s_add_i32 s90, s17, 0xc000
	v_mov_b32_e32 v193, 0
	s_mov_b32 s89, 0
	s_movk_i32 s87, 0x2000
	v_lshl_add_u64 v[176:177], v[56:57], 0, s[50:51]
	v_lshl_add_u64 v[178:179], v[56:57], 0, s[52:53]
	v_lshl_add_u64 v[180:181], v[54:55], 0, s[54:55]
	v_mov_b32_e32 v54, v193
	v_mov_b32_e32 v55, v193
	v_mov_b32_e32 v58, v193
	v_mov_b32_e32 v59, v193
	v_mov_b32_e32 v60, v193
	v_mov_b32_e32 v61, v193
	v_mov_b32_e32 v62, v193
	v_mov_b32_e32 v63, v193
	s_waitcnt vmcnt(3)
	ds_write_b128 v168, v[0:3]
	s_waitcnt vmcnt(2)
	ds_write_b128 v168, v[34:37] offset:1024
	s_waitcnt vmcnt(1)
	ds_write_b128 v168, v[38:41] offset:2048
	s_waitcnt vmcnt(0)
	ds_write_b128 v168, v[42:45] offset:3072
	s_mov_b32 s85, m0
	s_mov_b32 m0, s86
	s_nop 0
	global_load_lds_dwordx4 v[4:5], off
	s_mov_b32 m0, s85
	s_waitcnt vmcnt(3) lgkmcnt(0)
	s_barrier
	ds_read_b128 v[4:7], v189
	ds_read_b128 v[8:11], v189 offset:512
	s_waitcnt lgkmcnt(1)
	v_mfma_f32_32x32x16_bf16 v[16:31], v[4:7], v[0:3], 0
	ds_read_b128 v[46:49], v189 offset:2048
	ds_read_b128 v[50:53], v189 offset:2560
	s_mov_b32 s85, -1
	s_movk_i32 s86, 0x4000
	s_waitcnt lgkmcnt(2)
	v_mfma_f32_32x32x16_bf16 v[0:15], v[8:11], v[0:3], 0
	s_waitcnt lgkmcnt(1)
	v_mfma_f32_32x32x16_bf16 v[16:31], v[46:49], v[34:37], v[16:31]
	s_waitcnt lgkmcnt(0)
	v_mfma_f32_32x32x16_bf16 v[0:15], v[50:53], v[34:37], v[0:15]
	ds_read_b128 v[34:37], v189 offset:4096
	ds_read_b128 v[46:49], v189 offset:4608
	s_waitcnt lgkmcnt(1)
	v_mfma_f32_32x32x16_bf16 v[16:31], v[34:37], v[38:41], v[16:31]
	ds_read_b128 v[34:37], v189 offset:6656
	ds_read_b128 v[50:53], v189 offset:6144
	s_waitcnt lgkmcnt(2)
	v_mfma_f32_32x32x16_bf16 v[0:15], v[46:49], v[38:41], v[0:15]
	v_lshl_add_u64 v[38:39], v[56:57], 0, s[44:45]
	v_lshl_add_u64 v[40:41], v[56:57], 0, s[48:49]
	v_mov_b32_e32 v48, 0
	v_mov_b32_e32 v49, v193
	v_mov_b32_e32 v56, v193
	v_mov_b32_e32 v57, v193
	v_mov_b32_e32 v46, v193
	s_waitcnt lgkmcnt(0)
	v_mfma_f32_32x32x16_bf16 v[16:31], v[50:53], v[42:45], v[16:31]
	v_mov_b32_e32 v50, v193
	v_mov_b32_e32 v51, v193
	v_mov_b32_e32 v52, v193
	v_mov_b32_e32 v53, v193
	v_mov_b32_e32 v47, v193
	v_mfma_f32_32x32x16_bf16 v[0:15], v[34:37], v[42:45], v[0:15]
	s_nop 15
	s_nop 7
	s_waitcnt vmcnt(0) lgkmcnt(0)
	s_barrier
; #define WAIT_BAR(N) asm volatile("s_waitcnt vmcnt(" #N ") lgkmcnt(0)\n\ts_barrier":::"memory")
;   #define DMA_K(t,slot) glds16(ksrc+(long)(t)*KVBLK*KVP,(unsigned)__builtin_amdgcn_readfirstlane(kdst+(slot)))
;   #define DMA_V(t,slot) do{ glds16(vsrc+(long)(t)*KVBLK*KVP,(unsigned)__builtin_amdgcn_readfirstlane(vdst+VM*(slot))); if constexpr(VM==2) glds16(vsrc+64+(long)(t)*KVBLK*KVP,(unsigned)__builtin_amdgcn_readfirstlane(vdst+VM*(slot)+8192)); }while(0)
;   #define ROT() do{sl_prev=sl_cur;sl_cur=sl_next;sl_next=(sl_next==(NSLOT-1)*SLOTB)?0:sl_next+SLOTB;}while(0)
; template<int THRL,int VM,bool NOMAX> __device__ __forceinline__ void attn_unit(const bf16*Qb,const bf16*__restrict__ Kh,const bf16*__restrict__ Vh,bf16*Ob,const int NT,const int sp,float*wscr,char*shm){
;     ...
;   START(pA0,pA1);
;   _Pragma("unroll") for(int r=0;r<16;++r)pA1[r]=__builtin_amdgcn_exp2f(pA1[r]);
;   WAIT_BAR(0);
;   DMA_K(3,0);DMA_V(1,SLOTB);
;   ROT();
;   kload8(kf,kp0+sl_cur);
;   if constexpr(VM==2){WAIT_BAR(3);}else{WAIT_BAR(2);}
;   s16x4 vlo[8],vhi[8]; u32x4 pw0,pw1,pw2,pw3;
	s_mov_b32 s91, m0
	s_mov_b32 m0, s17
	s_nop 0
	global_load_lds_dwordx4 v[32:33], off
	s_mov_b32 m0, s91
	v_mov_b32_e32 v32, 0
	s_mov_b32 s91, m0
	s_mov_b32 m0, s88
	s_nop 0
	global_load_lds_dwordx4 v[38:39], off
	s_mov_b32 m0, s91
	s_mov_b32 s88, m0
	s_mov_b32 m0, s90
	s_nop 0
	global_load_lds_dwordx4 v[40:41], off
	s_mov_b32 m0, s88
	ds_read_b128 v[100:103], v189 offset:8192
	ds_read_b128 v[96:99], v189 offset:8704
	ds_read_b128 v[164:167], v189 offset:10240
	ds_read_b128 v[160:163], v189 offset:10752
	ds_read_b128 v[140:143], v189 offset:12288
	ds_read_b128 v[136:139], v189 offset:12800
	ds_read_b128 v[132:135], v189 offset:14336
	ds_read_b128 v[128:131], v189 offset:14848
	v_exp_f32_e32 v80, v16
	v_exp_f32_e32 v81, v17
	v_exp_f32_e32 v82, v18
	v_exp_f32_e32 v83, v19
	v_exp_f32_e32 v84, v20
	v_exp_f32_e32 v85, v21
	v_exp_f32_e32 v86, v22
	v_exp_f32_e32 v87, v23
	v_exp_f32_e32 v88, v24
	v_exp_f32_e32 v89, v25
	v_exp_f32_e32 v90, v26
	v_exp_f32_e32 v91, v27
	v_exp_f32_e32 v92, v28
	v_exp_f32_e32 v93, v29
	v_exp_f32_e32 v94, v30
	v_exp_f32_e32 v95, v31
	v_exp_f32_e32 v64, v0
	v_exp_f32_e32 v65, v1
	v_exp_f32_e32 v66, v2
	v_exp_f32_e32 v67, v3
	v_exp_f32_e32 v68, v4
	v_exp_f32_e32 v69, v5
	v_exp_f32_e32 v70, v6
	v_exp_f32_e32 v71, v7
	v_exp_f32_e32 v72, v8
	v_exp_f32_e32 v73, v9
	v_exp_f32_e32 v74, v10
	v_exp_f32_e32 v75, v11
	v_exp_f32_e32 v76, v12
	v_exp_f32_e32 v77, v13
	v_exp_f32_e32 v78, v14
	v_exp_f32_e32 v79, v15
	ds_read_b128 v[218:221], v168
	ds_read_b128 v[222:225], v168 offset:1024
	ds_read_b128 v[226:229], v168 offset:2048
	ds_read_b128 v[230:233], v168 offset:3072
	s_waitcnt vmcnt(3) lgkmcnt(0)
	s_barrier
	v_mov_b32_e32 v33, v193
	v_mov_b32_e32 v34, v193
	v_mov_b32_e32 v35, v193
	v_mov_b32_e32 v36, v193
	v_mov_b32_e32 v37, v193
	v_mov_b32_e32 v38, v193
	v_mov_b32_e32 v39, v193
	v_mov_b32_e32 v40, v193
	v_mov_b32_e32 v41, v193
	v_mov_b32_e32 v42, v193
	v_mov_b32_e32 v43, v193
	v_mov_b32_e32 v44, v193
	v_mov_b32_e32 v45, v193
	v_mov_b32_e32 v16, 0
	v_mov_b32_e32 v17, v193
	v_mov_b32_e32 v18, v193
	v_mov_b32_e32 v19, v193
	v_mov_b32_e32 v20, v193
	v_mov_b32_e32 v21, v193
	v_mov_b32_e32 v22, v193
	v_mov_b32_e32 v23, v193
	v_mov_b32_e32 v24, v193
	v_mov_b32_e32 v25, v193
	v_mov_b32_e32 v26, v193
	v_mov_b32_e32 v27, v193
	v_mov_b32_e32 v28, v193
	v_mov_b32_e32 v29, v193
	v_mov_b32_e32 v30, v193
	v_mov_b32_e32 v31, v193
	v_mov_b32_e32 v0, 0
	v_mov_b32_e32 v1, v193
	v_mov_b32_e32 v2, v193
	v_mov_b32_e32 v3, v193
	v_mov_b32_e32 v4, v193
	v_mov_b32_e32 v5, v193
	v_mov_b32_e32 v6, v193
	v_mov_b32_e32 v7, v193
	v_mov_b32_e32 v8, v193
	v_mov_b32_e32 v9, v193
	v_mov_b32_e32 v10, v193
	v_mov_b32_e32 v11, v193
	v_mov_b32_e32 v12, v193
	v_mov_b32_e32 v13, v193
	v_mov_b32_e32 v14, v193
	v_mov_b32_e32 v15, v193
.LBB0_874:
	v_lshl_add_u32 v206, s89, 1, v188
	ds_read_b64_tr_b16 v[194:195], v206 offset:24576
	ds_read_b64_tr_b16 v[196:197], v206 offset:25088
	v_add_f32_e32 v108, v80, v81
	v_add_f32_e32 v108, v82, v108
	v_add_f32_e32 v108, v83, v108
	v_add_f32_e32 v108, v84, v108
	v_add_f32_e32 v108, v85, v108
	v_cvt_pk_bf16_f32 v156, v80, v81
	v_cvt_pk_bf16_f32 v157, v82, v83
	v_mfma_f32_32x32x16_bf16 v[112:127], v[100:103], v[218:221], 0
	ds_read_b64_tr_b16 v[80:81], v206 offset:28672
	ds_read_b64_tr_b16 v[82:83], v206 offset:29184
	v_add_f32_e32 v104, v86, v108
	v_add_f32_e32 v104, v87, v104
	v_add_f32_e32 v104, v88, v104
	v_add_f32_e32 v144, v89, v104
	v_mfma_f32_32x32x16_bf16 v[96:111], v[96:99], v[218:221], 0
	v_cvt_pk_bf16_f32 v158, v84, v85
	v_cvt_pk_bf16_f32 v159, v86, v87
	ds_read_b64_tr_b16 v[84:85], v206 offset:25600
	ds_read_b64_tr_b16 v[86:87], v206 offset:26112
	v_add_f32_e32 v144, v90, v144
	v_add_f32_e32 v144, v91, v144
	v_add_f32_e32 v144, v92, v144
	v_add_f32_e32 v144, v93, v144
	v_cvt_pk_bf16_f32 v152, v88, v89
	v_cvt_pk_bf16_f32 v153, v90, v91
	v_mfma_f32_32x32x16_bf16 v[112:127], v[164:167], v[222:225], v[112:127]
	ds_read_b64_tr_b16 v[88:89], v206 offset:29696
	ds_read_b64_tr_b16 v[90:91], v206 offset:30208
	v_add_f32_e32 v144, v94, v144
	v_add_f32_e32 v144, v95, v144
	v_add_f32_e32 v144, v64, v144
	v_add_f32_e32 v144, v65, v144
	v_mfma_f32_32x32x16_bf16 v[96:111], v[160:163], v[222:225], v[96:111]
	v_cvt_pk_bf16_f32 v154, v92, v93
	v_cvt_pk_bf16_f32 v155, v94, v95
	ds_read_b64_tr_b16 v[92:93], v206 offset:26624
	ds_read_b64_tr_b16 v[94:95], v206 offset:27136
	v_add_f32_e32 v144, v66, v144
	v_add_f32_e32 v144, v67, v144
	v_add_f32_e32 v144, v68, v144
	v_add_f32_e32 v144, v69, v144
	v_cvt_pk_bf16_f32 v148, v64, v65
	v_cvt_pk_bf16_f32 v149, v66, v67
	v_mfma_f32_32x32x16_bf16 v[112:127], v[140:143], v[226:229], v[112:127]
	ds_read_b64_tr_b16 v[198:199], v206 offset:30720
	ds_read_b64_tr_b16 v[200:201], v206 offset:31232
	v_add_f32_e32 v140, v70, v144
	v_add_f32_e32 v140, v71, v140
	v_add_f32_e32 v140, v72, v140
	v_add_f32_e32 v140, v73, v140
	v_mfma_f32_32x32x16_bf16 v[96:111], v[136:139], v[226:229], v[96:111]
	v_cvt_pk_bf16_f32 v150, v68, v69
	v_cvt_pk_bf16_f32 v151, v70, v71
	ds_read_b64_tr_b16 v[202:203], v206 offset:27648
	ds_read_b64_tr_b16 v[204:205], v206 offset:28160
	v_add_f32_e32 v68, v74, v140
	v_add_f32_e32 v68, v75, v68
	v_add_f32_e32 v68, v76, v68
	v_add_f32_e32 v68, v77, v68
	v_cvt_pk_bf16_f32 v144, v72, v73
	v_cvt_pk_bf16_f32 v145, v74, v75
	v_mfma_f32_32x32x16_bf16 v[112:127], v[132:135], v[230:233], v[112:127]
	ds_read_b64_tr_b16 v[72:73], v206 offset:31744
	ds_read_b64_tr_b16 v[74:75], v206 offset:32256
	v_add_f32_e32 v68, v78, v68
	v_add_f32_e32 v68, v79, v68
	v_add_f32_e32 v68, 0, v68
	v_cvt_pk_bf16_f32 v146, v76, v77
	v_mfma_f32_32x32x16_bf16 v[96:111], v[128:131], v[230:233], v[96:111]
	v_cvt_pk_bf16_f32 v147, v78, v79
	s_add_i32 s88, s87, s17
	v_lshl_add_u64 v[64:65], v[180:181], 0, s[56:57]
	s_mov_b32 s89, m0
	s_mov_b32 m0, s88
	s_nop 0
	global_load_lds_dwordx4 v[64:65], off
	s_mov_b32 m0, s89
	s_lshl_b32 s88, s86, 1
	v_lshl_add_u64 v[64:65], v[178:179], 0, s[56:57]
	s_add_i32 s88, s88, s16
	s_mov_b32 s89, m0
	s_mov_b32 m0, s88
	s_nop 0
	global_load_lds_dwordx4 v[64:65], off
	s_mov_b32 m0, s89
	v_lshl_add_u64 v[64:65], v[176:177], 0, s[56:57]
	s_addk_i32 s88, 0x2000
	s_mov_b32 s89, m0
	s_mov_b32 m0, s88
	s_nop 0
	global_load_lds_dwordx4 v[64:65], off
	s_mov_b32 m0, s89
	v_add_f32_e32 v193, v193, v68
	s_waitcnt lgkmcnt(12)
	v_mfma_f32_32x32x16_bf16 v[48:63], v[156:159], v[194:197], v[48:63]
	ds_read_b64_tr_b16 v[76:77], v206 offset:32768
	ds_read_b64_tr_b16 v[78:79], v206 offset:33280
	v_exp_f32_e32 v112, v112
	v_exp_f32_e32 v113, v113
	v_mfma_f32_32x32x16_bf16 v[32:47], v[156:159], v[80:83], v[32:47]
	ds_read_b64_tr_b16 v[194:195], v206 offset:36864
	ds_read_b64_tr_b16 v[196:197], v206 offset:37376
	v_exp_f32_e32 v114, v114
	v_exp_f32_e32 v115, v115
	v_add_u32_e32 v128, s86, v189
	ds_read_b128 v[68:71], v128
	ds_read_b128 v[64:67], v128 offset:512
	s_waitcnt lgkmcnt(14)
	v_mfma_f32_32x32x16_bf16 v[48:63], v[152:155], v[84:87], v[48:63]
	ds_read_b64_tr_b16 v[80:81], v206 offset:33792
	ds_read_b64_tr_b16 v[82:83], v206 offset:34304
	v_exp_f32_e32 v116, v116
	v_exp_f32_e32 v117, v117
	ds_read_b128 v[164:167], v128 offset:2048
	ds_read_b128 v[140:143], v128 offset:2560
	v_mfma_f32_32x32x16_bf16 v[32:47], v[152:155], v[88:91], v[32:47]
	ds_read_b64_tr_b16 v[84:85], v206 offset:37888
	ds_read_b64_tr_b16 v[86:87], v206 offset:38400
	v_exp_f32_e32 v118, v118
	v_exp_f32_e32 v119, v119
	ds_read_b128 v[160:163], v128 offset:4096
	ds_read_b128 v[132:135], v128 offset:4608
	s_waitcnt lgkmcnt(14)
	v_mfma_f32_32x32x16_bf16 v[48:63], v[148:151], v[92:95], v[48:63]
	ds_read_b64_tr_b16 v[88:89], v206 offset:34816
	ds_read_b64_tr_b16 v[90:91], v206 offset:35328
	v_exp_f32_e32 v120, v120
	v_exp_f32_e32 v121, v121
	ds_read_b128 v[136:139], v128 offset:6144
	ds_read_b128 v[128:131], v128 offset:6656
	v_mfma_f32_32x32x16_bf16 v[32:47], v[148:151], v[198:201], v[32:47]
	ds_read_b64_tr_b16 v[92:93], v206 offset:38912
	ds_read_b64_tr_b16 v[94:95], v206 offset:39424
	v_exp_f32_e32 v122, v122
	v_exp_f32_e32 v123, v123
	s_waitcnt lgkmcnt(14)
	v_mfma_f32_32x32x16_bf16 v[48:63], v[144:147], v[202:205], v[48:63]
	ds_read_b64_tr_b16 v[198:199], v206 offset:35840
	ds_read_b64_tr_b16 v[200:201], v206 offset:36352
	v_exp_f32_e32 v124, v124
	v_exp_f32_e32 v125, v125
	v_mfma_f32_32x32x16_bf16 v[32:47], v[144:147], v[72:75], v[32:47]
	ds_read_b64_tr_b16 v[202:203], v206 offset:39936
	ds_read_b64_tr_b16 v[204:205], v206 offset:40448
	v_exp_f32_e32 v126, v126
	v_exp_f32_e32 v127, v127
	s_waitcnt lgkmcnt(14)
	v_mfma_f32_32x32x16_bf16 v[16:31], v[156:159], v[76:79], v[16:31]
	v_exp_f32_e32 v96, v96
	v_exp_f32_e32 v97, v97
	v_mfma_f32_32x32x16_bf16 v[0:15], v[156:159], v[194:197], v[0:15]
	v_exp_f32_e32 v98, v98
	v_exp_f32_e32 v99, v99
	v_mfma_f32_32x32x16_bf16 v[16:31], v[152:155], v[80:83], v[16:31]
	v_exp_f32_e32 v100, v100
	v_exp_f32_e32 v101, v101
	s_waitcnt lgkmcnt(12)
	v_mfma_f32_32x32x16_bf16 v[0:15], v[152:155], v[84:87], v[0:15]
	v_exp_f32_e32 v102, v102
	v_exp_f32_e32 v103, v103
	s_waitcnt lgkmcnt(8)
	v_mfma_f32_32x32x16_bf16 v[16:31], v[148:151], v[88:91], v[16:31]
	v_exp_f32_e32 v104, v104
	v_exp_f32_e32 v105, v105
	s_waitcnt lgkmcnt(4)
	v_mfma_f32_32x32x16_bf16 v[0:15], v[148:151], v[92:95], v[0:15]
	v_exp_f32_e32 v106, v106
	v_exp_f32_e32 v107, v107
	s_waitcnt lgkmcnt(2)
	v_mfma_f32_32x32x16_bf16 v[16:31], v[144:147], v[198:201], v[16:31]
	v_exp_f32_e32 v108, v108
	v_exp_f32_e32 v109, v109
	s_waitcnt lgkmcnt(0)
	v_mfma_f32_32x32x16_bf16 v[0:15], v[144:147], v[202:205], v[0:15]
	v_exp_f32_e32 v110, v110
	v_exp_f32_e32 v111, v111
	s_waitcnt vmcnt(3) lgkmcnt(0)
	s_barrier
	s_add_i32 s88, s86, 0x2000
	s_cmpk_lg_i32 s86, 0x4000
	s_cselect_b32 s88, s88, 0
	v_lshl_add_u32 v206, s87, 1, v188
	ds_read_b64_tr_b16 v[194:195], v206 offset:24576
	ds_read_b64_tr_b16 v[196:197], v206 offset:25088
	v_add_f32_e32 v76, v112, v113
	v_add_f32_e32 v76, v114, v76
	v_add_f32_e32 v76, v115, v76
	v_add_f32_e32 v76, v116, v76
	v_mfma_f32_32x32x16_bf16 v[80:95], v[68:71], v[218:221], 0
	v_add_f32_e32 v76, v117, v76
	v_cvt_pk_bf16_f32 v156, v112, v113
	v_cvt_pk_bf16_f32 v157, v114, v115
	ds_read_b64_tr_b16 v[112:113], v206 offset:28672
	ds_read_b64_tr_b16 v[114:115], v206 offset:29184
	v_add_f32_e32 v72, v118, v76
	v_add_f32_e32 v72, v119, v72
	v_add_f32_e32 v72, v120, v72
	v_add_f32_e32 v144, v121, v72
	v_mfma_f32_32x32x16_bf16 v[64:79], v[64:67], v[218:221], 0
	v_cvt_pk_bf16_f32 v158, v116, v117
	v_cvt_pk_bf16_f32 v159, v118, v119
	ds_read_b64_tr_b16 v[116:117], v206 offset:25600
	ds_read_b64_tr_b16 v[118:119], v206 offset:26112
	v_add_f32_e32 v144, v122, v144
	v_add_f32_e32 v144, v123, v144
	v_add_f32_e32 v144, v124, v144
	v_add_f32_e32 v144, v125, v144
	v_mfma_f32_32x32x16_bf16 v[80:95], v[164:167], v[222:225], v[80:95]
	v_cvt_pk_bf16_f32 v152, v120, v121
	v_cvt_pk_bf16_f32 v153, v122, v123
	ds_read_b64_tr_b16 v[120:121], v206 offset:29696
	ds_read_b64_tr_b16 v[122:123], v206 offset:30208
	v_add_f32_e32 v144, v126, v144
	v_add_f32_e32 v144, v127, v144
	v_add_f32_e32 v144, v96, v144
	v_add_f32_e32 v144, v97, v144
	v_mfma_f32_32x32x16_bf16 v[64:79], v[140:143], v[222:225], v[64:79]
	v_cvt_pk_bf16_f32 v154, v124, v125
	v_cvt_pk_bf16_f32 v155, v126, v127
	ds_read_b64_tr_b16 v[124:125], v206 offset:26624
	ds_read_b64_tr_b16 v[126:127], v206 offset:27136
	v_add_f32_e32 v144, v98, v144
	v_add_f32_e32 v144, v99, v144
	v_add_f32_e32 v144, v100, v144
	v_add_f32_e32 v144, v101, v144
	v_mfma_f32_32x32x16_bf16 v[80:95], v[160:163], v[226:229], v[80:95]
	v_cvt_pk_bf16_f32 v148, v96, v97
	v_cvt_pk_bf16_f32 v149, v98, v99
	ds_read_b64_tr_b16 v[198:199], v206 offset:30720
	ds_read_b64_tr_b16 v[200:201], v206 offset:31232
	v_add_f32_e32 v140, v102, v144
	v_add_f32_e32 v140, v103, v140
	v_add_f32_e32 v140, v104, v140
	v_add_f32_e32 v140, v105, v140
	v_mfma_f32_32x32x16_bf16 v[64:79], v[132:135], v[226:229], v[64:79]
	v_cvt_pk_bf16_f32 v150, v100, v101
	v_cvt_pk_bf16_f32 v151, v102, v103
	ds_read_b64_tr_b16 v[202:203], v206 offset:27648
	ds_read_b64_tr_b16 v[204:205], v206 offset:28160
	v_add_f32_e32 v100, v106, v140
	v_add_f32_e32 v100, v107, v100
	v_add_f32_e32 v100, v108, v100
	v_add_f32_e32 v100, v109, v100
	v_mfma_f32_32x32x16_bf16 v[80:95], v[136:139], v[230:233], v[80:95]
	v_cvt_pk_bf16_f32 v144, v104, v105
	v_cvt_pk_bf16_f32 v145, v106, v107
	ds_read_b64_tr_b16 v[104:105], v206 offset:31744
	ds_read_b64_tr_b16 v[106:107], v206 offset:32256
	v_add_f32_e32 v100, v110, v100
	v_add_f32_e32 v100, v111, v100
	v_add_f32_e32 v100, 0, v100
	v_cvt_pk_bf16_f32 v146, v108, v109
	v_mfma_f32_32x32x16_bf16 v[64:79], v[128:131], v[230:233], v[64:79]
	v_cvt_pk_bf16_f32 v147, v110, v111
	s_add_i32 s87, s86, s17
	s_mov_b32 s89, m0
	s_mov_b32 m0, s87
	s_nop 0
	global_load_lds_dwordx4 v[180:181], off
	s_mov_b32 m0, s89
	s_lshl_b32 s87, s88, 1
	s_add_i32 s87, s87, s16
	s_mov_b32 s89, m0
	s_mov_b32 m0, s87
	s_nop 0
	global_load_lds_dwordx4 v[178:179], off
	s_mov_b32 m0, s89
	s_addk_i32 s87, 0x2000
	s_mov_b32 s89, m0
	s_mov_b32 m0, s87
	s_nop 0
	global_load_lds_dwordx4 v[176:177], off
	s_mov_b32 m0, s89
	v_add_f32_e32 v193, v193, v100
	s_waitcnt lgkmcnt(12)
; #define WAIT_BAR(N) asm volatile("s_waitcnt vmcnt(" #N ") lgkmcnt(0)\n\ts_barrier":::"memory")
;   #define RESC() do{ if(!NOMAX&&resc){ asm volatile("s_waitcnt lgkmcnt(0)":::"memory"); \
;       _Pragma("unroll") for(int d_=0;d_<2*VM;++d_) _Pragma("unroll") for(int r=0;r<16;++r)o[d_][r]*=wsf[crow(r,hi)]; } }while(0)
;   #define ROT() do{sl_prev=sl_cur;sl_cur=sl_next;sl_next=(sl_next==(NSLOT-1)*SLOTB)?0:sl_next+SLOTB;}while(0)
;   #define ENDW(tt) do{ if((tt)+3<NT){ if constexpr(VM==2){WAIT_BAR(3);}else{WAIT_BAR(2);} } else if((tt)+2<NT){ if constexpr(VM==2){WAIT_BAR(2);}else{WAIT_BAR(1);} } else {WAIT_BAR(0);} }while(0)
; template<int THRL,int VM,bool NOMAX> __device__ __forceinline__ void attn_unit(const bf16*Qb,const bf16*__restrict__ Kh,const bf16*__restrict__ Vh,bf16*Ob,const int NT,const int sp,float*wscr,char*shm){
;     ...
;   int t=1;
;   for(;t+5<NT;t+=2){
;     STEP(pB0,pB1,pA0,pA1,t,true,true,true);     if constexpr(VM==2){WAIT_BAR(3);}else{WAIT_BAR(2);} RESC(); ROT();
;     STEP(pA0,pA1,pB0,pB1,t+1,true,true,true);   if constexpr(VM==2){WAIT_BAR(3);}else{WAIT_BAR(2);} RESC(); ROT();
;   }
;     ...
;   for(;t+1<NT;t+=2){
;     STEP(pB0,pB1,pA0,pA1,t,(t+3<NT),(t+1<NT),(t+1<NT));       ENDW(t);   RESC(); ROT();
;     STEP(pA0,pA1,pB0,pB1,t+1,(t+4<NT),(t+2<NT),(t+2<NT));     ENDW(t+1); RESC(); ROT();
	v_mfma_f32_32x32x16_bf16 v[48:63], v[156:159], v[194:197], v[48:63]
	ds_read_b64_tr_b16 v[108:109], v206 offset:32768
	ds_read_b64_tr_b16 v[110:111], v206 offset:33280
	v_exp_f32_e32 v80, v80
	v_exp_f32_e32 v81, v81
	v_mfma_f32_32x32x16_bf16 v[32:47], v[156:159], v[112:115], v[32:47]
	ds_read_b64_tr_b16 v[194:195], v206 offset:36864
	ds_read_b64_tr_b16 v[196:197], v206 offset:37376
	v_exp_f32_e32 v82, v82
	v_exp_f32_e32 v83, v83
	v_add_u32_e32 v128, s88, v189
	ds_read_b128 v[100:103], v128
	ds_read_b128 v[96:99], v128 offset:512
	s_waitcnt lgkmcnt(14)
	v_mfma_f32_32x32x16_bf16 v[48:63], v[152:155], v[116:119], v[48:63]
	ds_read_b64_tr_b16 v[112:113], v206 offset:33792
	ds_read_b64_tr_b16 v[114:115], v206 offset:34304
	v_exp_f32_e32 v84, v84
	v_exp_f32_e32 v85, v85
	ds_read_b128 v[164:167], v128 offset:2048
	ds_read_b128 v[160:163], v128 offset:2560
	v_mfma_f32_32x32x16_bf16 v[32:47], v[152:155], v[120:123], v[32:47]
	ds_read_b64_tr_b16 v[116:117], v206 offset:37888
	ds_read_b64_tr_b16 v[118:119], v206 offset:38400
	v_exp_f32_e32 v86, v86
	v_exp_f32_e32 v87, v87
	ds_read_b128 v[140:143], v128 offset:4096
	ds_read_b128 v[136:139], v128 offset:4608
	s_waitcnt lgkmcnt(14)
	v_mfma_f32_32x32x16_bf16 v[48:63], v[148:151], v[124:127], v[48:63]
	ds_read_b64_tr_b16 v[120:121], v206 offset:34816
	ds_read_b64_tr_b16 v[122:123], v206 offset:35328
	v_exp_f32_e32 v88, v88
	v_exp_f32_e32 v89, v89
	ds_read_b128 v[132:135], v128 offset:6144
	ds_read_b128 v[128:131], v128 offset:6656
	v_mfma_f32_32x32x16_bf16 v[32:47], v[148:151], v[198:201], v[32:47]
	ds_read_b64_tr_b16 v[124:125], v206 offset:38912
	ds_read_b64_tr_b16 v[126:127], v206 offset:39424
	v_exp_f32_e32 v90, v90
	v_exp_f32_e32 v91, v91
	s_waitcnt lgkmcnt(14)
	v_mfma_f32_32x32x16_bf16 v[48:63], v[144:147], v[202:205], v[48:63]
	ds_read_b64_tr_b16 v[198:199], v206 offset:35840
	ds_read_b64_tr_b16 v[200:201], v206 offset:36352
	v_exp_f32_e32 v92, v92
	v_exp_f32_e32 v93, v93
	v_mfma_f32_32x32x16_bf16 v[32:47], v[144:147], v[104:107], v[32:47]
	ds_read_b64_tr_b16 v[202:203], v206 offset:39936
	ds_read_b64_tr_b16 v[204:205], v206 offset:40448
	v_exp_f32_e32 v94, v94
	v_exp_f32_e32 v95, v95
	s_waitcnt lgkmcnt(14)
	v_mfma_f32_32x32x16_bf16 v[16:31], v[156:159], v[108:111], v[16:31]
	v_exp_f32_e32 v64, v64
	v_exp_f32_e32 v65, v65
	v_mfma_f32_32x32x16_bf16 v[0:15], v[156:159], v[194:197], v[0:15]
	v_exp_f32_e32 v66, v66
	v_exp_f32_e32 v67, v67
	v_mfma_f32_32x32x16_bf16 v[16:31], v[152:155], v[112:115], v[16:31]
	v_exp_f32_e32 v68, v68
	v_exp_f32_e32 v69, v69
	s_waitcnt lgkmcnt(12)
	v_mfma_f32_32x32x16_bf16 v[0:15], v[152:155], v[116:119], v[0:15]
	v_exp_f32_e32 v70, v70
	v_exp_f32_e32 v71, v71
	s_waitcnt lgkmcnt(8)
	v_mfma_f32_32x32x16_bf16 v[16:31], v[148:151], v[120:123], v[16:31]
	v_exp_f32_e32 v72, v72
	v_exp_f32_e32 v73, v73
	s_waitcnt lgkmcnt(4)
	v_mfma_f32_32x32x16_bf16 v[0:15], v[148:151], v[124:127], v[0:15]
	v_exp_f32_e32 v74, v74
	v_exp_f32_e32 v75, v75
	s_waitcnt lgkmcnt(2)
	v_mfma_f32_32x32x16_bf16 v[16:31], v[144:147], v[198:201], v[16:31]
	v_exp_f32_e32 v76, v76
	v_exp_f32_e32 v77, v77
	s_waitcnt lgkmcnt(0)
	v_mfma_f32_32x32x16_bf16 v[0:15], v[144:147], v[202:205], v[0:15]
	v_exp_f32_e32 v78, v78
	v_exp_f32_e32 v79, v79
	s_add_i32 s90, s88, 0x2000
	s_waitcnt vmcnt(3) lgkmcnt(0)
	s_barrier
	s_cmpk_lg_i32 s88, 0x4000
	s_mov_b32 s89, s86
	s_cselect_b32 s86, s90, 0
	s_add_i32 s85, s85, 2
	v_lshl_add_u64 v[176:177], v[176:177], 0, s[58:59]
	v_lshl_add_u64 v[178:179], v[178:179], 0, s[58:59]
	v_lshl_add_u64 v[180:181], v[180:181], 0, s[58:59]
	s_mov_b32 s87, s88
	s_cmp_lt_u32 s85, 57
	s_cbranch_scc1 .LBB0_874
	s_and_b32 s34, s34, 0x3fffffc0
	s_lshl_b32 s34, s34, 2
	s_add_i32 s34, s34, 0
	s_add_i32 s34, s34, 0x12000
	s_cmp_lg_u32 0, -1
	s_cselect_b32 s85, 0, 0
	s_add_i32 s86, s85, 0x6000
	v_add_u32_e32 v104, s86, v191
	v_add3_u32 v176, v104, v190, v192
	v_add_u32_e32 v177, 0x6000, v188
	ds_read_b64_tr_b16 v[178:179], v188 offset:40960
	ds_read_b64_tr_b16 v[180:181], v188 offset:41472
	v_add_f32_e32 v108, v80, v81
	ds_read_b128 v[104:107], v168
	v_add_f32_e32 v108, v82, v108
	v_add_f32_e32 v108, v83, v108
	v_add_f32_e32 v108, v84, v108
	v_add_f32_e32 v108, v85, v108
	v_cvt_pk_bf16_f32 v156, v80, v81
	v_cvt_pk_bf16_f32 v157, v82, v83
	s_waitcnt lgkmcnt(0)
	v_mfma_f32_32x32x16_bf16 v[112:127], v[100:103], v[104:107], 0
	ds_read_b64_tr_b16 v[80:81], v188 offset:45056
	ds_read_b64_tr_b16 v[82:83], v188 offset:45568
	ds_read_b128 v[100:103], v168
	v_add_f32_e32 v104, v86, v108
	v_add_f32_e32 v104, v87, v104
	v_add_f32_e32 v104, v88, v104
	v_add_f32_e32 v144, v89, v104
	v_cvt_pk_bf16_f32 v158, v84, v85
	v_cvt_pk_bf16_f32 v159, v86, v87
	s_waitcnt lgkmcnt(0)
	v_mfma_f32_32x32x16_bf16 v[96:111], v[96:99], v[100:103], 0
	ds_read_b64_tr_b16 v[84:85], v188 offset:41984
	ds_read_b64_tr_b16 v[86:87], v188 offset:42496
	ds_read_b128 v[194:197], v168 offset:1024
	v_add_f32_e32 v144, v90, v144
	v_add_f32_e32 v144, v91, v144
	v_add_f32_e32 v144, v92, v144
	v_add_f32_e32 v144, v93, v144
	v_cvt_pk_bf16_f32 v152, v88, v89
	v_cvt_pk_bf16_f32 v153, v90, v91
	s_waitcnt lgkmcnt(0)
	v_mfma_f32_32x32x16_bf16 v[112:127], v[164:167], v[194:197], v[112:127]
	ds_read_b64_tr_b16 v[88:89], v188 offset:46080
	ds_read_b64_tr_b16 v[90:91], v188 offset:46592
	ds_read_b128 v[164:167], v168 offset:1024
	v_add_f32_e32 v144, v94, v144
	v_add_f32_e32 v144, v95, v144
	v_add_f32_e32 v144, v64, v144
	v_add_f32_e32 v144, v65, v144
	v_cvt_pk_bf16_f32 v154, v92, v93
	v_cvt_pk_bf16_f32 v155, v94, v95
	s_waitcnt lgkmcnt(0)
	v_mfma_f32_32x32x16_bf16 v[96:111], v[160:163], v[164:167], v[96:111]
	ds_read_b64_tr_b16 v[194:195], v188 offset:43008
	ds_read_b64_tr_b16 v[196:197], v188 offset:43520
	ds_read_b128 v[92:95], v168 offset:2048
	v_add_f32_e32 v144, v66, v144
	v_add_f32_e32 v144, v67, v144
	v_add_f32_e32 v144, v68, v144
	v_add_f32_e32 v144, v69, v144
	v_cvt_pk_bf16_f32 v148, v64, v65
	v_cvt_pk_bf16_f32 v149, v66, v67
	s_waitcnt lgkmcnt(0)
	v_mfma_f32_32x32x16_bf16 v[112:127], v[140:143], v[92:95], v[112:127]
	ds_read_b64_tr_b16 v[140:141], v188 offset:47104
	ds_read_b64_tr_b16 v[142:143], v188 offset:47616
	ds_read_b128 v[64:67], v168 offset:2048
	v_add_f32_e32 v92, v70, v144
	v_add_f32_e32 v92, v71, v92
	v_add_f32_e32 v92, v72, v92
	v_add_f32_e32 v92, v73, v92
	v_cvt_pk_bf16_f32 v150, v68, v69
	v_cvt_pk_bf16_f32 v151, v70, v71
	s_waitcnt lgkmcnt(0)
	v_mfma_f32_32x32x16_bf16 v[96:111], v[136:139], v[64:67], v[96:111]
	ds_read_b64_tr_b16 v[136:137], v188 offset:44032
	ds_read_b64_tr_b16 v[138:139], v188 offset:44544
	ds_read_b128 v[64:67], v168 offset:3072
	v_add_f32_e32 v68, v74, v92
	v_add_f32_e32 v68, v75, v68
	v_add_f32_e32 v68, v76, v68
	v_add_f32_e32 v68, v77, v68
	v_cvt_pk_bf16_f32 v144, v72, v73
	v_cvt_pk_bf16_f32 v145, v74, v75
	s_waitcnt lgkmcnt(0)
	v_mfma_f32_32x32x16_bf16 v[112:127], v[132:135], v[64:67], v[112:127]
	ds_read_b64_tr_b16 v[72:73], v188 offset:48128
	ds_read_b64_tr_b16 v[74:75], v188 offset:48640
	ds_read_b128 v[64:67], v168 offset:3072
	v_add_f32_e32 v68, v78, v68
	v_add_f32_e32 v68, v79, v68
	v_add_f32_e32 v68, 0, v68
	v_cvt_pk_bf16_f32 v146, v76, v77
	v_cvt_pk_bf16_f32 v147, v78, v79
	s_waitcnt lgkmcnt(0)
	v_mfma_f32_32x32x16_bf16 v[96:111], v[128:131], v[64:67], v[96:111]
	s_add_i32 s85, s85, s35
	v_lshl_add_u64 v[64:65], v[174:175], 0, s[60:61]
	s_add_i32 s35, s85, 0x4000
	s_mov_b32 s86, m0
	s_mov_b32 m0, s35
	s_nop 0
	global_load_lds_dwordx4 v[64:65], off
	s_mov_b32 m0, s86
	v_lshl_add_u64 v[64:65], v[170:171], 0, s[62:63]
	s_mov_b32 s35, m0
	s_mov_b32 m0, s16
	s_nop 0
	global_load_lds_dwordx4 v[64:65], off
	s_mov_b32 m0, s35
	v_lshl_add_u64 v[64:65], v[172:173], 0, s[62:63]
	s_add_i32 s35, s16, 0x2000
	s_mov_b32 s86, m0
	s_mov_b32 m0, s35
	s_nop 0
	global_load_lds_dwordx4 v[64:65], off
	s_mov_b32 m0, s86
	v_add_f32_e32 v198, v193, v68
	v_mfma_f32_32x32x16_bf16 v[48:63], v[156:159], v[178:181], v[48:63]
	ds_read_b64_tr_b16 v[76:77], v188 offset:49152
	ds_read_b64_tr_b16 v[78:79], v188 offset:49664
	v_exp_f32_e32 v112, v112
	v_exp_f32_e32 v113, v113
	v_mfma_f32_32x32x16_bf16 v[32:47], v[156:159], v[80:83], v[32:47]
	ds_read_b64_tr_b16 v[128:129], v188 offset:53248
	ds_read_b64_tr_b16 v[130:131], v188 offset:53760
	v_exp_f32_e32 v114, v114
	v_exp_f32_e32 v115, v115
	ds_read_b128 v[68:71], v189
	ds_read_b128 v[64:67], v189 offset:512
	v_mfma_f32_32x32x16_bf16 v[48:63], v[152:155], v[84:87], v[48:63]
	ds_read_b64_tr_b16 v[132:133], v188 offset:50176
	ds_read_b64_tr_b16 v[134:135], v188 offset:50688
	v_exp_f32_e32 v116, v116
	v_exp_f32_e32 v117, v117
	ds_read_b128 v[164:167], v189 offset:2048
	ds_read_b128 v[92:95], v189 offset:2560
	v_mfma_f32_32x32x16_bf16 v[32:47], v[152:155], v[88:91], v[32:47]
	ds_read_b64_tr_b16 v[178:179], v188 offset:54272
	ds_read_b64_tr_b16 v[180:181], v188 offset:54784
	v_exp_f32_e32 v118, v118
	v_exp_f32_e32 v119, v119
	ds_read_b128 v[160:163], v189 offset:4096
	ds_read_b128 v[84:87], v189 offset:4608
	v_mfma_f32_32x32x16_bf16 v[48:63], v[148:151], v[194:197], v[48:63]
	ds_read_b64_tr_b16 v[190:191], v188 offset:51200
	ds_read_b64_tr_b16 v[192:193], v188 offset:51712
	v_exp_f32_e32 v120, v120
	v_exp_f32_e32 v121, v121
	ds_read_b128 v[88:91], v189 offset:6144
	ds_read_b128 v[80:83], v189 offset:6656
	v_mfma_f32_32x32x16_bf16 v[32:47], v[148:151], v[140:143], v[32:47]
	ds_read_b64_tr_b16 v[194:195], v188 offset:55296
	ds_read_b64_tr_b16 v[196:197], v188 offset:55808
	v_exp_f32_e32 v122, v122
	v_exp_f32_e32 v123, v123
	v_mfma_f32_32x32x16_bf16 v[48:63], v[144:147], v[136:139], v[48:63]
	ds_read_b64_tr_b16 v[140:141], v188 offset:52224
	ds_read_b64_tr_b16 v[142:143], v188 offset:52736
	v_exp_f32_e32 v124, v124
	v_exp_f32_e32 v125, v125
	v_mfma_f32_32x32x16_bf16 v[32:47], v[144:147], v[72:75], v[32:47]
	ds_read_b64_tr_b16 v[136:137], v188 offset:56320
	ds_read_b64_tr_b16 v[138:139], v188 offset:56832
	v_exp_f32_e32 v126, v126
	v_exp_f32_e32 v127, v127
	s_waitcnt lgkmcnt(14)
	v_mfma_f32_32x32x16_bf16 v[16:31], v[156:159], v[76:79], v[16:31]
	v_exp_f32_e32 v96, v96
	v_exp_f32_e32 v97, v97
	v_mfma_f32_32x32x16_bf16 v[0:15], v[156:159], v[128:131], v[0:15]
	v_exp_f32_e32 v98, v98
	v_exp_f32_e32 v99, v99
	v_mfma_f32_32x32x16_bf16 v[16:31], v[152:155], v[132:135], v[16:31]
	v_exp_f32_e32 v100, v100
	v_exp_f32_e32 v101, v101
	s_waitcnt lgkmcnt(12)
	v_mfma_f32_32x32x16_bf16 v[0:15], v[152:155], v[178:181], v[0:15]
	v_exp_f32_e32 v102, v102
	v_exp_f32_e32 v103, v103
	s_waitcnt lgkmcnt(8)
	v_mfma_f32_32x32x16_bf16 v[16:31], v[148:151], v[190:193], v[16:31]
	v_exp_f32_e32 v104, v104
	v_exp_f32_e32 v105, v105
	s_waitcnt lgkmcnt(4)
	v_mfma_f32_32x32x16_bf16 v[0:15], v[148:151], v[194:197], v[0:15]
	v_exp_f32_e32 v106, v106
	v_exp_f32_e32 v107, v107
	s_waitcnt lgkmcnt(2)
	v_mfma_f32_32x32x16_bf16 v[16:31], v[144:147], v[140:143], v[16:31]
	v_exp_f32_e32 v108, v108
	v_exp_f32_e32 v109, v109
	s_waitcnt lgkmcnt(0)
	v_mfma_f32_32x32x16_bf16 v[0:15], v[144:147], v[136:139], v[0:15]
	v_exp_f32_e32 v110, v110
	v_exp_f32_e32 v111, v111
	s_waitcnt vmcnt(3) lgkmcnt(0)
	s_barrier
	ds_read_b64_tr_b16 v[178:179], v188 offset:57344
	ds_read_b64_tr_b16 v[180:181], v188 offset:57856
	v_add_f32_e32 v76, v112, v113
	ds_read_b128 v[72:75], v168
	v_add_f32_e32 v76, v114, v76
	v_add_f32_e32 v76, v115, v76
	v_add_f32_e32 v76, v116, v76
	v_add_f32_e32 v76, v117, v76
	v_cvt_pk_bf16_f32 v156, v112, v113
	v_cvt_pk_bf16_f32 v157, v114, v115
	s_waitcnt lgkmcnt(0)
	v_mfma_f32_32x32x16_bf16 v[128:143], v[68:71], v[72:75], 0
	ds_read_b64_tr_b16 v[112:113], v188 offset:61440
	ds_read_b64_tr_b16 v[114:115], v188 offset:61952
	ds_read_b128 v[68:71], v168
	v_add_f32_e32 v72, v118, v76
	v_add_f32_e32 v72, v119, v72
	v_add_f32_e32 v72, v120, v72
	v_add_f32_e32 v144, v121, v72
	s_waitcnt lgkmcnt(0)
	v_mfma_f32_32x32x16_bf16 v[64:79], v[64:67], v[68:71], 0
	v_cvt_pk_bf16_f32 v158, v116, v117
	v_cvt_pk_bf16_f32 v159, v118, v119
	ds_read_b64_tr_b16 v[116:117], v188 offset:58368
	ds_read_b64_tr_b16 v[118:119], v188 offset:58880
	ds_read_b128 v[190:193], v168 offset:1024
	v_add_f32_e32 v144, v122, v144
	v_add_f32_e32 v144, v123, v144
	v_add_f32_e32 v144, v124, v144
	v_add_f32_e32 v144, v125, v144
	v_cvt_pk_bf16_f32 v152, v120, v121
	v_cvt_pk_bf16_f32 v153, v122, v123
	s_waitcnt lgkmcnt(0)
	v_mfma_f32_32x32x16_bf16 v[128:143], v[164:167], v[190:193], v[128:143]
	ds_read_b64_tr_b16 v[120:121], v188 offset:62464
	ds_read_b64_tr_b16 v[122:123], v188 offset:62976
	ds_read_b128 v[164:167], v168 offset:1024
	v_add_f32_e32 v144, v126, v144
	v_add_f32_e32 v144, v127, v144
	v_add_f32_e32 v144, v96, v144
	v_add_f32_e32 v144, v97, v144
	s_waitcnt lgkmcnt(0)
	v_mfma_f32_32x32x16_bf16 v[64:79], v[92:95], v[164:167], v[64:79]
	v_cvt_pk_bf16_f32 v154, v124, v125
	v_cvt_pk_bf16_f32 v155, v126, v127
	ds_read_b64_tr_b16 v[92:93], v188 offset:59392
	ds_read_b64_tr_b16 v[94:95], v188 offset:59904
	ds_read_b128 v[124:127], v168 offset:2048
	v_add_f32_e32 v144, v98, v144
	v_add_f32_e32 v144, v99, v144
	v_add_f32_e32 v144, v100, v144
	v_add_f32_e32 v144, v101, v144
	v_cvt_pk_bf16_f32 v148, v96, v97
	v_cvt_pk_bf16_f32 v149, v98, v99
	s_waitcnt lgkmcnt(0)
	v_mfma_f32_32x32x16_bf16 v[128:143], v[160:163], v[124:127], v[128:143]
	ds_read_b64_tr_b16 v[96:97], v188 offset:63488
	ds_read_b64_tr_b16 v[98:99], v188 offset:64000
	ds_read_b128 v[124:127], v168 offset:2048
	v_add_f32_e32 v144, v102, v144
	v_add_f32_e32 v144, v103, v144
	v_add_f32_e32 v144, v104, v144
	v_add_f32_e32 v144, v105, v144
	s_waitcnt lgkmcnt(0)
	v_mfma_f32_32x32x16_bf16 v[64:79], v[84:87], v[124:127], v[64:79]
	v_cvt_pk_bf16_f32 v150, v100, v101
	v_cvt_pk_bf16_f32 v151, v102, v103
	ds_read_b64_tr_b16 v[100:101], v188 offset:60416
	ds_read_b64_tr_b16 v[102:103], v188 offset:60928
	ds_read_b128 v[84:87], v168 offset:3072
	v_add_f32_e32 v124, v106, v144
	v_add_f32_e32 v124, v107, v124
	v_add_f32_e32 v124, v108, v124
	v_add_f32_e32 v124, v109, v124
	v_cvt_pk_bf16_f32 v144, v104, v105
	v_cvt_pk_bf16_f32 v145, v106, v107
	s_waitcnt lgkmcnt(0)
	v_mfma_f32_32x32x16_bf16 v[128:143], v[88:91], v[84:87], v[128:143]
	ds_read_b64_tr_b16 v[88:89], v188 offset:64512
	ds_read_b64_tr_b16 v[90:91], v188 offset:65024
	ds_read_b128 v[84:87], v168 offset:3072
	v_add_f32_e32 v104, v110, v124
	v_add_f32_e32 v104, v111, v104
	v_add_f32_e32 v104, 0, v104
	v_cvt_pk_bf16_f32 v146, v108, v109
	s_waitcnt lgkmcnt(0)
	v_mfma_f32_32x32x16_bf16 v[64:79], v[80:83], v[84:87], v[64:79]
	v_cvt_pk_bf16_f32 v147, v110, v111
	v_lshl_add_u64 v[80:81], v[174:175], 0, s[64:65]
	s_mov_b32 s86, m0
	s_mov_b32 m0, s17
	s_nop 0
	global_load_lds_dwordx4 v[80:81], off
	s_mov_b32 m0, s86
	v_lshl_add_u64 v[80:81], v[170:171], 0, s[66:67]
	s_add_i32 s17, s85, 0xa000
	s_mov_b32 s86, m0
	s_mov_b32 m0, s17
	s_nop 0
	global_load_lds_dwordx4 v[80:81], off
	s_mov_b32 m0, s86
	v_lshl_add_u64 v[80:81], v[172:173], 0, s[66:67]
	s_add_i32 s17, s85, 0xc000
	s_mov_b32 s86, m0
	s_mov_b32 m0, s17
	s_nop 0
	global_load_lds_dwordx4 v[80:81], off
	s_mov_b32 m0, s86
	v_add_f32_e32 v198, v198, v104
	v_mfma_f32_32x32x16_bf16 v[48:63], v[156:159], v[178:181], v[48:63]
	ds_read_b64_tr_b16 v[104:105], v177 offset:40960
	ds_read_b64_tr_b16 v[106:107], v177 offset:41472
	v_exp_f32_e32 v128, v128
	v_exp_f32_e32 v129, v129
	v_mfma_f32_32x32x16_bf16 v[32:47], v[156:159], v[112:115], v[32:47]
	ds_read_b64_tr_b16 v[108:109], v177 offset:45056
	ds_read_b64_tr_b16 v[110:111], v177 offset:45568
	v_exp_f32_e32 v130, v130
	v_exp_f32_e32 v131, v131
	ds_read_b128 v[84:87], v189 offset:8192
	ds_read_b128 v[80:83], v189 offset:8704
	v_mfma_f32_32x32x16_bf16 v[48:63], v[152:155], v[116:119], v[48:63]
	ds_read_b64_tr_b16 v[178:179], v177 offset:41984
	ds_read_b64_tr_b16 v[180:181], v177 offset:42496
	v_exp_f32_e32 v132, v132
	v_exp_f32_e32 v133, v133
	ds_read_b128 v[164:167], v189 offset:10240
	ds_read_b128 v[124:127], v189 offset:10752
	v_mfma_f32_32x32x16_bf16 v[32:47], v[152:155], v[120:123], v[32:47]
	ds_read_b64_tr_b16 v[190:191], v177 offset:46080
	ds_read_b64_tr_b16 v[192:193], v177 offset:46592
	v_exp_f32_e32 v134, v134
	v_exp_f32_e32 v135, v135
	ds_read_b128 v[160:163], v189 offset:12288
	ds_read_b128 v[116:119], v189 offset:12800
	v_mfma_f32_32x32x16_bf16 v[48:63], v[148:151], v[92:95], v[48:63]
	ds_read_b64_tr_b16 v[194:195], v177 offset:43008
	ds_read_b64_tr_b16 v[196:197], v177 offset:43520
	v_exp_f32_e32 v136, v136
	v_exp_f32_e32 v137, v137
	ds_read_b128 v[120:123], v189 offset:14336
	ds_read_b128 v[112:115], v189 offset:14848
	v_mfma_f32_32x32x16_bf16 v[32:47], v[148:151], v[96:99], v[32:47]
	ds_read_b64_tr_b16 v[92:93], v177 offset:47104
	ds_read_b64_tr_b16 v[94:95], v177 offset:47616
	v_exp_f32_e32 v138, v138
	v_exp_f32_e32 v139, v139
	v_mfma_f32_32x32x16_bf16 v[48:63], v[144:147], v[100:103], v[48:63]
	ds_read_b64_tr_b16 v[96:97], v177 offset:44032
	ds_read_b64_tr_b16 v[98:99], v177 offset:44544
	v_exp_f32_e32 v140, v140
	v_exp_f32_e32 v141, v141
	v_mfma_f32_32x32x16_bf16 v[32:47], v[144:147], v[88:91], v[32:47]
	ds_read_b64_tr_b16 v[100:101], v177 offset:48128
	ds_read_b64_tr_b16 v[102:103], v177 offset:48640
	v_exp_f32_e32 v142, v142
	v_exp_f32_e32 v143, v143
	s_waitcnt lgkmcnt(14)
; #define WAIT_BAR(N) asm volatile("s_waitcnt vmcnt(" #N ") lgkmcnt(0)\n\ts_barrier":::"memory")
;   #define RESC() do{ if(!NOMAX&&resc){ asm volatile("s_waitcnt lgkmcnt(0)":::"memory"); \
;       _Pragma("unroll") for(int d_=0;d_<2*VM;++d_) _Pragma("unroll") for(int r=0;r<16;++r)o[d_][r]*=wsf[crow(r,hi)]; } }while(0)
;   #define ROT() do{sl_prev=sl_cur;sl_cur=sl_next;sl_next=(sl_next==(NSLOT-1)*SLOTB)?0:sl_next+SLOTB;}while(0)
;   #define ENDW(tt) do{ if((tt)+3<NT){ if constexpr(VM==2){WAIT_BAR(3);}else{WAIT_BAR(2);} } else if((tt)+2<NT){ if constexpr(VM==2){WAIT_BAR(2);}else{WAIT_BAR(1);} } else {WAIT_BAR(0);} }while(0)
; template<int THRL,int VM,bool NOMAX> __device__ __forceinline__ void attn_unit(const bf16*Qb,const bf16*__restrict__ Kh,const bf16*__restrict__ Vh,bf16*Ob,const int NT,const int sp,float*wscr,char*shm){
;     ...
;   int t=1;
;   for(;t+5<NT;t+=2){
;     STEP(pB0,pB1,pA0,pA1,t,true,true,true);     if constexpr(VM==2){WAIT_BAR(3);}else{WAIT_BAR(2);} RESC(); ROT();
;     STEP(pA0,pA1,pB0,pB1,t+1,true,true,true);   if constexpr(VM==2){WAIT_BAR(3);}else{WAIT_BAR(2);} RESC(); ROT();
;   }
;     ...
;   for(;t+1<NT;t+=2){
;     STEP(pB0,pB1,pA0,pA1,t,(t+3<NT),(t+1<NT),(t+1<NT));       ENDW(t);   RESC(); ROT();
;     STEP(pA0,pA1,pB0,pB1,t+1,(t+4<NT),(t+2<NT),(t+2<NT));     ENDW(t+1); RESC(); ROT();
	v_mfma_f32_32x32x16_bf16 v[16:31], v[156:159], v[104:107], v[16:31]
	v_exp_f32_e32 v64, v64
	v_exp_f32_e32 v65, v65
	v_mfma_f32_32x32x16_bf16 v[0:15], v[156:159], v[108:111], v[0:15]
	v_exp_f32_e32 v66, v66
	v_exp_f32_e32 v67, v67
	v_mfma_f32_32x32x16_bf16 v[16:31], v[152:155], v[178:181], v[16:31]
	v_exp_f32_e32 v68, v68
	v_exp_f32_e32 v69, v69
	s_waitcnt lgkmcnt(12)
	v_mfma_f32_32x32x16_bf16 v[0:15], v[152:155], v[190:193], v[0:15]
	v_exp_f32_e32 v70, v70
	v_exp_f32_e32 v71, v71
	s_waitcnt lgkmcnt(8)
	v_mfma_f32_32x32x16_bf16 v[16:31], v[148:151], v[194:197], v[16:31]
	v_exp_f32_e32 v72, v72
	v_exp_f32_e32 v73, v73
	s_waitcnt lgkmcnt(4)
	v_mfma_f32_32x32x16_bf16 v[0:15], v[148:151], v[92:95], v[0:15]
	v_exp_f32_e32 v74, v74
	v_exp_f32_e32 v75, v75
	s_waitcnt lgkmcnt(2)
	v_mfma_f32_32x32x16_bf16 v[16:31], v[144:147], v[96:99], v[16:31]
	v_exp_f32_e32 v76, v76
	v_exp_f32_e32 v77, v77
	s_waitcnt lgkmcnt(0)
	v_mfma_f32_32x32x16_bf16 v[0:15], v[144:147], v[100:103], v[0:15]
	v_exp_f32_e32 v78, v78
	v_exp_f32_e32 v79, v79
	s_waitcnt vmcnt(3) lgkmcnt(0)
	s_barrier
	ds_read_b64_tr_b16 v[178:179], v188 offset:24576
	ds_read_b64_tr_b16 v[180:181], v188 offset:25088
	v_add_f32_e32 v92, v128, v129
	ds_read_b128 v[88:91], v168
	v_add_f32_e32 v92, v130, v92
	v_add_f32_e32 v92, v131, v92
	v_add_f32_e32 v92, v132, v92
	v_add_f32_e32 v92, v133, v92
	v_cvt_pk_bf16_f32 v156, v128, v129
	v_cvt_pk_bf16_f32 v157, v130, v131
	s_waitcnt lgkmcnt(0)
	v_mfma_f32_32x32x16_bf16 v[96:111], v[84:87], v[88:91], 0
	ds_read_b64_tr_b16 v[128:129], v188 offset:28672
	ds_read_b64_tr_b16 v[130:131], v188 offset:29184
	ds_read_b128 v[84:87], v168
	v_add_f32_e32 v88, v134, v92
	v_add_f32_e32 v88, v135, v88
	v_add_f32_e32 v88, v136, v88
	v_add_f32_e32 v144, v137, v88
	v_cvt_pk_bf16_f32 v158, v132, v133
	v_cvt_pk_bf16_f32 v159, v134, v135
	s_waitcnt lgkmcnt(0)
	v_mfma_f32_32x32x16_bf16 v[80:95], v[80:83], v[84:87], 0
	ds_read_b64_tr_b16 v[132:133], v188 offset:25600
	ds_read_b64_tr_b16 v[134:135], v188 offset:26112
	ds_read_b128 v[190:193], v168 offset:1024
	v_add_f32_e32 v144, v138, v144
	v_add_f32_e32 v144, v139, v144
	v_add_f32_e32 v144, v140, v144
	v_add_f32_e32 v144, v141, v144
	v_cvt_pk_bf16_f32 v152, v136, v137
	v_cvt_pk_bf16_f32 v153, v138, v139
	s_waitcnt lgkmcnt(0)
	v_mfma_f32_32x32x16_bf16 v[96:111], v[164:167], v[190:193], v[96:111]
	ds_read_b64_tr_b16 v[136:137], v188 offset:29696
	ds_read_b64_tr_b16 v[138:139], v188 offset:30208
	ds_read_b128 v[164:167], v168 offset:1024
	v_add_f32_e32 v144, v142, v144
	v_add_f32_e32 v144, v143, v144
	v_add_f32_e32 v144, v64, v144
	v_add_f32_e32 v144, v65, v144
	v_cvt_pk_bf16_f32 v154, v140, v141
	v_cvt_pk_bf16_f32 v155, v142, v143
	s_waitcnt lgkmcnt(0)
	v_mfma_f32_32x32x16_bf16 v[80:95], v[124:127], v[164:167], v[80:95]
	ds_read_b64_tr_b16 v[124:125], v188 offset:26624
	ds_read_b64_tr_b16 v[126:127], v188 offset:27136
	ds_read_b128 v[140:143], v168 offset:2048
	v_add_f32_e32 v144, v66, v144
	v_add_f32_e32 v144, v67, v144
	v_add_f32_e32 v144, v68, v144
	v_add_f32_e32 v144, v69, v144
	v_cvt_pk_bf16_f32 v148, v64, v65
	v_cvt_pk_bf16_f32 v149, v66, v67
	s_waitcnt lgkmcnt(0)
	v_mfma_f32_32x32x16_bf16 v[96:111], v[160:163], v[140:143], v[96:111]
	ds_read_b64_tr_b16 v[190:191], v188 offset:30720
	ds_read_b64_tr_b16 v[192:193], v188 offset:31232
	ds_read_b128 v[64:67], v168 offset:2048
	v_add_f32_e32 v140, v70, v144
	v_add_f32_e32 v140, v71, v140
	v_add_f32_e32 v140, v72, v140
	v_add_f32_e32 v140, v73, v140
	v_cvt_pk_bf16_f32 v150, v68, v69
	v_cvt_pk_bf16_f32 v151, v70, v71
	s_waitcnt lgkmcnt(0)
	v_mfma_f32_32x32x16_bf16 v[80:95], v[116:119], v[64:67], v[80:95]
	ds_read_b64_tr_b16 v[116:117], v188 offset:27648
	ds_read_b64_tr_b16 v[118:119], v188 offset:28160
	ds_read_b128 v[64:67], v168 offset:3072
	v_add_f32_e32 v68, v74, v140
	v_add_f32_e32 v68, v75, v68
	v_add_f32_e32 v68, v76, v68
	v_add_f32_e32 v68, v77, v68
	v_cvt_pk_bf16_f32 v144, v72, v73
	v_cvt_pk_bf16_f32 v145, v74, v75
	s_waitcnt lgkmcnt(0)
	v_mfma_f32_32x32x16_bf16 v[96:111], v[120:123], v[64:67], v[96:111]
	ds_read_b64_tr_b16 v[72:73], v188 offset:31744
	ds_read_b64_tr_b16 v[74:75], v188 offset:32256
	ds_read_b128 v[64:67], v168 offset:3072
	v_add_f32_e32 v68, v78, v68
	v_add_f32_e32 v68, v79, v68
	v_add_f32_e32 v68, 0, v68
	v_cvt_pk_bf16_f32 v146, v76, v77
	v_cvt_pk_bf16_f32 v147, v78, v79
	s_waitcnt lgkmcnt(0)
; #define WAIT_BAR(N) asm volatile("s_waitcnt vmcnt(" #N ") lgkmcnt(0)\n\ts_barrier":::"memory")
;   #define RESC() do{ if(!NOMAX&&resc){ asm volatile("s_waitcnt lgkmcnt(0)":::"memory"); \
;       _Pragma("unroll") for(int d_=0;d_<2*VM;++d_) _Pragma("unroll") for(int r=0;r<16;++r)o[d_][r]*=wsf[crow(r,hi)]; } }while(0)
;   #define ROT() do{sl_prev=sl_cur;sl_cur=sl_next;sl_next=(sl_next==(NSLOT-1)*SLOTB)?0:sl_next+SLOTB;}while(0)
;   #define ENDW(tt) do{ if((tt)+3<NT){ if constexpr(VM==2){WAIT_BAR(3);}else{WAIT_BAR(2);} } else if((tt)+2<NT){ if constexpr(VM==2){WAIT_BAR(2);}else{WAIT_BAR(1);} } else {WAIT_BAR(0);} }while(0)
; template<int THRL,int VM,bool NOMAX> __device__ __forceinline__ void attn_unit(const bf16*Qb,const bf16*__restrict__ Kh,const bf16*__restrict__ Vh,bf16*Ob,const int NT,const int sp,float*wscr,char*shm){
;     ...
;   int t=1;
;   for(;t+5<NT;t+=2){
;     STEP(pB0,pB1,pA0,pA1,t,true,true,true);     if constexpr(VM==2){WAIT_BAR(3);}else{WAIT_BAR(2);} RESC(); ROT();
;     STEP(pA0,pA1,pB0,pB1,t+1,true,true,true);   if constexpr(VM==2){WAIT_BAR(3);}else{WAIT_BAR(2);} RESC(); ROT();
;   }
;     ...
;   for(;t+1<NT;t+=2){
;     STEP(pB0,pB1,pA0,pA1,t,(t+3<NT),(t+1<NT),(t+1<NT));       ENDW(t);   RESC(); ROT();
;     STEP(pA0,pA1,pB0,pB1,t+1,(t+4<NT),(t+2<NT),(t+2<NT));     ENDW(t+1); RESC(); ROT();
	v_mfma_f32_32x32x16_bf16 v[80:95], v[112:115], v[64:67], v[80:95]
	v_lshl_add_u64 v[64:65], v[170:171], 0, s[60:61]
	s_add_i32 s17, s85, 0xe000
	s_mov_b32 s86, m0
	s_mov_b32 m0, s17
	s_nop 0
	global_load_lds_dwordx4 v[64:65], off
	s_mov_b32 m0, s86
	v_lshl_add_u64 v[64:65], v[172:173], 0, s[60:61]
	s_add_i32 s85, s85, 0x10000
	s_mov_b32 s17, m0
	s_mov_b32 m0, s85
	s_nop 0
	global_load_lds_dwordx4 v[64:65], off
	s_mov_b32 m0, s17
	v_add_f32_e32 v174, v198, v68
	v_mfma_f32_32x32x16_bf16 v[48:63], v[156:159], v[178:181], v[48:63]
	ds_read_b64_tr_b16 v[76:77], v188 offset:32768
	ds_read_b64_tr_b16 v[78:79], v188 offset:33280
	v_exp_f32_e32 v96, v96
	v_exp_f32_e32 v97, v97
	v_mfma_f32_32x32x16_bf16 v[32:47], v[156:159], v[128:131], v[32:47]
	ds_read_b64_tr_b16 v[112:113], v188 offset:36864
	ds_read_b64_tr_b16 v[114:115], v188 offset:37376
	v_exp_f32_e32 v98, v98
	v_exp_f32_e32 v99, v99
	ds_read_b128 v[68:71], v189 offset:16384
	ds_read_b128 v[64:67], v189 offset:16896
	v_mfma_f32_32x32x16_bf16 v[48:63], v[152:155], v[132:135], v[48:63]
	ds_read_b64_tr_b16 v[120:121], v188 offset:33792
	ds_read_b64_tr_b16 v[122:123], v188 offset:34304
	v_exp_f32_e32 v100, v100
	v_exp_f32_e32 v101, v101
	ds_read_b128 v[164:167], v189 offset:18432
	ds_read_b128 v[140:143], v189 offset:18944
	v_mfma_f32_32x32x16_bf16 v[32:47], v[152:155], v[136:139], v[32:47]
	ds_read_b64_tr_b16 v[178:179], v188 offset:37888
	ds_read_b64_tr_b16 v[180:181], v188 offset:38400
	v_exp_f32_e32 v102, v102
	v_exp_f32_e32 v103, v103
	ds_read_b128 v[160:163], v189 offset:20480
	ds_read_b128 v[132:135], v189 offset:20992
	v_mfma_f32_32x32x16_bf16 v[48:63], v[148:151], v[124:127], v[48:63]
	ds_read_b64_tr_b16 v[194:195], v188 offset:34816
	ds_read_b64_tr_b16 v[196:197], v188 offset:35328
	v_exp_f32_e32 v104, v104
	v_exp_f32_e32 v105, v105
	ds_read_b128 v[136:139], v189 offset:22528
	ds_read_b128 v[128:131], v189 offset:23040
	v_mfma_f32_32x32x16_bf16 v[32:47], v[148:151], v[190:193], v[32:47]
	ds_read_b64_tr_b16 v[124:125], v188 offset:38912
	ds_read_b64_tr_b16 v[126:127], v188 offset:39424
	v_exp_f32_e32 v106, v106
	v_exp_f32_e32 v107, v107
	v_mfma_f32_32x32x16_bf16 v[48:63], v[144:147], v[116:119], v[48:63]
	ds_read_b64_tr_b16 v[190:191], v188 offset:35840
	ds_read_b64_tr_b16 v[192:193], v188 offset:36352
	v_exp_f32_e32 v108, v108
	v_exp_f32_e32 v109, v109
	v_mfma_f32_32x32x16_bf16 v[32:47], v[144:147], v[72:75], v[32:47]
	ds_read_b64_tr_b16 v[116:117], v188 offset:39936
	ds_read_b64_tr_b16 v[118:119], v188 offset:40448
	v_exp_f32_e32 v110, v110
	v_exp_f32_e32 v111, v111
	s_waitcnt lgkmcnt(14)
	v_mfma_f32_32x32x16_bf16 v[16:31], v[156:159], v[76:79], v[16:31]
	v_exp_f32_e32 v80, v80
	v_exp_f32_e32 v81, v81
	v_mfma_f32_32x32x16_bf16 v[0:15], v[156:159], v[112:115], v[0:15]
	v_exp_f32_e32 v82, v82
	v_exp_f32_e32 v83, v83
	v_mfma_f32_32x32x16_bf16 v[16:31], v[152:155], v[120:123], v[16:31]
	v_exp_f32_e32 v84, v84
	v_exp_f32_e32 v85, v85
	s_waitcnt lgkmcnt(12)
	v_mfma_f32_32x32x16_bf16 v[0:15], v[152:155], v[178:181], v[0:15]
	v_exp_f32_e32 v86, v86
	v_exp_f32_e32 v87, v87
	s_waitcnt lgkmcnt(8)
	v_mfma_f32_32x32x16_bf16 v[16:31], v[148:151], v[194:197], v[16:31]
	v_exp_f32_e32 v88, v88
	v_exp_f32_e32 v89, v89
	s_waitcnt lgkmcnt(4)
	v_mfma_f32_32x32x16_bf16 v[0:15], v[148:151], v[124:127], v[0:15]
	v_exp_f32_e32 v90, v90
	v_exp_f32_e32 v91, v91
	s_waitcnt lgkmcnt(2)
	v_mfma_f32_32x32x16_bf16 v[16:31], v[144:147], v[190:193], v[16:31]
	v_exp_f32_e32 v92, v92
	v_exp_f32_e32 v93, v93
	s_waitcnt lgkmcnt(0)
	v_mfma_f32_32x32x16_bf16 v[0:15], v[144:147], v[116:119], v[0:15]
	v_exp_f32_e32 v94, v94
	v_exp_f32_e32 v95, v95
	s_waitcnt vmcnt(2) lgkmcnt(0)
	s_barrier
	ds_read_b64_tr_b16 v[178:179], v188 offset:40960
	ds_read_b64_tr_b16 v[180:181], v188 offset:41472
	v_add_f32_e32 v76, v96, v97
	ds_read_b128 v[72:75], v168
	v_add_f32_e32 v76, v98, v76
	v_add_f32_e32 v76, v99, v76
	v_add_f32_e32 v76, v100, v76
	v_add_f32_e32 v76, v101, v76
	v_cvt_pk_bf16_f32 v156, v96, v97
	v_cvt_pk_bf16_f32 v157, v98, v99
	s_waitcnt lgkmcnt(0)
	v_mfma_f32_32x32x16_bf16 v[112:127], v[68:71], v[72:75], 0
	ds_read_b64_tr_b16 v[96:97], v188 offset:45056
	ds_read_b64_tr_b16 v[98:99], v188 offset:45568
	ds_read_b128 v[68:71], v168
	v_add_f32_e32 v72, v102, v76
	v_add_f32_e32 v72, v103, v72
	v_add_f32_e32 v72, v104, v72
	v_add_f32_e32 v144, v105, v72
	s_waitcnt lgkmcnt(0)
	v_mfma_f32_32x32x16_bf16 v[64:79], v[64:67], v[68:71], 0
	v_cvt_pk_bf16_f32 v158, v100, v101
	v_cvt_pk_bf16_f32 v159, v102, v103
	ds_read_b64_tr_b16 v[100:101], v188 offset:41984
	ds_read_b64_tr_b16 v[102:103], v188 offset:42496
	ds_read_b128 v[190:193], v168 offset:1024
	v_add_f32_e32 v144, v106, v144
	v_add_f32_e32 v144, v107, v144
	v_add_f32_e32 v144, v108, v144
	v_add_f32_e32 v144, v109, v144
	v_cvt_pk_bf16_f32 v152, v104, v105
	v_cvt_pk_bf16_f32 v153, v106, v107
	s_waitcnt lgkmcnt(0)
	v_mfma_f32_32x32x16_bf16 v[112:127], v[164:167], v[190:193], v[112:127]
	ds_read_b64_tr_b16 v[104:105], v188 offset:46080
	ds_read_b64_tr_b16 v[106:107], v188 offset:46592
	ds_read_b128 v[164:167], v168 offset:1024
	v_add_f32_e32 v144, v110, v144
	v_add_f32_e32 v144, v111, v144
	v_add_f32_e32 v144, v80, v144
	v_add_f32_e32 v144, v81, v144
	s_waitcnt lgkmcnt(0)
	v_mfma_f32_32x32x16_bf16 v[64:79], v[140:143], v[164:167], v[64:79]
	v_cvt_pk_bf16_f32 v154, v108, v109
	v_cvt_pk_bf16_f32 v155, v110, v111
	ds_read_b64_tr_b16 v[108:109], v188 offset:43008
	ds_read_b64_tr_b16 v[110:111], v188 offset:43520
	ds_read_b128 v[140:143], v168 offset:2048
	v_add_f32_e32 v144, v82, v144
	v_add_f32_e32 v144, v83, v144
	v_add_f32_e32 v144, v84, v144
	v_add_f32_e32 v144, v85, v144
	v_cvt_pk_bf16_f32 v148, v80, v81
	v_cvt_pk_bf16_f32 v149, v82, v83
	s_waitcnt lgkmcnt(0)
; #define WAIT_BAR(N) asm volatile("s_waitcnt vmcnt(" #N ") lgkmcnt(0)\n\ts_barrier":::"memory")
;   #define RESC() do{ if(!NOMAX&&resc){ asm volatile("s_waitcnt lgkmcnt(0)":::"memory"); \
;       _Pragma("unroll") for(int d_=0;d_<2*VM;++d_) _Pragma("unroll") for(int r=0;r<16;++r)o[d_][r]*=wsf[crow(r,hi)]; } }while(0)
;   #define ROT() do{sl_prev=sl_cur;sl_cur=sl_next;sl_next=(sl_next==(NSLOT-1)*SLOTB)?0:sl_next+SLOTB;}while(0)
;   #define ENDW(tt) do{ if((tt)+3<NT){ if constexpr(VM==2){WAIT_BAR(3);}else{WAIT_BAR(2);} } else if((tt)+2<NT){ if constexpr(VM==2){WAIT_BAR(2);}else{WAIT_BAR(1);} } else {WAIT_BAR(0);} }while(0)
; template<int THRL,int VM,bool NOMAX> __device__ __forceinline__ void attn_unit(const bf16*Qb,const bf16*__restrict__ Kh,const bf16*__restrict__ Vh,bf16*Ob,const int NT,const int sp,float*wscr,char*shm){
;     ...
;   int t=1;
;   for(;t+5<NT;t+=2){
;     STEP(pB0,pB1,pA0,pA1,t,true,true,true);     if constexpr(VM==2){WAIT_BAR(3);}else{WAIT_BAR(2);} RESC(); ROT();
;     STEP(pA0,pA1,pB0,pB1,t+1,true,true,true);   if constexpr(VM==2){WAIT_BAR(3);}else{WAIT_BAR(2);} RESC(); ROT();
;   }
;     ...
;   for(;t+1<NT;t+=2){
;     STEP(pB0,pB1,pA0,pA1,t,(t+3<NT),(t+1<NT),(t+1<NT));       ENDW(t);   RESC(); ROT();
;     STEP(pA0,pA1,pB0,pB1,t+1,(t+4<NT),(t+2<NT),(t+2<NT));     ENDW(t+1); RESC(); ROT();
	v_mfma_f32_32x32x16_bf16 v[112:127], v[160:163], v[140:143], v[112:127]
	ds_read_b64_tr_b16 v[190:191], v188 offset:47104
	ds_read_b64_tr_b16 v[192:193], v188 offset:47616
	ds_read_b128 v[80:83], v168 offset:2048
	v_add_f32_e32 v140, v86, v144
	v_add_f32_e32 v140, v87, v140
	v_add_f32_e32 v140, v88, v140
	v_add_f32_e32 v140, v89, v140
	s_waitcnt lgkmcnt(0)
	v_mfma_f32_32x32x16_bf16 v[64:79], v[132:135], v[80:83], v[64:79]
	v_cvt_pk_bf16_f32 v150, v84, v85
	v_cvt_pk_bf16_f32 v151, v86, v87
	ds_read_b64_tr_b16 v[84:85], v188 offset:44032
	ds_read_b64_tr_b16 v[86:87], v188 offset:44544
	ds_read_b128 v[80:83], v168 offset:3072
	v_add_f32_e32 v132, v90, v140
	v_add_f32_e32 v132, v91, v132
	v_add_f32_e32 v132, v92, v132
	v_add_f32_e32 v132, v93, v132
	v_cvt_pk_bf16_f32 v144, v88, v89
	v_cvt_pk_bf16_f32 v145, v90, v91
	s_waitcnt lgkmcnt(0)
	v_mfma_f32_32x32x16_bf16 v[112:127], v[136:139], v[80:83], v[112:127]
	ds_read_b64_tr_b16 v[88:89], v188 offset:48128
	ds_read_b64_tr_b16 v[90:91], v188 offset:48640
	ds_read_b128 v[80:83], v168 offset:3072
	v_add_f32_e32 v132, v94, v132
	v_add_f32_e32 v132, v95, v132
	v_add_f32_e32 v132, 0, v132
	v_cvt_pk_bf16_f32 v146, v92, v93
	s_waitcnt lgkmcnt(0)
	v_mfma_f32_32x32x16_bf16 v[64:79], v[128:131], v[80:83], v[64:79]
	v_cvt_pk_bf16_f32 v147, v94, v95
	v_lshl_add_u64 v[80:81], v[170:171], 0, s[64:65]
	s_mov_b32 s17, m0
	s_mov_b32 m0, s16
	s_nop 0
	global_load_lds_dwordx4 v[80:81], off
	s_mov_b32 m0, s17
	v_lshl_add_u64 v[80:81], v[172:173], 0, s[64:65]
	s_mov_b32 s16, m0
	s_mov_b32 m0, s35
	s_nop 0
	global_load_lds_dwordx4 v[80:81], off
	s_mov_b32 m0, s16
	v_add_f32_e32 v174, v174, v132
	v_mfma_f32_32x32x16_bf16 v[48:63], v[156:159], v[178:181], v[48:63]
	ds_read_b64_tr_b16 v[92:93], v188 offset:49152
	ds_read_b64_tr_b16 v[94:95], v188 offset:49664
	v_exp_f32_e32 v112, v112
	v_exp_f32_e32 v113, v113
	v_mfma_f32_32x32x16_bf16 v[32:47], v[156:159], v[96:99], v[32:47]
	ds_read_b64_tr_b16 v[170:171], v188 offset:53248
	ds_read_b64_tr_b16 v[172:173], v188 offset:53760
	v_exp_f32_e32 v114, v114
	v_exp_f32_e32 v115, v115
	ds_read_b128 v[80:83], v189
	ds_read_b128 v[96:99], v189 offset:512
	v_mfma_f32_32x32x16_bf16 v[48:63], v[152:155], v[100:103], v[48:63]
	ds_read_b64_tr_b16 v[178:179], v188 offset:50176
	ds_read_b64_tr_b16 v[180:181], v188 offset:50688
	v_exp_f32_e32 v116, v116
	v_exp_f32_e32 v117, v117
	ds_read_b128 v[164:167], v189 offset:2048
	ds_read_b128 v[140:143], v189 offset:2560
	v_mfma_f32_32x32x16_bf16 v[32:47], v[152:155], v[104:107], v[32:47]
	ds_read_b64_tr_b16 v[100:101], v188 offset:54272
	ds_read_b64_tr_b16 v[102:103], v188 offset:54784
	v_exp_f32_e32 v118, v118
	v_exp_f32_e32 v119, v119
	ds_read_b128 v[160:163], v189 offset:4096
	ds_read_b128 v[132:135], v189 offset:4608
	v_mfma_f32_32x32x16_bf16 v[48:63], v[148:151], v[108:111], v[48:63]
	ds_read_b64_tr_b16 v[104:105], v188 offset:51200
	ds_read_b64_tr_b16 v[106:107], v188 offset:51712
	v_exp_f32_e32 v120, v120
	v_exp_f32_e32 v121, v121
	ds_read_b128 v[136:139], v189 offset:6144
	ds_read_b128 v[128:131], v189 offset:6656
	v_mfma_f32_32x32x16_bf16 v[32:47], v[148:151], v[190:193], v[32:47]
	ds_read_b64_tr_b16 v[108:109], v188 offset:55296
	ds_read_b64_tr_b16 v[110:111], v188 offset:55808
	v_exp_f32_e32 v122, v122
	v_exp_f32_e32 v123, v123
	v_mfma_f32_32x32x16_bf16 v[48:63], v[144:147], v[84:87], v[48:63]
	ds_read_b64_tr_b16 v[190:191], v188 offset:52224
	ds_read_b64_tr_b16 v[192:193], v188 offset:52736
	v_exp_f32_e32 v124, v124
	v_exp_f32_e32 v125, v125
	v_mfma_f32_32x32x16_bf16 v[32:47], v[144:147], v[88:91], v[32:47]
	ds_read_b64_tr_b16 v[84:85], v188 offset:56320
	ds_read_b64_tr_b16 v[86:87], v188 offset:56832
	v_exp_f32_e32 v126, v126
	v_exp_f32_e32 v127, v127
	s_waitcnt lgkmcnt(14)
	v_mfma_f32_32x32x16_bf16 v[16:31], v[156:159], v[92:95], v[16:31]
	v_exp_f32_e32 v64, v64
	v_exp_f32_e32 v65, v65
	v_mfma_f32_32x32x16_bf16 v[0:15], v[156:159], v[170:173], v[0:15]
	v_exp_f32_e32 v66, v66
	v_exp_f32_e32 v67, v67
	v_mfma_f32_32x32x16_bf16 v[16:31], v[152:155], v[178:181], v[16:31]
	v_exp_f32_e32 v68, v68
	v_exp_f32_e32 v69, v69
	s_waitcnt lgkmcnt(12)
	v_mfma_f32_32x32x16_bf16 v[0:15], v[152:155], v[100:103], v[0:15]
	v_exp_f32_e32 v70, v70
	v_exp_f32_e32 v71, v71
	s_waitcnt lgkmcnt(8)
	v_mfma_f32_32x32x16_bf16 v[16:31], v[148:151], v[104:107], v[16:31]
	v_exp_f32_e32 v72, v72
	v_exp_f32_e32 v73, v73
	s_waitcnt lgkmcnt(4)
	v_mfma_f32_32x32x16_bf16 v[0:15], v[148:151], v[108:111], v[0:15]
	v_exp_f32_e32 v74, v74
	v_exp_f32_e32 v75, v75
	s_waitcnt lgkmcnt(2)
	v_mfma_f32_32x32x16_bf16 v[16:31], v[144:147], v[190:193], v[16:31]
	v_exp_f32_e32 v76, v76
	v_exp_f32_e32 v77, v77
	s_waitcnt lgkmcnt(0)
	v_mfma_f32_32x32x16_bf16 v[0:15], v[144:147], v[84:87], v[0:15]
	v_exp_f32_e32 v78, v78
	v_exp_f32_e32 v79, v79
	s_waitcnt vmcnt(0) lgkmcnt(0)
	s_barrier
; #define WAIT_BAR(N) asm volatile("s_waitcnt vmcnt(" #N ") lgkmcnt(0)\n\ts_barrier":::"memory")
;   #define RESC() do{ if(!NOMAX&&resc){ asm volatile("s_waitcnt lgkmcnt(0)":::"memory"); \
;       _Pragma("unroll") for(int d_=0;d_<2*VM;++d_) _Pragma("unroll") for(int r=0;r<16;++r)o[d_][r]*=wsf[crow(r,hi)]; } }while(0)
;   #define ROT() do{sl_prev=sl_cur;sl_cur=sl_next;sl_next=(sl_next==(NSLOT-1)*SLOTB)?0:sl_next+SLOTB;}while(0)
;   #define ENDW(tt) do{ if((tt)+3<NT){ if constexpr(VM==2){WAIT_BAR(3);}else{WAIT_BAR(2);} } else if((tt)+2<NT){ if constexpr(VM==2){WAIT_BAR(2);}else{WAIT_BAR(1);} } else {WAIT_BAR(0);} }while(0)
; template<int THRL,int VM,bool NOMAX> __device__ __forceinline__ void attn_unit(const bf16*Qb,const bf16*__restrict__ Kh,const bf16*__restrict__ Vh,bf16*Ob,const int NT,const int sp,float*wscr,char*shm){
;     ...
;   int t=1;
;   for(;t+5<NT;t+=2){
;     STEP(pB0,pB1,pA0,pA1,t,true,true,true);     if constexpr(VM==2){WAIT_BAR(3);}else{WAIT_BAR(2);} RESC(); ROT();
;     STEP(pA0,pA1,pB0,pB1,t+1,true,true,true);   if constexpr(VM==2){WAIT_BAR(3);}else{WAIT_BAR(2);} RESC(); ROT();
;   }
;     ...
;   for(;t+1<NT;t+=2){
;     STEP(pB0,pB1,pA0,pA1,t,(t+3<NT),(t+1<NT),(t+1<NT));       ENDW(t);   RESC(); ROT();
;     STEP(pA0,pA1,pB0,pB1,t+1,(t+4<NT),(t+2<NT),(t+2<NT));     ENDW(t+1); RESC(); ROT();
;   }
;   STEP(pB0,pB1,pA0,pA1,NT-1,false,false,false); RESC();
	ds_read_b64_tr_b16 v[170:171], v188 offset:57344
	ds_read_b64_tr_b16 v[172:173], v188 offset:57856
	v_add_f32_e32 v88, v112, v113
	ds_read_b128 v[84:87], v168
	v_add_f32_e32 v88, v114, v88
	v_add_f32_e32 v88, v115, v88
	v_add_f32_e32 v88, v116, v88
	v_add_f32_e32 v104, v117, v88
	v_cvt_pk_bf16_f32 v156, v112, v113
	v_cvt_pk_bf16_f32 v157, v114, v115
	s_waitcnt lgkmcnt(0)
	v_mfma_f32_32x32x16_bf16 v[80:95], v[80:83], v[84:87], 0
	ds_read_b64_tr_b16 v[112:113], v188 offset:61440
	ds_read_b64_tr_b16 v[114:115], v188 offset:61952
	ds_read_b128 v[100:103], v168
	v_add_f32_e32 v104, v118, v104
	v_add_f32_e32 v104, v119, v104
	v_add_f32_e32 v104, v120, v104
	v_add_f32_e32 v144, v121, v104
	v_cvt_pk_bf16_f32 v158, v116, v117
	v_cvt_pk_bf16_f32 v159, v118, v119
	s_waitcnt lgkmcnt(0)
	v_mfma_f32_32x32x16_bf16 v[96:111], v[96:99], v[100:103], 0
	ds_read_b64_tr_b16 v[116:117], v188 offset:58368
	ds_read_b64_tr_b16 v[118:119], v188 offset:58880
	ds_read_b128 v[178:181], v168 offset:1024
	v_add_f32_e32 v144, v122, v144
	v_add_f32_e32 v144, v123, v144
	v_add_f32_e32 v144, v124, v144
	v_add_f32_e32 v144, v125, v144
	v_cvt_pk_bf16_f32 v152, v120, v121
	v_cvt_pk_bf16_f32 v153, v122, v123
	s_waitcnt lgkmcnt(0)
	v_mfma_f32_32x32x16_bf16 v[80:95], v[164:167], v[178:181], v[80:95]
	ds_read_b64_tr_b16 v[120:121], v188 offset:62464
	ds_read_b64_tr_b16 v[122:123], v188 offset:62976
	ds_read_b128 v[164:167], v168 offset:1024
	v_add_f32_e32 v144, v126, v144
	v_add_f32_e32 v144, v127, v144
	v_add_f32_e32 v144, v64, v144
	v_add_f32_e32 v144, v65, v144
	v_cvt_pk_bf16_f32 v154, v124, v125
	v_cvt_pk_bf16_f32 v155, v126, v127
	s_waitcnt lgkmcnt(0)
	v_mfma_f32_32x32x16_bf16 v[96:111], v[140:143], v[164:167], v[96:111]
	ds_read_b64_tr_b16 v[124:125], v188 offset:59392
	ds_read_b64_tr_b16 v[126:127], v188 offset:59904
	ds_read_b128 v[140:143], v168 offset:2048
	v_add_f32_e32 v144, v66, v144
	v_add_f32_e32 v144, v67, v144
	v_add_f32_e32 v144, v68, v144
	v_add_f32_e32 v144, v69, v144
	v_cvt_pk_bf16_f32 v148, v64, v65
	v_cvt_pk_bf16_f32 v149, v66, v67
	s_waitcnt lgkmcnt(0)
	v_mfma_f32_32x32x16_bf16 v[80:95], v[160:163], v[140:143], v[80:95]
	ds_read_b64_tr_b16 v[64:65], v188 offset:63488
	ds_read_b64_tr_b16 v[66:67], v188 offset:64000
	ds_read_b128 v[140:143], v168 offset:2048
	v_add_f32_e32 v144, v70, v144
	v_add_f32_e32 v144, v71, v144
	v_add_f32_e32 v144, v72, v144
	v_add_f32_e32 v144, v73, v144
	v_cvt_pk_bf16_f32 v150, v68, v69
	v_cvt_pk_bf16_f32 v151, v70, v71
	s_waitcnt lgkmcnt(0)
	v_mfma_f32_32x32x16_bf16 v[96:111], v[132:135], v[140:143], v[96:111]
	ds_read_b64_tr_b16 v[68:69], v188 offset:60416
	ds_read_b64_tr_b16 v[70:71], v188 offset:60928
	ds_read_b128 v[132:135], v168 offset:3072
	v_add_f32_e32 v140, v74, v144
	v_add_f32_e32 v140, v75, v140
	v_add_f32_e32 v140, v76, v140
	v_add_f32_e32 v140, v77, v140
	v_cvt_pk_bf16_f32 v144, v72, v73
	v_cvt_pk_bf16_f32 v145, v74, v75
	s_waitcnt lgkmcnt(0)
	v_mfma_f32_32x32x16_bf16 v[80:95], v[136:139], v[132:135], v[80:95]
	ds_read_b64_tr_b16 v[72:73], v188 offset:64512
	ds_read_b64_tr_b16 v[74:75], v188 offset:65024
	ds_read_b128 v[132:135], v168 offset:3072
	v_add_f32_e32 v136, v78, v140
	v_add_f32_e32 v136, v79, v136
	v_add_f32_e32 v136, 0, v136
	v_cvt_pk_bf16_f32 v146, v76, v77
	v_cvt_pk_bf16_f32 v147, v78, v79
	s_waitcnt lgkmcnt(0)
	v_mfma_f32_32x32x16_bf16 v[96:111], v[128:131], v[132:135], v[96:111]
	v_mfma_f32_32x32x16_bf16 v[48:63], v[156:159], v[170:173], v[48:63]
	ds_read_b64_tr_b16 v[76:77], v177 offset:40960
	ds_read_b64_tr_b16 v[78:79], v177 offset:41472
	v_exp_f32_e32 v80, v80
	v_exp_f32_e32 v81, v81
	v_mfma_f32_32x32x16_bf16 v[32:47], v[156:159], v[112:115], v[32:47]
	ds_read_b64_tr_b16 v[128:129], v177 offset:45056
	ds_read_b64_tr_b16 v[130:131], v177 offset:45568
	v_exp_f32_e32 v82, v82
	v_exp_f32_e32 v83, v83
	v_mfma_f32_32x32x16_bf16 v[48:63], v[152:155], v[116:119], v[48:63]
	ds_read_b64_tr_b16 v[112:113], v177 offset:41984
	ds_read_b64_tr_b16 v[114:115], v177 offset:42496
	v_exp_f32_e32 v84, v84
	v_exp_f32_e32 v85, v85
	v_mfma_f32_32x32x16_bf16 v[32:47], v[152:155], v[120:123], v[32:47]
	ds_read_b64_tr_b16 v[116:117], v177 offset:46080
	ds_read_b64_tr_b16 v[118:119], v177 offset:46592
	v_exp_f32_e32 v86, v86
	v_exp_f32_e32 v87, v87
	v_mfma_f32_32x32x16_bf16 v[48:63], v[148:151], v[124:127], v[48:63]
	ds_read_b64_tr_b16 v[120:121], v177 offset:43008
	ds_read_b64_tr_b16 v[122:123], v177 offset:43520
	v_exp_f32_e32 v88, v88
	v_exp_f32_e32 v89, v89
	v_mfma_f32_32x32x16_bf16 v[32:47], v[148:151], v[64:67], v[32:47]
	ds_read_b64_tr_b16 v[124:125], v177 offset:47104
	ds_read_b64_tr_b16 v[126:127], v177 offset:47616
	v_exp_f32_e32 v90, v90
	v_exp_f32_e32 v91, v91
	v_mfma_f32_32x32x16_bf16 v[48:63], v[144:147], v[68:71], v[48:63]
	ds_read_b64_tr_b16 v[64:65], v177 offset:44032
	ds_read_b64_tr_b16 v[66:67], v177 offset:44544
	v_exp_f32_e32 v92, v92
	v_exp_f32_e32 v93, v93
	v_mfma_f32_32x32x16_bf16 v[32:47], v[144:147], v[72:75], v[32:47]
	ds_read_b64_tr_b16 v[68:69], v177 offset:48128
	ds_read_b64_tr_b16 v[70:71], v177 offset:48640
	v_exp_f32_e32 v94, v94
	v_exp_f32_e32 v95, v95
	s_waitcnt lgkmcnt(14)
	v_mfma_f32_32x32x16_bf16 v[16:31], v[156:159], v[76:79], v[16:31]
	v_exp_f32_e32 v96, v96
	v_exp_f32_e32 v97, v97
	s_waitcnt lgkmcnt(12)
; #define SBAR() __builtin_amdgcn_sched_barrier(0)
; #define WAIT_BAR(N) asm volatile("s_waitcnt vmcnt(" #N ") lgkmcnt(0)\n\ts_barrier":::"memory")
;   #define RESC() do{ if(!NOMAX&&resc){ asm volatile("s_waitcnt lgkmcnt(0)":::"memory"); \
;       _Pragma("unroll") for(int d_=0;d_<2*VM;++d_) _Pragma("unroll") for(int r=0;r<16;++r)o[d_][r]*=wsf[crow(r,hi)]; } }while(0)
;   #define ROT() do{sl_prev=sl_cur;sl_cur=sl_next;sl_next=(sl_next==(NSLOT-1)*SLOTB)?0:sl_next+SLOTB;}while(0)
;   #define PKW(P,B) cvtpk_s(P[B],P[B+1])
;   #define ENDW(tt) do{ if((tt)+3<NT){ if constexpr(VM==2){WAIT_BAR(3);}else{WAIT_BAR(2);} } else if((tt)+2<NT){ if constexpr(VM==2){WAIT_BAR(2);}else{WAIT_BAR(1);} } else {WAIT_BAR(0);} }while(0)
; template<int THRL,int VM,bool NOMAX> __device__ __forceinline__ void attn_unit(const bf16*Qb,const bf16*__restrict__ Kh,const bf16*__restrict__ Vh,bf16*Ob,const int NT,const int sp,float*wscr,char*shm){
;     ...
;   int t=1;
;   for(;t+5<NT;t+=2){
;     STEP(pB0,pB1,pA0,pA1,t,true,true,true);     if constexpr(VM==2){WAIT_BAR(3);}else{WAIT_BAR(2);} RESC(); ROT();
;     STEP(pA0,pA1,pB0,pB1,t+1,true,true,true);   if constexpr(VM==2){WAIT_BAR(3);}else{WAIT_BAR(2);} RESC(); ROT();
;   }
;     ...
;   for(;t+1<NT;t+=2){
;     STEP(pB0,pB1,pA0,pA1,t,(t+3<NT),(t+1<NT),(t+1<NT));       ENDW(t);   RESC(); ROT();
;     STEP(pA0,pA1,pB0,pB1,t+1,(t+4<NT),(t+2<NT),(t+2<NT));     ENDW(t+1); RESC(); ROT();
;   }
;   STEP(pB0,pB1,pA0,pA1,NT-1,false,false,false); RESC();
;   { float sacc=pB0[0]+pB0[1]; _Pragma("unroll") for(int r=2;r<16;++r)sacc+=pB0[r]; _Pragma("unroll") for(int r=0;r<16;++r)sacc+=pB1[r]; l_reg+=sacc;
;     pw0=(u32x4){PKW(pB0,0),PKW(pB0,2),PKW(pB0,4),PKW(pB0,6)};pw1=(u32x4){PKW(pB0,8),PKW(pB0,10),PKW(pB0,12),PKW(pB0,14)};pw2=(u32x4){PKW(pB1,0),PKW(pB1,2),PKW(pB1,4),PKW(pB1,6)};pw3=(u32x4){PKW(pB1,8),PKW(pB1,10),PKW(pB1,12),PKW(pB1,14)};
;     SBAR(); pv(o,vb0+VM*sl_cur,PAF(0),PAF(1),PAF(2),PAF(3)); if constexpr(VM==2) pv(o+2,vb0+VM*sl_cur+8192,PAF(0),PAF(1),PAF(2),PAF(3)); }
;     ...
;   {auto rr=__builtin_amdgcn_permlane32_swap(__float_as_uint(l_reg),__float_as_uint(l_reg),false,false);l_reg=__uint_as_float(rr[0])+__uint_as_float(rr[1]);}
;   if(hi==0)wsf[32+r32]=l_reg;asm volatile("s_waitcnt lgkmcnt(0)":::"memory");
	v_mfma_f32_32x32x16_bf16 v[0:15], v[156:159], v[128:131], v[0:15]
	v_exp_f32_e32 v98, v98
	v_exp_f32_e32 v99, v99
	s_waitcnt lgkmcnt(10)
	v_mfma_f32_32x32x16_bf16 v[16:31], v[152:155], v[112:115], v[16:31]
	v_exp_f32_e32 v100, v100
	v_exp_f32_e32 v101, v101
	s_waitcnt lgkmcnt(8)
	v_mfma_f32_32x32x16_bf16 v[0:15], v[152:155], v[116:119], v[0:15]
	v_exp_f32_e32 v102, v102
	v_exp_f32_e32 v103, v103
	s_waitcnt lgkmcnt(6)
	v_mfma_f32_32x32x16_bf16 v[16:31], v[148:151], v[120:123], v[16:31]
	v_exp_f32_e32 v104, v104
	v_exp_f32_e32 v105, v105
	s_waitcnt lgkmcnt(4)
	v_mfma_f32_32x32x16_bf16 v[0:15], v[148:151], v[124:127], v[0:15]
	v_exp_f32_e32 v106, v106
	v_exp_f32_e32 v107, v107
	s_waitcnt lgkmcnt(2)
	v_mfma_f32_32x32x16_bf16 v[16:31], v[144:147], v[64:67], v[16:31]
	v_exp_f32_e32 v108, v108
	v_exp_f32_e32 v109, v109
	s_waitcnt lgkmcnt(0)
	v_mfma_f32_32x32x16_bf16 v[0:15], v[144:147], v[68:71], v[0:15]
	v_exp_f32_e32 v110, v110
	v_exp_f32_e32 v111, v111
	v_add_f32_e32 v64, v80, v81
	v_add_f32_e32 v64, v82, v64
	v_add_f32_e32 v64, v83, v64
	v_add_f32_e32 v64, v84, v64
	v_add_f32_e32 v64, v85, v64
	v_add_f32_e32 v64, v86, v64
	v_add_f32_e32 v64, v87, v64
	v_add_f32_e32 v64, v88, v64
	v_add_f32_e32 v64, v89, v64
	v_add_f32_e32 v64, v90, v64
	v_add_f32_e32 v64, v91, v64
	v_add_f32_e32 v64, v92, v64
	v_add_f32_e32 v64, v93, v64
	v_add_f32_e32 v64, v94, v64
	v_add_f32_e32 v64, v95, v64
	v_add_f32_e32 v64, v64, v96
	v_add_f32_e32 v64, v97, v64
	v_add_f32_e32 v64, v98, v64
	v_add_f32_e32 v64, v99, v64
	v_add_f32_e32 v64, v100, v64
	v_add_f32_e32 v64, v101, v64
	v_add_f32_e32 v64, v102, v64
	v_add_f32_e32 v64, v103, v64
	v_add_f32_e32 v64, v104, v64
	v_add_f32_e32 v64, v105, v64
	v_add_f32_e32 v64, v106, v64
	v_add_f32_e32 v64, v107, v64
	v_add_f32_e32 v64, v108, v64
	v_add_f32_e32 v64, v109, v64
	v_add_f32_e32 v64, v110, v64
	v_add_f32_e32 v64, v111, v64
	v_add_f32_e32 v65, v174, v136
	v_add_f32_e32 v64, v65, v64
	v_cvt_pk_bf16_f32 v66, v80, v81
	v_cvt_pk_bf16_f32 v67, v82, v83
	v_cvt_pk_bf16_f32 v68, v84, v85
	v_cvt_pk_bf16_f32 v69, v86, v87
	v_cvt_pk_bf16_f32 v70, v88, v89
	v_cvt_pk_bf16_f32 v71, v90, v91
	v_cvt_pk_bf16_f32 v72, v92, v93
	v_cvt_pk_bf16_f32 v73, v94, v95
	v_cvt_pk_bf16_f32 v74, v96, v97
	v_cvt_pk_bf16_f32 v75, v98, v99
	v_cvt_pk_bf16_f32 v76, v100, v101
	v_cvt_pk_bf16_f32 v77, v102, v103
	v_cvt_pk_bf16_f32 v78, v104, v105
	v_cvt_pk_bf16_f32 v79, v106, v107
	v_cvt_pk_bf16_f32 v80, v108, v109
	v_cvt_pk_bf16_f32 v81, v110, v111
	ds_read_b64_tr_b16 v[82:83],v176 offset:0
	ds_read_b64_tr_b16 v[84:85],v176 offset:512
	ds_read_b64_tr_b16 v[86:87],v176 offset:1024
	ds_read_b64_tr_b16 v[88:89],v176 offset:1536
	ds_read_b64_tr_b16 v[90:91],v176 offset:2048
	ds_read_b64_tr_b16 v[92:93],v176 offset:2560
	ds_read_b64_tr_b16 v[94:95],v176 offset:3072
	ds_read_b64_tr_b16 v[96:97],v176 offset:3584
	s_waitcnt lgkmcnt(0)
	s_nop 0
	v_mfma_f32_32x32x16_bf16 v[48:63], v[66:69], v[82:85], v[48:63]
	ds_read_b64_tr_b16 v[82:83],v176 offset:4096
	ds_read_b64_tr_b16 v[84:85],v176 offset:4608
	v_mfma_f32_32x32x16_bf16 v[48:63], v[70:73], v[86:89], v[48:63]
	ds_read_b64_tr_b16 v[86:87],v176 offset:5120
	ds_read_b64_tr_b16 v[88:89],v176 offset:5632
	v_mfma_f32_32x32x16_bf16 v[48:63], v[74:77], v[90:93], v[48:63]
	ds_read_b64_tr_b16 v[90:91],v176 offset:6144
	ds_read_b64_tr_b16 v[92:93],v176 offset:6656
	ds_read_b64_tr_b16 v[98:99],v176 offset:7168
	ds_read_b64_tr_b16 v[100:101],v176 offset:7680
	s_waitcnt lgkmcnt(0)
	v_mfma_f32_32x32x16_bf16 v[48:63], v[78:81], v[94:97], v[48:63]
	v_mfma_f32_32x32x16_bf16 v[32:47], v[66:69], v[82:85], v[32:47]
	v_add_u32_e32 v65, 0x2000, v176
	ds_read_b64_tr_b16 v[82:83],v65 offset:0
	ds_read_b64_tr_b16 v[84:85],v65 offset:512
	v_mfma_f32_32x32x16_bf16 v[32:47], v[70:73], v[86:89], v[32:47]
	ds_read_b64_tr_b16 v[86:87],v65 offset:1024
	ds_read_b64_tr_b16 v[88:89],v65 offset:1536
	v_mfma_f32_32x32x16_bf16 v[32:47], v[74:77], v[90:93], v[32:47]
	ds_read_b64_tr_b16 v[90:91],v65 offset:2048
	ds_read_b64_tr_b16 v[92:93],v65 offset:2560
	ds_read_b64_tr_b16 v[94:95],v65 offset:3072
	ds_read_b64_tr_b16 v[96:97],v65 offset:3584
	s_waitcnt lgkmcnt(0)
	v_mfma_f32_32x32x16_bf16 v[32:47], v[78:81], v[98:101], v[32:47]
	v_mfma_f32_32x32x16_bf16 v[16:31], v[66:69], v[82:85], v[16:31]
	ds_read_b64_tr_b16 v[82:83],v65 offset:4096
	ds_read_b64_tr_b16 v[84:85],v65 offset:4608
	v_mfma_f32_32x32x16_bf16 v[16:31], v[70:73], v[86:89], v[16:31]
	ds_read_b64_tr_b16 v[86:87],v65 offset:5120
	ds_read_b64_tr_b16 v[88:89],v65 offset:5632
	v_mfma_f32_32x32x16_bf16 v[16:31], v[74:77], v[90:93], v[16:31]
	ds_read_b64_tr_b16 v[90:91],v65 offset:6144
	ds_read_b64_tr_b16 v[92:93],v65 offset:6656
	ds_read_b64_tr_b16 v[98:99],v65 offset:7168
	ds_read_b64_tr_b16 v[100:101],v65 offset:7680
	s_waitcnt lgkmcnt(0)
	v_mfma_f32_32x32x16_bf16 v[16:31], v[78:81], v[94:97], v[16:31]
	v_mfma_f32_32x32x16_bf16 v[0:15], v[66:69], v[82:85], v[0:15]
	v_mov_b32_e32 v65, v64
	s_nop 1
	v_permlane32_swap_b32_e32 v64, v65
	v_cmp_gt_u32_e32 vcc, 32, v187
	v_mfma_f32_32x32x16_bf16 v[0:15], v[70:73], v[86:89], v[0:15]
	v_mfma_f32_32x32x16_bf16 v[0:15], v[74:77], v[90:93], v[0:15]
	v_mfma_f32_32x32x16_bf16 v[0:15], v[78:81], v[98:101], v[0:15]
	s_and_saveexec_b64 s[16:17], vcc
	s_cbranch_execz .LBB0_870
	v_add_f32_e32 v64, v64, v65
	v_lshl_add_u32 v65, v186, 2, s34
	ds_write_b32 v65, v64 offset:128
	s_branch .LBB0_870

; __global__ void __launch_bounds__(NWAVES * 64, 2) mk_fwd(Args args) {
	.amdhsa_kernel _Z6mk_fwd4Args
		.amdhsa_group_segment_fixed_size 0
		.amdhsa_private_segment_fixed_size 0
		.amdhsa_kernarg_size 472
		.amdhsa_user_sgpr_count 2
		.amdhsa_user_sgpr_dispatch_ptr 0
		.amdhsa_user_sgpr_queue_ptr 0
		.amdhsa_user_sgpr_kernarg_segment_ptr 1
		.amdhsa_user_sgpr_dispatch_id 0
		.amdhsa_user_sgpr_kernarg_preload_length 0
		.amdhsa_user_sgpr_kernarg_preload_offset 0
		.amdhsa_user_sgpr_private_segment_size 0
		.amdhsa_uses_dynamic_stack 0
		.amdhsa_enable_private_segment 0
		.amdhsa_system_sgpr_workgroup_id_x 1
		.amdhsa_system_sgpr_workgroup_id_y 0
		.amdhsa_system_sgpr_workgroup_id_z 0
		.amdhsa_system_sgpr_workgroup_info 0
		.amdhsa_system_vgpr_workitem_id 2
		.amdhsa_next_free_vgpr 241
		.amdhsa_next_free_sgpr 98
		.amdhsa_accum_offset 244
		.amdhsa_reserve_vcc 1
		.amdhsa_float_round_mode_32 0
		.amdhsa_float_round_mode_16_64 0
		.amdhsa_float_denorm_mode_32 3
		.amdhsa_float_denorm_mode_16_64 3
		.amdhsa_dx10_clamp 1
		.amdhsa_ieee_mode 1
		.amdhsa_fp16_overflow 0
		.amdhsa_tg_split 0
		.amdhsa_exception_fp_ieee_invalid_op 0
		.amdhsa_exception_fp_denorm_src 0
		.amdhsa_exception_fp_ieee_div_zero 0
		.amdhsa_exception_fp_ieee_overflow 0
		.amdhsa_exception_fp_ieee_underflow 0
		.amdhsa_exception_fp_ieee_inexact 0
		.amdhsa_exception_int_div_zero 0
	.end_amdhsa_kernel

; __global__ void __launch_bounds__(NWAVES * 64, 2) mk_fwd(Args args) {
.Lfunc_end0:
	.size	_Z6mk_fwd4Args, .Lfunc_end0-_Z6mk_fwd4Args
	.set _Z6mk_fwd4Args.num_vgpr, 241
	.set _Z6mk_fwd4Args.num_agpr, 0
	.set _Z6mk_fwd4Args.numbered_sgpr, 98
	.set _Z6mk_fwd4Args.num_named_barrier, 0
	.set _Z6mk_fwd4Args.private_seg_size, 0
	.set _Z6mk_fwd4Args.uses_vcc, 1
	.set _Z6mk_fwd4Args.uses_flat_scratch, 0
	.set _Z6mk_fwd4Args.has_dyn_sized_stack, 0
	.set _Z6mk_fwd4Args.has_recursion, 0
	.set _Z6mk_fwd4Args.has_indirect_call, 0

; __global__ void __launch_bounds__(NWAVES * 64, 2) mk_fwd(Args args) {
amdhsa.kernels:
  - .agpr_count:     0
    .args:
      - .offset:         0
        .size:           216
        .value_kind:     by_value
      - .offset:         216
        .size:           4
        .value_kind:     hidden_block_count_x
      - .offset:         220
        .size:           4
        .value_kind:     hidden_block_count_y
      - .offset:         224
        .size:           4
        .value_kind:     hidden_block_count_z
      - .offset:         228
        .size:           2
        .value_kind:     hidden_group_size_x
      - .offset:         230
        .size:           2
        .value_kind:     hidden_group_size_y
      - .offset:         232
        .size:           2
        .value_kind:     hidden_group_size_z
      - .offset:         234
        .size:           2
        .value_kind:     hidden_remainder_x
      - .offset:         236
        .size:           2
        .value_kind:     hidden_remainder_y
      - .offset:         238
        .size:           2
        .value_kind:     hidden_remainder_z
      - .offset:         256
        .size:           8
        .value_kind:     hidden_global_offset_x
      - .offset:         264
        .size:           8
        .value_kind:     hidden_global_offset_y
      - .offset:         272
        .size:           8
        .value_kind:     hidden_global_offset_z
      - .offset:         280
        .size:           2
        .value_kind:     hidden_grid_dims
      - .offset:         304
        .size:           8
        .value_kind:     hidden_multigrid_sync_arg
      - .offset:         336
        .size:           4
        .value_kind:     hidden_dynamic_lds_size
    .group_segment_fixed_size: 0
    .kernarg_segment_align: 8
    .kernarg_segment_size: 472
    .language:       OpenCL C
    .language_version:
      - 2
      - 0
    .max_flat_workgroup_size: 512
    .name:           _Z6mk_fwd4Args
    .private_segment_fixed_size: 0
    .sgpr_count:     104
    .sgpr_spill_count: 32
    .symbol:         _Z6mk_fwd4Args.kd
    .uniform_work_group_size: 1
    .uses_dynamic_stack: false
    .vgpr_count:     241
    .vgpr_spill_count: 0
    .wavefront_size: 64
